# v33 + mid-block s_setprio 0/1 flip pairs removed from the K-loop MFMA blocks
# baseline (speedup 1.0000x reference)
; #define PG8_STAGE(bufoff, gbase, voff) do { _Pragma("unroll") for (int _i = 0; _i < 2; ++_i) \
;         __builtin_amdgcn_global_load_lds((const unsigned*)((const char*)(gbase) + (voff)[_i]), (PG8_LAS unsigned*)(lds + (bufoff) + ldsw + _i * 8192), 16, 0, 0); } while (0)
; #define PG8_LDA(dst, b, h) do { _Pragma("unroll") for (int m = 0; m < 4; ++m) _Pragma("unroll") for (int k = 0; k < 2; ++k) dst[m][k] = *(const PG8_LAS bf16x8*)(lds + PG8_SA(b, h) + aoff + m * 2048 + k * 1024); } while (0)
; #define PG8_LDB(dst, b, h) do { _Pragma("unroll") for (int n = 0; n < 2; ++n) _Pragma("unroll") for (int k = 0; k < 2; ++k) dst[n][k] = *(const PG8_LAS bf16x8*)(lds + PG8_SB(b, h) + boff + n * 2048 + k * 1024); } while (0)
; #define PG8_WAIT_V(n) asm volatile("s_waitcnt vmcnt(" #n ")" ::: "memory")
; #define PG8_WAIT_L(n) asm volatile("s_waitcnt lgkmcnt(" #n ")" ::: "memory")
; #define PG8_BAR __builtin_amdgcn_s_barrier()
; #define PG8_SCHED __builtin_amdgcn_sched_barrier(0)
; template <class Epi, class Sched, bool ALIGN_EPI = false, bool SP2 = false, bool AGM = false  >
; __device__ __forceinline__ void gemm_phase(PG8_LAS unsigned char* lds, const Gemm g, const Sched& S, const Epi& E) {
;     ...
;         const bool has_next = S.next(ui + 1, nxt);
;         const char* nA = has_next ? (const char*)g.A + (size_t)nxt.pm * tstepA : cA; const char* nB = has_next ? (const char*)g.Bt + (size_t)nxt.pn * tstep : cB;
;         for (int t = 0; t < nt; t += 2) {
;             const bool last = (t == nt - 2);
;             const char* a1 = cA + (size_t)(t + 1) * kstepA;
;             const char* a2 = last ? nA : cA + (size_t)(t + 2) * kstepA; const char* b2 = last ? nB : cB + (size_t)(t + 2) * kstep;
;             const char* a3 = a2 + kstepA; const char* b3 = b2 + kstep;
;             if (last && has_next) S.a_ready(nxt);
;             if constexpr (SP2) {
;             PG8_LDB(B0, 0, 0); PG8_LDB(B1, 0, 1); PG8_SCHED; PG8_LDA(At, 0, 0); PG8_STAGE(PG8_SA(1, 1), a1 + hstepA, voffA);
;             PG8_WAIT_V(8); PG8_WAIT_L(0); PG8_BAR; PG8_MMA(0, 0, At, B0); PG8_MMA(0, 1, At, B1); PG8_BAR; PG8_SCHED;
;             PG8_LDA(At, 0, 1); PG8_STAGE(PG8_SB(0, 0), b2, voffB); PG8_STAGE(PG8_SB(0, 1), b2 + hstep, voffB); PG8_STAGE(PG8_SA(0, 0), a2, voffA);
;             PG8_WAIT_V(8); PG8_WAIT_L(0); PG8_BAR; PG8_MMA(1, 0, At, B0); PG8_MMA(1, 1, At, B1); PG8_BAR; PG8_SCHED;
.LBB0_136:
	s_ashr_i32 s15, s14, 31
	s_lshl_b64 s[16:17], s[14:15], 19
	s_add_u32 s16, s46, s16
	s_addc_u32 s17, s47, s17
	s_and_b64 s[18:19], s[0:1], exec
	s_cselect_b32 s15, s17, s23
	s_cselect_b32 s21, s16, s22
	s_ashr_i32 s13, s12, 31
	s_lshl_b64 s[18:19], s[12:13], 19
	s_add_u32 s18, s3, s18
	s_addc_u32 s19, s28, s19
	s_and_b64 s[26:27], s[0:1], exec
	s_cselect_b32 s13, s19, s25
	s_cselect_b32 s45, s18, s24
	s_add_u32 s22, s22, 0x40080
	s_addc_u32 s23, s23, 0
	s_add_u32 s53, s24, 0x100
	s_addc_u32 s54, s25, 0
	s_mov_b32 s55, -2
	ds_read_b128 v[150:153], v160
	ds_read_b128 v[164:167], v160 offset:1024
	ds_read_b128 v[168:171], v160 offset:2048
	ds_read_b128 v[172:175], v160 offset:3072
	ds_read_b128 v[176:179], v161
	ds_read_b128 v[180:183], v161 offset:1024
	ds_read_b128 v[184:187], v161 offset:2048
	ds_read_b128 v[188:191], v161 offset:3072
	s_add_u32 s24, s22, 0xfffc0080
	s_addc_u32 s25, s23, -1
	s_cmp_eq_u32 s55, 12
	s_cselect_b32 s27, s15, s25
	s_cselect_b32 s26, s21, s24
	s_cselect_b32 s25, s13, s54
	s_cselect_b32 s24, s45, s53
	v_lshl_add_u64 v[224:225], s[22:23], 0, v[142:143]
	s_add_i32 m0, s33, 0xc000
	ds_read_b128 v[192:195], v162
	ds_read_b128 v[196:199], v162 offset:1024
	ds_read_b128 v[200:203], v162 offset:2048
	ds_read_b128 v[204:207], v162 offset:3072
	ds_read_b128 v[208:211], v162 offset:4096
	ds_read_b128 v[212:215], v162 offset:5120
	ds_read_b128 v[216:219], v162 offset:6144
	ds_read_b128 v[220:223], v162 offset:7168
	global_load_lds_dwordx4 v[224:225], off
	v_lshl_add_u64 v[224:225], s[22:23], 0, v[144:145]
	s_add_i32 m0, s33, 0xe000
	s_nop 0
	global_load_lds_dwordx4 v[224:225], off
	s_waitcnt vmcnt(8)
	s_waitcnt lgkmcnt(0)
	s_barrier
	s_setprio 1
	s_waitcnt lgkmcnt(0)
	v_mfma_f32_16x16x32_bf16 v[126:129], v[150:153], v[192:195], 0
	v_mfma_f32_16x16x32_bf16 v[122:125], v[168:171], v[192:195], 0
	v_mfma_f32_16x16x32_bf16 v[114:117], v[150:153], v[200:203], 0
	v_mfma_f32_16x16x32_bf16 v[106:109], v[168:171], v[200:203], 0
	v_mfma_f32_16x16x32_bf16 v[102:105], v[150:153], v[208:211], 0
	v_mfma_f32_16x16x32_bf16 v[94:97], v[168:171], v[208:211], 0
	v_mfma_f32_16x16x32_bf16 v[86:89], v[150:153], v[216:219], 0
	v_mfma_f32_16x16x32_bf16 v[78:81], v[168:171], v[216:219], 0
	v_mfma_f32_16x16x32_bf16 v[126:129], v[164:167], v[196:199], v[126:129]
	v_mfma_f32_16x16x32_bf16 v[122:125], v[172:175], v[196:199], v[122:125]
	v_mfma_f32_16x16x32_bf16 v[114:117], v[164:167], v[204:207], v[114:117]
	v_mfma_f32_16x16x32_bf16 v[106:109], v[172:175], v[204:207], v[106:109]
	v_mfma_f32_16x16x32_bf16 v[102:105], v[164:167], v[212:215], v[102:105]
	v_mfma_f32_16x16x32_bf16 v[94:97], v[172:175], v[212:215], v[94:97]
	v_mfma_f32_16x16x32_bf16 v[86:89], v[164:167], v[220:223], v[86:89]
	v_mfma_f32_16x16x32_bf16 v[78:81], v[172:175], v[220:223], v[78:81]
	v_mfma_f32_16x16x32_bf16 v[118:121], v[176:179], v[192:195], 0
	v_mfma_f32_16x16x32_bf16 v[110:113], v[184:187], v[192:195], 0
	v_mfma_f32_16x16x32_bf16 v[98:101], v[176:179], v[200:203], 0
	v_mfma_f32_16x16x32_bf16 v[90:93], v[184:187], v[200:203], 0
	v_mfma_f32_16x16x32_bf16 v[82:85], v[176:179], v[208:211], 0
	v_mfma_f32_16x16x32_bf16 v[74:77], v[184:187], v[208:211], 0
	v_mfma_f32_16x16x32_bf16 v[70:73], v[176:179], v[216:219], 0
	v_mfma_f32_16x16x32_bf16 v[66:69], v[184:187], v[216:219], 0
	v_mfma_f32_16x16x32_bf16 v[118:121], v[180:183], v[196:199], v[118:121]
	v_mfma_f32_16x16x32_bf16 v[110:113], v[188:191], v[196:199], v[110:113]
	v_mfma_f32_16x16x32_bf16 v[98:101], v[180:183], v[204:207], v[98:101]
	v_mfma_f32_16x16x32_bf16 v[90:93], v[188:191], v[204:207], v[90:93]
	v_mfma_f32_16x16x32_bf16 v[82:85], v[180:183], v[212:215], v[82:85]
	v_mfma_f32_16x16x32_bf16 v[74:77], v[188:191], v[212:215], v[74:77]
	v_mfma_f32_16x16x32_bf16 v[70:73], v[180:183], v[220:223], v[70:73]
	v_mfma_f32_16x16x32_bf16 v[66:69], v[188:191], v[220:223], v[66:69]
	s_setprio 0
	s_barrier
	s_add_i32 s58, s41, s29
	v_lshl_add_u64 v[224:225], s[24:25], 0, v[134:135]
	s_mov_b32 m0, s58
	ds_read_b128 v[192:195], v162 offset:16384
	ds_read_b128 v[196:199], v162 offset:17408
	ds_read_b128 v[200:203], v162 offset:18432
	ds_read_b128 v[204:207], v162 offset:19456
	ds_read_b128 v[208:211], v162 offset:20480
	ds_read_b128 v[212:215], v162 offset:21504
	ds_read_b128 v[216:219], v162 offset:22528
	ds_read_b128 v[220:223], v162 offset:23552
	global_load_lds_dwordx4 v[224:225], off
	s_add_i32 m0, s58, 0x2000
	s_add_u32 s58, s24, 0x40000
	v_lshl_add_u64 v[226:227], s[24:25], 0, v[130:131]
	s_addc_u32 s59, s25, 0
	s_add_i32 s60, s42, s29
	global_load_lds_dwordx4 v[226:227], off
	v_lshl_add_u64 v[228:229], s[58:59], 0, v[134:135]
	s_mov_b32 m0, s60
	v_lshl_add_u64 v[230:231], s[26:27], 0, v[132:133]
	global_load_lds_dwordx4 v[228:229], off
	v_lshl_add_u64 v[228:229], s[58:59], 0, v[130:131]
	s_add_i32 m0, s60, 0x2000
	s_nop 0
	global_load_lds_dwordx4 v[228:229], off
	v_lshl_add_u64 v[228:229], s[26:27], 0, v[136:137]
	s_mov_b32 m0, s33
	s_nop 0
	global_load_lds_dwordx4 v[228:229], off
	s_mov_b32 m0, s34
	s_nop 0
	global_load_lds_dwordx4 v[230:231], off
	s_waitcnt vmcnt(8)
	s_waitcnt lgkmcnt(0)
	s_barrier
; #define PG8_STAGE(bufoff, gbase, voff) do { _Pragma("unroll") for (int _i = 0; _i < 2; ++_i) \
;         __builtin_amdgcn_global_load_lds((const unsigned*)((const char*)(gbase) + (voff)[_i]), (PG8_LAS unsigned*)(lds + (bufoff) + ldsw + _i * 8192), 16, 0, 0); } while (0)
; #define PG8_LDA(dst, b, h) do { _Pragma("unroll") for (int m = 0; m < 4; ++m) _Pragma("unroll") for (int k = 0; k < 2; ++k) dst[m][k] = *(const PG8_LAS bf16x8*)(lds + PG8_SA(b, h) + aoff + m * 2048 + k * 1024); } while (0)
; #define PG8_LDB(dst, b, h) do { _Pragma("unroll") for (int n = 0; n < 2; ++n) _Pragma("unroll") for (int k = 0; k < 2; ++k) dst[n][k] = *(const PG8_LAS bf16x8*)(lds + PG8_SB(b, h) + boff + n * 2048 + k * 1024); } while (0)
; #define PG8_MMA(ai, bj, At, Bt) do { __builtin_amdgcn_s_setprio(1); _Pragma("unroll") for (int m = 0; m < 4; ++m) _Pragma("unroll") for (int n = 0; n < 2; ++n) _Pragma("unroll") for (int k = 0; k < 2; ++k) \
;         acc[ai][bj][m][n] = __builtin_amdgcn_mfma_f32_16x16x32_bf16(Bt[n][k], At[m][k], acc[ai][bj][m][n], 0, 0, 0); __builtin_amdgcn_s_setprio(0); } while (0)
; #define PG8_WAIT_V(n) asm volatile("s_waitcnt vmcnt(" #n ")" ::: "memory")
; #define PG8_WAIT_L(n) asm volatile("s_waitcnt lgkmcnt(" #n ")" ::: "memory")
; #define PG8_BAR __builtin_amdgcn_s_barrier()
; #define PG8_SCHED __builtin_amdgcn_sched_barrier(0)
; template <class Epi, class Sched, bool ALIGN_EPI = false, bool SP2 = false, bool AGM = false  >
; __device__ __forceinline__ void gemm_phase(PG8_LAS unsigned char* lds, const Gemm g, const Sched& S, const Epi& E) {
;     ...
;             PG8_WAIT_V(8); PG8_WAIT_L(0); PG8_BAR; PG8_MMA(1, 0, At, B0); PG8_MMA(1, 1, At, B1); PG8_BAR; PG8_SCHED;
;             PG8_LDB(B0, 1, 0); PG8_LDB(B1, 1, 1); PG8_SCHED; PG8_LDA(At, 1, 0); PG8_STAGE(PG8_SA(0, 1), a2 + hstepA, voffA);
;             PG8_WAIT_V(8); PG8_WAIT_L(0); PG8_BAR; PG8_MMA(0, 0, At, B0); PG8_MMA(0, 1, At, B1); PG8_BAR; PG8_SCHED;
	s_setprio 1
	s_waitcnt lgkmcnt(0)
	v_mfma_f32_16x16x32_bf16 v[62:65], v[150:153], v[192:195], 0
	v_mfma_f32_16x16x32_bf16 v[58:61], v[168:171], v[192:195], 0
	v_mfma_f32_16x16x32_bf16 v[54:57], v[150:153], v[200:203], 0
	v_mfma_f32_16x16x32_bf16 v[46:49], v[168:171], v[200:203], 0
	v_mfma_f32_16x16x32_bf16 v[38:41], v[150:153], v[208:211], 0
	v_mfma_f32_16x16x32_bf16 v[30:33], v[168:171], v[208:211], 0
	v_mfma_f32_16x16x32_bf16 v[22:25], v[150:153], v[216:219], 0
	v_mfma_f32_16x16x32_bf16 v[14:17], v[168:171], v[216:219], 0
	v_mfma_f32_16x16x32_bf16 v[62:65], v[164:167], v[196:199], v[62:65]
	v_mfma_f32_16x16x32_bf16 v[58:61], v[172:175], v[196:199], v[58:61]
	v_mfma_f32_16x16x32_bf16 v[54:57], v[164:167], v[204:207], v[54:57]
	v_mfma_f32_16x16x32_bf16 v[46:49], v[172:175], v[204:207], v[46:49]
	v_mfma_f32_16x16x32_bf16 v[38:41], v[164:167], v[212:215], v[38:41]
	v_mfma_f32_16x16x32_bf16 v[30:33], v[172:175], v[212:215], v[30:33]
	v_mfma_f32_16x16x32_bf16 v[22:25], v[164:167], v[220:223], v[22:25]
	v_mfma_f32_16x16x32_bf16 v[14:17], v[172:175], v[220:223], v[14:17]
	v_mfma_f32_16x16x32_bf16 v[50:53], v[176:179], v[192:195], 0
	v_mfma_f32_16x16x32_bf16 v[42:45], v[184:187], v[192:195], 0
	v_mfma_f32_16x16x32_bf16 v[34:37], v[176:179], v[200:203], 0
	v_mfma_f32_16x16x32_bf16 v[26:29], v[184:187], v[200:203], 0
	v_mfma_f32_16x16x32_bf16 v[18:21], v[176:179], v[208:211], 0
	v_mfma_f32_16x16x32_bf16 v[10:13], v[184:187], v[208:211], 0
	v_mfma_f32_16x16x32_bf16 v[6:9], v[176:179], v[216:219], 0
	v_mfma_f32_16x16x32_bf16 v[2:5], v[184:187], v[216:219], 0
	v_mfma_f32_16x16x32_bf16 v[50:53], v[180:183], v[196:199], v[50:53]
	v_mfma_f32_16x16x32_bf16 v[42:45], v[188:191], v[196:199], v[42:45]
	v_mfma_f32_16x16x32_bf16 v[34:37], v[180:183], v[204:207], v[34:37]
	v_mfma_f32_16x16x32_bf16 v[26:29], v[188:191], v[204:207], v[26:29]
	v_mfma_f32_16x16x32_bf16 v[18:21], v[180:183], v[212:215], v[18:21]
	v_mfma_f32_16x16x32_bf16 v[10:13], v[188:191], v[212:215], v[10:13]
	v_mfma_f32_16x16x32_bf16 v[6:9], v[180:183], v[220:223], v[6:9]
	v_mfma_f32_16x16x32_bf16 v[2:5], v[188:191], v[220:223], v[2:5]
	s_setprio 0
	s_barrier
	s_add_i32 s58, 0, 0x18000
	v_add_u32_e32 v138, s58, v157
	s_add_i32 s59, 0, 0x1c000
	ds_read_b128 v[150:153], v138
	ds_read_b128 v[164:167], v138 offset:1024
	ds_read_b128 v[168:171], v138 offset:2048
	ds_read_b128 v[172:175], v138 offset:3072
	v_add_u32_e32 v138, s59, v157
	ds_read_b128 v[176:179], v138
	ds_read_b128 v[180:183], v138 offset:1024
	ds_read_b128 v[184:187], v138 offset:2048
	ds_read_b128 v[188:191], v138 offset:3072
	s_add_u32 s26, s26, 0x40000
	s_addc_u32 s27, s27, 0
	s_mov_b32 m0, s35
	v_lshl_add_u64 v[232:233], s[26:27], 0, v[136:137]
	ds_read_b128 v[192:195], v162 offset:32768
	ds_read_b128 v[196:199], v162 offset:33792
	ds_read_b128 v[200:203], v162 offset:34816
	ds_read_b128 v[204:207], v162 offset:35840
	ds_read_b128 v[208:211], v162 offset:36864
	ds_read_b128 v[212:215], v162 offset:37888
	ds_read_b128 v[216:219], v162 offset:38912
	ds_read_b128 v[220:223], v162 offset:39936
	global_load_lds_dwordx4 v[232:233], off
	v_lshl_add_u64 v[232:233], s[26:27], 0, v[132:133]
	s_mov_b32 m0, s36
	s_nop 0
	global_load_lds_dwordx4 v[232:233], off
	s_waitcnt vmcnt(8)
	s_waitcnt lgkmcnt(0)
	s_barrier
	s_setprio 1
	s_waitcnt lgkmcnt(0)
	v_mfma_f32_16x16x32_bf16 v[126:129], v[150:153], v[192:195], v[126:129]
	v_mfma_f32_16x16x32_bf16 v[122:125], v[168:171], v[192:195], v[122:125]
	v_mfma_f32_16x16x32_bf16 v[114:117], v[150:153], v[200:203], v[114:117]
	v_mfma_f32_16x16x32_bf16 v[106:109], v[168:171], v[200:203], v[106:109]
	v_mfma_f32_16x16x32_bf16 v[102:105], v[150:153], v[208:211], v[102:105]
	v_mfma_f32_16x16x32_bf16 v[94:97], v[168:171], v[208:211], v[94:97]
	v_mfma_f32_16x16x32_bf16 v[86:89], v[150:153], v[216:219], v[86:89]
	v_mfma_f32_16x16x32_bf16 v[78:81], v[168:171], v[216:219], v[78:81]
	v_mfma_f32_16x16x32_bf16 v[126:129], v[164:167], v[196:199], v[126:129]
	v_mfma_f32_16x16x32_bf16 v[122:125], v[172:175], v[196:199], v[122:125]
	v_mfma_f32_16x16x32_bf16 v[114:117], v[164:167], v[204:207], v[114:117]
	v_mfma_f32_16x16x32_bf16 v[106:109], v[172:175], v[204:207], v[106:109]
	v_mfma_f32_16x16x32_bf16 v[102:105], v[164:167], v[212:215], v[102:105]
	v_mfma_f32_16x16x32_bf16 v[94:97], v[172:175], v[212:215], v[94:97]
	v_mfma_f32_16x16x32_bf16 v[86:89], v[164:167], v[220:223], v[86:89]
	v_mfma_f32_16x16x32_bf16 v[78:81], v[172:175], v[220:223], v[78:81]
	v_mfma_f32_16x16x32_bf16 v[118:121], v[176:179], v[192:195], v[118:121]
	v_mfma_f32_16x16x32_bf16 v[110:113], v[184:187], v[192:195], v[110:113]
	v_mfma_f32_16x16x32_bf16 v[98:101], v[176:179], v[200:203], v[98:101]
	v_mfma_f32_16x16x32_bf16 v[90:93], v[184:187], v[200:203], v[90:93]
	v_mfma_f32_16x16x32_bf16 v[82:85], v[176:179], v[208:211], v[82:85]
	v_mfma_f32_16x16x32_bf16 v[74:77], v[184:187], v[208:211], v[74:77]
	v_mfma_f32_16x16x32_bf16 v[70:73], v[176:179], v[216:219], v[70:73]
	v_mfma_f32_16x16x32_bf16 v[66:69], v[184:187], v[216:219], v[66:69]
	v_mfma_f32_16x16x32_bf16 v[118:121], v[180:183], v[196:199], v[118:121]
	v_mfma_f32_16x16x32_bf16 v[110:113], v[188:191], v[196:199], v[110:113]
	v_mfma_f32_16x16x32_bf16 v[98:101], v[180:183], v[204:207], v[98:101]
	v_mfma_f32_16x16x32_bf16 v[90:93], v[188:191], v[204:207], v[90:93]
	v_mfma_f32_16x16x32_bf16 v[82:85], v[180:183], v[212:215], v[82:85]
	v_mfma_f32_16x16x32_bf16 v[74:77], v[188:191], v[212:215], v[74:77]
	v_mfma_f32_16x16x32_bf16 v[70:73], v[180:183], v[220:223], v[70:73]
	v_mfma_f32_16x16x32_bf16 v[66:69], v[188:191], v[220:223], v[66:69]
	s_setprio 0
	s_barrier
; #define PG8_STAGE(bufoff, gbase, voff) do { _Pragma("unroll") for (int _i = 0; _i < 2; ++_i) \
;         __builtin_amdgcn_global_load_lds((const unsigned*)((const char*)(gbase) + (voff)[_i]), (PG8_LAS unsigned*)(lds + (bufoff) + ldsw + _i * 8192), 16, 0, 0); } while (0)
; #define PG8_LDA(dst, b, h) do { _Pragma("unroll") for (int m = 0; m < 4; ++m) _Pragma("unroll") for (int k = 0; k < 2; ++k) dst[m][k] = *(const PG8_LAS bf16x8*)(lds + PG8_SA(b, h) + aoff + m * 2048 + k * 1024); } while (0)
; #define PG8_LDB(dst, b, h) do { _Pragma("unroll") for (int n = 0; n < 2; ++n) _Pragma("unroll") for (int k = 0; k < 2; ++k) dst[n][k] = *(const PG8_LAS bf16x8*)(lds + PG8_SB(b, h) + boff + n * 2048 + k * 1024); } while (0)
; #define PG8_MMA(ai, bj, At, Bt) do { __builtin_amdgcn_s_setprio(1); _Pragma("unroll") for (int m = 0; m < 4; ++m) _Pragma("unroll") for (int n = 0; n < 2; ++n) _Pragma("unroll") for (int k = 0; k < 2; ++k) \
;         acc[ai][bj][m][n] = __builtin_amdgcn_mfma_f32_16x16x32_bf16(Bt[n][k], At[m][k], acc[ai][bj][m][n], 0, 0, 0); __builtin_amdgcn_s_setprio(0); } while (0)
; #define PG8_WAIT_V(n) asm volatile("s_waitcnt vmcnt(" #n ")" ::: "memory")
; #define PG8_WAIT_L(n) asm volatile("s_waitcnt lgkmcnt(" #n ")" ::: "memory")
; #define PG8_BAR __builtin_amdgcn_s_barrier()
; #define PG8_SCHED __builtin_amdgcn_sched_barrier(0)
; template <class Epi, class Sched, bool ALIGN_EPI = false, bool SP2 = false, bool AGM = false  >
; __device__ __forceinline__ void gemm_phase(PG8_LAS unsigned char* lds, const Gemm g, const Sched& S, const Epi& E) {
;     ...
;             PG8_LDB(B0, 0, 0); PG8_LDB(B1, 0, 1); PG8_SCHED; PG8_LDA(At, 0, 0); PG8_STAGE(PG8_SA(1, 1), a1 + hstepA, voffA);
;     ...
;             PG8_LDA(At, 1, 1); PG8_STAGE(PG8_SB(1, 0), b3, voffB); PG8_STAGE(PG8_SB(1, 1), b3 + hstep, voffB); PG8_STAGE(PG8_SA(1, 0), a3, voffA);
;             PG8_WAIT_V(8); PG8_WAIT_L(0); PG8_BAR; PG8_MMA(1, 0, At, B0); PG8_MMA(1, 1, At, B1); PG8_BAR; PG8_SCHED;
	s_add_i32 s26, s58, s29
	v_lshl_add_u64 v[224:225], v[224:225], 0, s[10:11]
	s_mov_b32 m0, s26
	ds_read_b128 v[192:195], v162 offset:49152
	ds_read_b128 v[196:199], v162 offset:50176
	ds_read_b128 v[200:203], v162 offset:51200
	ds_read_b128 v[204:207], v162 offset:52224
	ds_read_b128 v[208:211], v162 offset:53248
	ds_read_b128 v[212:215], v162 offset:54272
	ds_read_b128 v[216:219], v162 offset:55296
	ds_read_b128 v[220:223], v162 offset:56320
	global_load_lds_dwordx4 v[224:225], off
	s_add_i32 m0, s26, 0x2000
	s_add_u32 s24, s24, 0x40080
	v_lshl_add_u64 v[224:225], v[226:227], 0, s[10:11]
	s_addc_u32 s25, s25, 0
	s_add_i32 s26, s59, s29
	global_load_lds_dwordx4 v[224:225], off
	v_lshl_add_u64 v[224:225], s[24:25], 0, v[134:135]
	s_mov_b32 m0, s26
	s_nop 0
	global_load_lds_dwordx4 v[224:225], off
	v_lshl_add_u64 v[224:225], s[24:25], 0, v[130:131]
	s_add_i32 m0, s26, 0x2000
	s_nop 0
	global_load_lds_dwordx4 v[224:225], off
	v_lshl_add_u64 v[224:225], v[228:229], 0, s[10:11]
	s_mov_b32 m0, s38
	s_nop 0
	global_load_lds_dwordx4 v[224:225], off
	v_lshl_add_u64 v[224:225], v[230:231], 0, s[10:11]
	s_mov_b32 m0, s39
	s_nop 0
	global_load_lds_dwordx4 v[224:225], off
	s_waitcnt vmcnt(8)
	s_waitcnt lgkmcnt(0)
	s_barrier
	s_setprio 1
	s_waitcnt lgkmcnt(0)
	v_mfma_f32_16x16x32_bf16 v[62:65], v[150:153], v[192:195], v[62:65]
	v_mfma_f32_16x16x32_bf16 v[58:61], v[168:171], v[192:195], v[58:61]
	v_mfma_f32_16x16x32_bf16 v[54:57], v[150:153], v[200:203], v[54:57]
	v_mfma_f32_16x16x32_bf16 v[46:49], v[168:171], v[200:203], v[46:49]
	v_mfma_f32_16x16x32_bf16 v[38:41], v[150:153], v[208:211], v[38:41]
	v_mfma_f32_16x16x32_bf16 v[30:33], v[168:171], v[208:211], v[30:33]
	v_mfma_f32_16x16x32_bf16 v[22:25], v[150:153], v[216:219], v[22:25]
	v_mfma_f32_16x16x32_bf16 v[14:17], v[168:171], v[216:219], v[14:17]
	v_mfma_f32_16x16x32_bf16 v[62:65], v[164:167], v[196:199], v[62:65]
	v_mfma_f32_16x16x32_bf16 v[58:61], v[172:175], v[196:199], v[58:61]
	v_mfma_f32_16x16x32_bf16 v[54:57], v[164:167], v[204:207], v[54:57]
	v_mfma_f32_16x16x32_bf16 v[46:49], v[172:175], v[204:207], v[46:49]
	v_mfma_f32_16x16x32_bf16 v[38:41], v[164:167], v[212:215], v[38:41]
	v_mfma_f32_16x16x32_bf16 v[30:33], v[172:175], v[212:215], v[30:33]
	v_mfma_f32_16x16x32_bf16 v[22:25], v[164:167], v[220:223], v[22:25]
	v_mfma_f32_16x16x32_bf16 v[14:17], v[172:175], v[220:223], v[14:17]
	v_mfma_f32_16x16x32_bf16 v[50:53], v[176:179], v[192:195], v[50:53]
	v_mfma_f32_16x16x32_bf16 v[42:45], v[184:187], v[192:195], v[42:45]
	v_mfma_f32_16x16x32_bf16 v[34:37], v[176:179], v[200:203], v[34:37]
	v_mfma_f32_16x16x32_bf16 v[26:29], v[184:187], v[200:203], v[26:29]
	v_mfma_f32_16x16x32_bf16 v[18:21], v[176:179], v[208:211], v[18:21]
	v_mfma_f32_16x16x32_bf16 v[10:13], v[184:187], v[208:211], v[10:13]
	v_mfma_f32_16x16x32_bf16 v[6:9], v[176:179], v[216:219], v[6:9]
	v_mfma_f32_16x16x32_bf16 v[2:5], v[184:187], v[216:219], v[2:5]
	v_mfma_f32_16x16x32_bf16 v[50:53], v[180:183], v[196:199], v[50:53]
	v_mfma_f32_16x16x32_bf16 v[42:45], v[188:191], v[196:199], v[42:45]
	v_mfma_f32_16x16x32_bf16 v[34:37], v[180:183], v[204:207], v[34:37]
	v_mfma_f32_16x16x32_bf16 v[26:29], v[188:191], v[204:207], v[26:29]
	v_mfma_f32_16x16x32_bf16 v[18:21], v[180:183], v[212:215], v[18:21]
	v_mfma_f32_16x16x32_bf16 v[10:13], v[188:191], v[212:215], v[10:13]
	v_mfma_f32_16x16x32_bf16 v[6:9], v[180:183], v[220:223], v[6:9]
	v_mfma_f32_16x16x32_bf16 v[2:5], v[188:191], v[220:223], v[2:5]
	s_setprio 0
	s_barrier
	s_add_i32 s55, s55, 2
	s_add_u32 s22, s22, 0x100
	s_addc_u32 s23, s23, 0
	s_add_u32 s53, s53, 0x100
	s_addc_u32 s54, s54, 0
	s_cmp_gt_u32 s55, 13
	s_cbranch_scc1 .Lpeel_done_p1
	.p2align	6
.LBB0_137:
	ds_read_b128 v[150:153], v160
	ds_read_b128 v[164:167], v160 offset:1024
	ds_read_b128 v[168:171], v160 offset:2048
	ds_read_b128 v[172:175], v160 offset:3072
	ds_read_b128 v[176:179], v161
	ds_read_b128 v[180:183], v161 offset:1024
	ds_read_b128 v[184:187], v161 offset:2048
	ds_read_b128 v[188:191], v161 offset:3072
	s_add_u32 s24, s22, 0xfffc0080
	s_addc_u32 s25, s23, -1
	s_cmp_eq_u32 s55, 12
	s_cselect_b32 s27, s15, s25
	s_cselect_b32 s26, s21, s24
	s_cselect_b32 s25, s13, s54
	s_cselect_b32 s24, s45, s53
	v_lshl_add_u64 v[224:225], s[22:23], 0, v[142:143]
	s_add_i32 m0, s33, 0xc000
	ds_read_b128 v[192:195], v162
	ds_read_b128 v[196:199], v162 offset:1024
	ds_read_b128 v[200:203], v162 offset:2048
	ds_read_b128 v[204:207], v162 offset:3072
	ds_read_b128 v[208:211], v162 offset:4096
	ds_read_b128 v[212:215], v162 offset:5120
	ds_read_b128 v[216:219], v162 offset:6144
	ds_read_b128 v[220:223], v162 offset:7168
	global_load_lds_dwordx4 v[224:225], off
	v_lshl_add_u64 v[224:225], s[22:23], 0, v[144:145]
	s_add_i32 m0, s33, 0xe000
	s_nop 0
	global_load_lds_dwordx4 v[224:225], off
	s_waitcnt vmcnt(8)
	s_waitcnt lgkmcnt(0)
	s_barrier
; #define PG8_STAGE(bufoff, gbase, voff) do { _Pragma("unroll") for (int _i = 0; _i < 2; ++_i) \
;         __builtin_amdgcn_global_load_lds((const unsigned*)((const char*)(gbase) + (voff)[_i]), (PG8_LAS unsigned*)(lds + (bufoff) + ldsw + _i * 8192), 16, 0, 0); } while (0)
; #define PG8_LDA(dst, b, h) do { _Pragma("unroll") for (int m = 0; m < 4; ++m) _Pragma("unroll") for (int k = 0; k < 2; ++k) dst[m][k] = *(const PG8_LAS bf16x8*)(lds + PG8_SA(b, h) + aoff + m * 2048 + k * 1024); } while (0)
; #define PG8_MMA(ai, bj, At, Bt) do { __builtin_amdgcn_s_setprio(1); _Pragma("unroll") for (int m = 0; m < 4; ++m) _Pragma("unroll") for (int n = 0; n < 2; ++n) _Pragma("unroll") for (int k = 0; k < 2; ++k) \
;         acc[ai][bj][m][n] = __builtin_amdgcn_mfma_f32_16x16x32_bf16(Bt[n][k], At[m][k], acc[ai][bj][m][n], 0, 0, 0); __builtin_amdgcn_s_setprio(0); } while (0)
; #define PG8_WAIT_V(n) asm volatile("s_waitcnt vmcnt(" #n ")" ::: "memory")
; #define PG8_WAIT_L(n) asm volatile("s_waitcnt lgkmcnt(" #n ")" ::: "memory")
; #define PG8_BAR __builtin_amdgcn_s_barrier()
; #define PG8_SCHED __builtin_amdgcn_sched_barrier(0)
; template <class Epi, class Sched, bool ALIGN_EPI = false, bool SP2 = false, bool AGM = false  >
; __device__ __forceinline__ void gemm_phase(PG8_LAS unsigned char* lds, const Gemm g, const Sched& S, const Epi& E) {
;     ...
;             PG8_WAIT_V(8); PG8_WAIT_L(0); PG8_BAR; PG8_MMA(0, 0, At, B0); PG8_MMA(0, 1, At, B1); PG8_BAR; PG8_SCHED;
;             PG8_LDA(At, 0, 1); PG8_STAGE(PG8_SB(0, 0), b2, voffB); PG8_STAGE(PG8_SB(0, 1), b2 + hstep, voffB); PG8_STAGE(PG8_SA(0, 0), a2, voffA);
;             PG8_WAIT_V(8); PG8_WAIT_L(0); PG8_BAR; PG8_MMA(1, 0, At, B0); PG8_MMA(1, 1, At, B1); PG8_BAR; PG8_SCHED;
	s_setprio 1
	s_waitcnt lgkmcnt(0)
	v_mfma_f32_16x16x32_bf16 v[126:129], v[150:153], v[192:195], v[126:129]
	v_mfma_f32_16x16x32_bf16 v[122:125], v[168:171], v[192:195], v[122:125]
	v_mfma_f32_16x16x32_bf16 v[114:117], v[150:153], v[200:203], v[114:117]
	v_mfma_f32_16x16x32_bf16 v[106:109], v[168:171], v[200:203], v[106:109]
	v_mfma_f32_16x16x32_bf16 v[102:105], v[150:153], v[208:211], v[102:105]
	v_mfma_f32_16x16x32_bf16 v[94:97], v[168:171], v[208:211], v[94:97]
	v_mfma_f32_16x16x32_bf16 v[86:89], v[150:153], v[216:219], v[86:89]
	v_mfma_f32_16x16x32_bf16 v[78:81], v[168:171], v[216:219], v[78:81]
	v_mfma_f32_16x16x32_bf16 v[126:129], v[164:167], v[196:199], v[126:129]
	v_mfma_f32_16x16x32_bf16 v[122:125], v[172:175], v[196:199], v[122:125]
	v_mfma_f32_16x16x32_bf16 v[114:117], v[164:167], v[204:207], v[114:117]
	v_mfma_f32_16x16x32_bf16 v[106:109], v[172:175], v[204:207], v[106:109]
	v_mfma_f32_16x16x32_bf16 v[102:105], v[164:167], v[212:215], v[102:105]
	v_mfma_f32_16x16x32_bf16 v[94:97], v[172:175], v[212:215], v[94:97]
	v_mfma_f32_16x16x32_bf16 v[86:89], v[164:167], v[220:223], v[86:89]
	v_mfma_f32_16x16x32_bf16 v[78:81], v[172:175], v[220:223], v[78:81]
	v_mfma_f32_16x16x32_bf16 v[118:121], v[176:179], v[192:195], v[118:121]
	v_mfma_f32_16x16x32_bf16 v[110:113], v[184:187], v[192:195], v[110:113]
	v_mfma_f32_16x16x32_bf16 v[98:101], v[176:179], v[200:203], v[98:101]
	v_mfma_f32_16x16x32_bf16 v[90:93], v[184:187], v[200:203], v[90:93]
	v_mfma_f32_16x16x32_bf16 v[82:85], v[176:179], v[208:211], v[82:85]
	v_mfma_f32_16x16x32_bf16 v[74:77], v[184:187], v[208:211], v[74:77]
	v_mfma_f32_16x16x32_bf16 v[70:73], v[176:179], v[216:219], v[70:73]
	v_mfma_f32_16x16x32_bf16 v[66:69], v[184:187], v[216:219], v[66:69]
	v_mfma_f32_16x16x32_bf16 v[118:121], v[180:183], v[196:199], v[118:121]
	v_mfma_f32_16x16x32_bf16 v[110:113], v[188:191], v[196:199], v[110:113]
	v_mfma_f32_16x16x32_bf16 v[98:101], v[180:183], v[204:207], v[98:101]
	v_mfma_f32_16x16x32_bf16 v[90:93], v[188:191], v[204:207], v[90:93]
	v_mfma_f32_16x16x32_bf16 v[82:85], v[180:183], v[212:215], v[82:85]
	v_mfma_f32_16x16x32_bf16 v[74:77], v[188:191], v[212:215], v[74:77]
	v_mfma_f32_16x16x32_bf16 v[70:73], v[180:183], v[220:223], v[70:73]
	v_mfma_f32_16x16x32_bf16 v[66:69], v[188:191], v[220:223], v[66:69]
	s_setprio 0
	s_barrier
	s_add_i32 s58, s41, s29
	v_lshl_add_u64 v[224:225], s[24:25], 0, v[134:135]
	s_mov_b32 m0, s58
	ds_read_b128 v[192:195], v162 offset:16384
	ds_read_b128 v[196:199], v162 offset:17408
	ds_read_b128 v[200:203], v162 offset:18432
	ds_read_b128 v[204:207], v162 offset:19456
	ds_read_b128 v[208:211], v162 offset:20480
	ds_read_b128 v[212:215], v162 offset:21504
	ds_read_b128 v[216:219], v162 offset:22528
	ds_read_b128 v[220:223], v162 offset:23552
	global_load_lds_dwordx4 v[224:225], off
	s_add_i32 m0, s58, 0x2000
	s_add_u32 s58, s24, 0x40000
	v_lshl_add_u64 v[226:227], s[24:25], 0, v[130:131]
	s_addc_u32 s59, s25, 0
	s_add_i32 s60, s42, s29
	global_load_lds_dwordx4 v[226:227], off
	v_lshl_add_u64 v[228:229], s[58:59], 0, v[134:135]
	s_mov_b32 m0, s60
	v_lshl_add_u64 v[230:231], s[26:27], 0, v[132:133]
	global_load_lds_dwordx4 v[228:229], off
	v_lshl_add_u64 v[228:229], s[58:59], 0, v[130:131]
	s_add_i32 m0, s60, 0x2000
	s_nop 0
	global_load_lds_dwordx4 v[228:229], off
	v_lshl_add_u64 v[228:229], s[26:27], 0, v[136:137]
	s_mov_b32 m0, s33
	s_nop 0
	global_load_lds_dwordx4 v[228:229], off
	s_mov_b32 m0, s34
	s_nop 0
	global_load_lds_dwordx4 v[230:231], off
	s_waitcnt vmcnt(8)
	s_waitcnt lgkmcnt(0)
	s_barrier
	s_setprio 1
	s_waitcnt lgkmcnt(0)
	v_mfma_f32_16x16x32_bf16 v[62:65], v[150:153], v[192:195], v[62:65]
	v_mfma_f32_16x16x32_bf16 v[58:61], v[168:171], v[192:195], v[58:61]
	v_mfma_f32_16x16x32_bf16 v[54:57], v[150:153], v[200:203], v[54:57]
	v_mfma_f32_16x16x32_bf16 v[46:49], v[168:171], v[200:203], v[46:49]
	v_mfma_f32_16x16x32_bf16 v[38:41], v[150:153], v[208:211], v[38:41]
	v_mfma_f32_16x16x32_bf16 v[30:33], v[168:171], v[208:211], v[30:33]
	v_mfma_f32_16x16x32_bf16 v[22:25], v[150:153], v[216:219], v[22:25]
	v_mfma_f32_16x16x32_bf16 v[14:17], v[168:171], v[216:219], v[14:17]
	v_mfma_f32_16x16x32_bf16 v[62:65], v[164:167], v[196:199], v[62:65]
	v_mfma_f32_16x16x32_bf16 v[58:61], v[172:175], v[196:199], v[58:61]
	v_mfma_f32_16x16x32_bf16 v[54:57], v[164:167], v[204:207], v[54:57]
	v_mfma_f32_16x16x32_bf16 v[46:49], v[172:175], v[204:207], v[46:49]
	v_mfma_f32_16x16x32_bf16 v[38:41], v[164:167], v[212:215], v[38:41]
	v_mfma_f32_16x16x32_bf16 v[30:33], v[172:175], v[212:215], v[30:33]
	v_mfma_f32_16x16x32_bf16 v[22:25], v[164:167], v[220:223], v[22:25]
	v_mfma_f32_16x16x32_bf16 v[14:17], v[172:175], v[220:223], v[14:17]
	v_mfma_f32_16x16x32_bf16 v[50:53], v[176:179], v[192:195], v[50:53]
	v_mfma_f32_16x16x32_bf16 v[42:45], v[184:187], v[192:195], v[42:45]
	v_mfma_f32_16x16x32_bf16 v[34:37], v[176:179], v[200:203], v[34:37]
	v_mfma_f32_16x16x32_bf16 v[26:29], v[184:187], v[200:203], v[26:29]
	v_mfma_f32_16x16x32_bf16 v[18:21], v[176:179], v[208:211], v[18:21]
	v_mfma_f32_16x16x32_bf16 v[10:13], v[184:187], v[208:211], v[10:13]
	v_mfma_f32_16x16x32_bf16 v[6:9], v[176:179], v[216:219], v[6:9]
	v_mfma_f32_16x16x32_bf16 v[2:5], v[184:187], v[216:219], v[2:5]
	v_mfma_f32_16x16x32_bf16 v[50:53], v[180:183], v[196:199], v[50:53]
	v_mfma_f32_16x16x32_bf16 v[42:45], v[188:191], v[196:199], v[42:45]
	v_mfma_f32_16x16x32_bf16 v[34:37], v[180:183], v[204:207], v[34:37]
	v_mfma_f32_16x16x32_bf16 v[26:29], v[188:191], v[204:207], v[26:29]
	v_mfma_f32_16x16x32_bf16 v[18:21], v[180:183], v[212:215], v[18:21]
	v_mfma_f32_16x16x32_bf16 v[10:13], v[188:191], v[212:215], v[10:13]
	v_mfma_f32_16x16x32_bf16 v[6:9], v[180:183], v[220:223], v[6:9]
	v_mfma_f32_16x16x32_bf16 v[2:5], v[188:191], v[220:223], v[2:5]
	s_setprio 0
	s_barrier
; #define PG8_STAGE(bufoff, gbase, voff) do { _Pragma("unroll") for (int _i = 0; _i < 2; ++_i) \
;         __builtin_amdgcn_global_load_lds((const unsigned*)((const char*)(gbase) + (voff)[_i]), (PG8_LAS unsigned*)(lds + (bufoff) + ldsw + _i * 8192), 16, 0, 0); } while (0)
; #define PG8_LDA(dst, b, h) do { _Pragma("unroll") for (int m = 0; m < 4; ++m) _Pragma("unroll") for (int k = 0; k < 2; ++k) dst[m][k] = *(const PG8_LAS bf16x8*)(lds + PG8_SA(b, h) + aoff + m * 2048 + k * 1024); } while (0)
; #define PG8_LDB(dst, b, h) do { _Pragma("unroll") for (int n = 0; n < 2; ++n) _Pragma("unroll") for (int k = 0; k < 2; ++k) dst[n][k] = *(const PG8_LAS bf16x8*)(lds + PG8_SB(b, h) + boff + n * 2048 + k * 1024); } while (0)
; #define PG8_MMA(ai, bj, At, Bt) do { __builtin_amdgcn_s_setprio(1); _Pragma("unroll") for (int m = 0; m < 4; ++m) _Pragma("unroll") for (int n = 0; n < 2; ++n) _Pragma("unroll") for (int k = 0; k < 2; ++k) \
;         acc[ai][bj][m][n] = __builtin_amdgcn_mfma_f32_16x16x32_bf16(Bt[n][k], At[m][k], acc[ai][bj][m][n], 0, 0, 0); __builtin_amdgcn_s_setprio(0); } while (0)
; #define PG8_WAIT_V(n) asm volatile("s_waitcnt vmcnt(" #n ")" ::: "memory")
; #define PG8_WAIT_L(n) asm volatile("s_waitcnt lgkmcnt(" #n ")" ::: "memory")
; #define PG8_BAR __builtin_amdgcn_s_barrier()
; #define PG8_SCHED __builtin_amdgcn_sched_barrier(0)
; template <class Epi, class Sched, bool ALIGN_EPI = false, bool SP2 = false, bool AGM = false  >
; __device__ __forceinline__ void gemm_phase(PG8_LAS unsigned char* lds, const Gemm g, const Sched& S, const Epi& E) {
;     ...
;             PG8_LDB(B0, 1, 0); PG8_LDB(B1, 1, 1); PG8_SCHED; PG8_LDA(At, 1, 0); PG8_STAGE(PG8_SA(0, 1), a2 + hstepA, voffA);
;             PG8_WAIT_V(8); PG8_WAIT_L(0); PG8_BAR; PG8_MMA(0, 0, At, B0); PG8_MMA(0, 1, At, B1); PG8_BAR; PG8_SCHED;
	s_add_i32 s58, 0, 0x18000
	v_add_u32_e32 v138, s58, v157
	s_add_i32 s59, 0, 0x1c000
	ds_read_b128 v[150:153], v138
	ds_read_b128 v[164:167], v138 offset:1024
	ds_read_b128 v[168:171], v138 offset:2048
	ds_read_b128 v[172:175], v138 offset:3072
	v_add_u32_e32 v138, s59, v157
	ds_read_b128 v[176:179], v138
	ds_read_b128 v[180:183], v138 offset:1024
	ds_read_b128 v[184:187], v138 offset:2048
	ds_read_b128 v[188:191], v138 offset:3072
	s_add_u32 s26, s26, 0x40000
	s_addc_u32 s27, s27, 0
	s_mov_b32 m0, s35
	v_lshl_add_u64 v[232:233], s[26:27], 0, v[136:137]
	ds_read_b128 v[192:195], v162 offset:32768
	ds_read_b128 v[196:199], v162 offset:33792
	ds_read_b128 v[200:203], v162 offset:34816
	ds_read_b128 v[204:207], v162 offset:35840
	ds_read_b128 v[208:211], v162 offset:36864
	ds_read_b128 v[212:215], v162 offset:37888
	ds_read_b128 v[216:219], v162 offset:38912
	ds_read_b128 v[220:223], v162 offset:39936
	global_load_lds_dwordx4 v[232:233], off
	v_lshl_add_u64 v[232:233], s[26:27], 0, v[132:133]
	s_mov_b32 m0, s36
	s_nop 0
	global_load_lds_dwordx4 v[232:233], off
	s_waitcnt vmcnt(8)
	s_waitcnt lgkmcnt(0)
	s_barrier
	s_setprio 1
	s_waitcnt lgkmcnt(0)
	v_mfma_f32_16x16x32_bf16 v[126:129], v[150:153], v[192:195], v[126:129]
	v_mfma_f32_16x16x32_bf16 v[122:125], v[168:171], v[192:195], v[122:125]
	v_mfma_f32_16x16x32_bf16 v[114:117], v[150:153], v[200:203], v[114:117]
	v_mfma_f32_16x16x32_bf16 v[106:109], v[168:171], v[200:203], v[106:109]
	v_mfma_f32_16x16x32_bf16 v[102:105], v[150:153], v[208:211], v[102:105]
	v_mfma_f32_16x16x32_bf16 v[94:97], v[168:171], v[208:211], v[94:97]
	v_mfma_f32_16x16x32_bf16 v[86:89], v[150:153], v[216:219], v[86:89]
	v_mfma_f32_16x16x32_bf16 v[78:81], v[168:171], v[216:219], v[78:81]
	v_mfma_f32_16x16x32_bf16 v[126:129], v[164:167], v[196:199], v[126:129]
	v_mfma_f32_16x16x32_bf16 v[122:125], v[172:175], v[196:199], v[122:125]
	v_mfma_f32_16x16x32_bf16 v[114:117], v[164:167], v[204:207], v[114:117]
	v_mfma_f32_16x16x32_bf16 v[106:109], v[172:175], v[204:207], v[106:109]
	v_mfma_f32_16x16x32_bf16 v[102:105], v[164:167], v[212:215], v[102:105]
	v_mfma_f32_16x16x32_bf16 v[94:97], v[172:175], v[212:215], v[94:97]
	v_mfma_f32_16x16x32_bf16 v[86:89], v[164:167], v[220:223], v[86:89]
	v_mfma_f32_16x16x32_bf16 v[78:81], v[172:175], v[220:223], v[78:81]
	v_mfma_f32_16x16x32_bf16 v[118:121], v[176:179], v[192:195], v[118:121]
	v_mfma_f32_16x16x32_bf16 v[110:113], v[184:187], v[192:195], v[110:113]
	v_mfma_f32_16x16x32_bf16 v[98:101], v[176:179], v[200:203], v[98:101]
	v_mfma_f32_16x16x32_bf16 v[90:93], v[184:187], v[200:203], v[90:93]
	v_mfma_f32_16x16x32_bf16 v[82:85], v[176:179], v[208:211], v[82:85]
	v_mfma_f32_16x16x32_bf16 v[74:77], v[184:187], v[208:211], v[74:77]
	v_mfma_f32_16x16x32_bf16 v[70:73], v[176:179], v[216:219], v[70:73]
	v_mfma_f32_16x16x32_bf16 v[66:69], v[184:187], v[216:219], v[66:69]
	v_mfma_f32_16x16x32_bf16 v[118:121], v[180:183], v[196:199], v[118:121]
	v_mfma_f32_16x16x32_bf16 v[110:113], v[188:191], v[196:199], v[110:113]
	v_mfma_f32_16x16x32_bf16 v[98:101], v[180:183], v[204:207], v[98:101]
	v_mfma_f32_16x16x32_bf16 v[90:93], v[188:191], v[204:207], v[90:93]
	v_mfma_f32_16x16x32_bf16 v[82:85], v[180:183], v[212:215], v[82:85]
	v_mfma_f32_16x16x32_bf16 v[74:77], v[188:191], v[212:215], v[74:77]
	v_mfma_f32_16x16x32_bf16 v[70:73], v[180:183], v[220:223], v[70:73]
	v_mfma_f32_16x16x32_bf16 v[66:69], v[188:191], v[220:223], v[66:69]
	s_setprio 0
	s_barrier
; #define PG8_STAGE(bufoff, gbase, voff) do { _Pragma("unroll") for (int _i = 0; _i < 2; ++_i) \
;         __builtin_amdgcn_global_load_lds((const unsigned*)((const char*)(gbase) + (voff)[_i]), (PG8_LAS unsigned*)(lds + (bufoff) + ldsw + _i * 8192), 16, 0, 0); } while (0)
; #define PG8_LDA(dst, b, h) do { _Pragma("unroll") for (int m = 0; m < 4; ++m) _Pragma("unroll") for (int k = 0; k < 2; ++k) dst[m][k] = *(const PG8_LAS bf16x8*)(lds + PG8_SA(b, h) + aoff + m * 2048 + k * 1024); } while (0)
; #define PG8_MMA(ai, bj, At, Bt) do { __builtin_amdgcn_s_setprio(1); _Pragma("unroll") for (int m = 0; m < 4; ++m) _Pragma("unroll") for (int n = 0; n < 2; ++n) _Pragma("unroll") for (int k = 0; k < 2; ++k) \
;         acc[ai][bj][m][n] = __builtin_amdgcn_mfma_f32_16x16x32_bf16(Bt[n][k], At[m][k], acc[ai][bj][m][n], 0, 0, 0); __builtin_amdgcn_s_setprio(0); } while (0)
; #define PG8_WAIT_V(n) asm volatile("s_waitcnt vmcnt(" #n ")" ::: "memory")
; #define PG8_WAIT_L(n) asm volatile("s_waitcnt lgkmcnt(" #n ")" ::: "memory")
; #define PG8_BAR __builtin_amdgcn_s_barrier()
; #define PG8_SCHED __builtin_amdgcn_sched_barrier(0)
; template <class Epi, class Sched, bool ALIGN_EPI = false, bool SP2 = false, bool AGM = false  >
; __device__ __forceinline__ void gemm_phase(PG8_LAS unsigned char* lds, const Gemm g, const Sched& S, const Epi& E) {
;     ...
;             PG8_LDA(At, 1, 1); PG8_STAGE(PG8_SB(1, 0), b3, voffB); PG8_STAGE(PG8_SB(1, 1), b3 + hstep, voffB); PG8_STAGE(PG8_SA(1, 0), a3, voffA);
;             PG8_WAIT_V(8); PG8_WAIT_L(0); PG8_BAR; PG8_MMA(1, 0, At, B0); PG8_MMA(1, 1, At, B1); PG8_BAR; PG8_SCHED;
	s_add_i32 s26, s58, s29
	v_lshl_add_u64 v[224:225], v[224:225], 0, s[10:11]
	s_mov_b32 m0, s26
	ds_read_b128 v[192:195], v162 offset:49152
	ds_read_b128 v[196:199], v162 offset:50176
	ds_read_b128 v[200:203], v162 offset:51200
	ds_read_b128 v[204:207], v162 offset:52224
	ds_read_b128 v[208:211], v162 offset:53248
	ds_read_b128 v[212:215], v162 offset:54272
	ds_read_b128 v[216:219], v162 offset:55296
	ds_read_b128 v[220:223], v162 offset:56320
	global_load_lds_dwordx4 v[224:225], off
	s_add_i32 m0, s26, 0x2000
	s_add_u32 s24, s24, 0x40080
	v_lshl_add_u64 v[224:225], v[226:227], 0, s[10:11]
	s_addc_u32 s25, s25, 0
	s_add_i32 s26, s59, s29
	global_load_lds_dwordx4 v[224:225], off
	v_lshl_add_u64 v[224:225], s[24:25], 0, v[134:135]
	s_mov_b32 m0, s26
	s_nop 0
	global_load_lds_dwordx4 v[224:225], off
	v_lshl_add_u64 v[224:225], s[24:25], 0, v[130:131]
	s_add_i32 m0, s26, 0x2000
	s_nop 0
	global_load_lds_dwordx4 v[224:225], off
	v_lshl_add_u64 v[224:225], v[228:229], 0, s[10:11]
	s_mov_b32 m0, s38
	s_nop 0
	global_load_lds_dwordx4 v[224:225], off
	v_lshl_add_u64 v[224:225], v[230:231], 0, s[10:11]
	s_mov_b32 m0, s39
	s_nop 0
	global_load_lds_dwordx4 v[224:225], off
	s_waitcnt vmcnt(8)
	s_waitcnt lgkmcnt(0)
	s_barrier
	s_setprio 1
	s_waitcnt lgkmcnt(0)
	v_mfma_f32_16x16x32_bf16 v[62:65], v[150:153], v[192:195], v[62:65]
	v_mfma_f32_16x16x32_bf16 v[58:61], v[168:171], v[192:195], v[58:61]
	v_mfma_f32_16x16x32_bf16 v[54:57], v[150:153], v[200:203], v[54:57]
	v_mfma_f32_16x16x32_bf16 v[46:49], v[168:171], v[200:203], v[46:49]
	v_mfma_f32_16x16x32_bf16 v[38:41], v[150:153], v[208:211], v[38:41]
	v_mfma_f32_16x16x32_bf16 v[30:33], v[168:171], v[208:211], v[30:33]
	v_mfma_f32_16x16x32_bf16 v[22:25], v[150:153], v[216:219], v[22:25]
	v_mfma_f32_16x16x32_bf16 v[14:17], v[168:171], v[216:219], v[14:17]
	v_mfma_f32_16x16x32_bf16 v[62:65], v[164:167], v[196:199], v[62:65]
	v_mfma_f32_16x16x32_bf16 v[58:61], v[172:175], v[196:199], v[58:61]
	v_mfma_f32_16x16x32_bf16 v[54:57], v[164:167], v[204:207], v[54:57]
	v_mfma_f32_16x16x32_bf16 v[46:49], v[172:175], v[204:207], v[46:49]
	v_mfma_f32_16x16x32_bf16 v[38:41], v[164:167], v[212:215], v[38:41]
	v_mfma_f32_16x16x32_bf16 v[30:33], v[172:175], v[212:215], v[30:33]
	v_mfma_f32_16x16x32_bf16 v[22:25], v[164:167], v[220:223], v[22:25]
	v_mfma_f32_16x16x32_bf16 v[14:17], v[172:175], v[220:223], v[14:17]
	v_mfma_f32_16x16x32_bf16 v[50:53], v[176:179], v[192:195], v[50:53]
	v_mfma_f32_16x16x32_bf16 v[42:45], v[184:187], v[192:195], v[42:45]
	v_mfma_f32_16x16x32_bf16 v[34:37], v[176:179], v[200:203], v[34:37]
	v_mfma_f32_16x16x32_bf16 v[26:29], v[184:187], v[200:203], v[26:29]
	v_mfma_f32_16x16x32_bf16 v[18:21], v[176:179], v[208:211], v[18:21]
	v_mfma_f32_16x16x32_bf16 v[10:13], v[184:187], v[208:211], v[10:13]
	v_mfma_f32_16x16x32_bf16 v[6:9], v[176:179], v[216:219], v[6:9]
	v_mfma_f32_16x16x32_bf16 v[2:5], v[184:187], v[216:219], v[2:5]
	v_mfma_f32_16x16x32_bf16 v[50:53], v[180:183], v[196:199], v[50:53]
	v_mfma_f32_16x16x32_bf16 v[42:45], v[188:191], v[196:199], v[42:45]
	v_mfma_f32_16x16x32_bf16 v[34:37], v[180:183], v[204:207], v[34:37]
	v_mfma_f32_16x16x32_bf16 v[26:29], v[188:191], v[204:207], v[26:29]
	v_mfma_f32_16x16x32_bf16 v[18:21], v[180:183], v[212:215], v[18:21]
	v_mfma_f32_16x16x32_bf16 v[10:13], v[188:191], v[212:215], v[10:13]
	v_mfma_f32_16x16x32_bf16 v[6:9], v[180:183], v[220:223], v[6:9]
	v_mfma_f32_16x16x32_bf16 v[2:5], v[188:191], v[220:223], v[2:5]
	s_setprio 0
	s_barrier
	s_add_i32 s55, s55, 2
	s_add_u32 s22, s22, 0x100
	s_addc_u32 s23, s23, 0
	s_add_u32 s53, s53, 0x100
	s_addc_u32 s54, s54, 0
	s_cmp_gt_u32 s55, 13
	s_cbranch_scc0 .LBB0_137

; #define PG8_STAGE(bufoff, gbase, voff) do { _Pragma("unroll") for (int _i = 0; _i < 2; ++_i) \
;         __builtin_amdgcn_global_load_lds((const unsigned*)((const char*)(gbase) + (voff)[_i]), (PG8_LAS unsigned*)(lds + (bufoff) + ldsw + _i * 8192), 16, 0, 0); } while (0)
; #define PG8_LDA(dst, b, h) do { _Pragma("unroll") for (int m = 0; m < 4; ++m) _Pragma("unroll") for (int k = 0; k < 2; ++k) dst[m][k] = *(const PG8_LAS bf16x8*)(lds + PG8_SA(b, h) + aoff + m * 2048 + k * 1024); } while (0)
; #define PG8_LDB(dst, b, h) do { _Pragma("unroll") for (int n = 0; n < 2; ++n) _Pragma("unroll") for (int k = 0; k < 2; ++k) dst[n][k] = *(const PG8_LAS bf16x8*)(lds + PG8_SB(b, h) + boff + n * 2048 + k * 1024); } while (0)
; #define PG8_MMA(ai, bj, At, Bt) do { __builtin_amdgcn_s_setprio(1); _Pragma("unroll") for (int m = 0; m < 4; ++m) _Pragma("unroll") for (int n = 0; n < 2; ++n) _Pragma("unroll") for (int k = 0; k < 2; ++k) \
;         acc[ai][bj][m][n] = __builtin_amdgcn_mfma_f32_16x16x32_bf16(Bt[n][k], At[m][k], acc[ai][bj][m][n], 0, 0, 0); __builtin_amdgcn_s_setprio(0); } while (0)
; #define PG8_WAIT_V(n) asm volatile("s_waitcnt vmcnt(" #n ")" ::: "memory")
; #define PG8_WAIT_L(n) asm volatile("s_waitcnt lgkmcnt(" #n ")" ::: "memory")
; #define PG8_BAR __builtin_amdgcn_s_barrier()
; #define PG8_SCHED __builtin_amdgcn_sched_barrier(0)
; template <class Epi, class Sched, bool ALIGN_EPI = false, bool SP2 = false, bool AGM = false  >
; __device__ __forceinline__ void gemm_phase(PG8_LAS unsigned char* lds, const Gemm g, const Sched& S, const Epi& E) {
;     ...
;             const bool last = (t == nt - 2);
;             const char* a1 = cA + (size_t)(t + 1) * kstepA;
;             const char* a2 = last ? nA : cA + (size_t)(t + 2) * kstepA; const char* b2 = last ? nB : cB + (size_t)(t + 2) * kstep;
;             const char* a3 = a2 + kstepA; const char* b3 = b2 + kstep;
;             if (last && has_next) S.a_ready(nxt);
;             if constexpr (SP2) {
;             PG8_LDB(B0, 0, 0); PG8_LDB(B1, 0, 1); PG8_SCHED; PG8_LDA(At, 0, 0); PG8_STAGE(PG8_SA(1, 1), a1 + hstepA, voffA);
;             PG8_WAIT_V(8); PG8_WAIT_L(0); PG8_BAR; PG8_MMA(0, 0, At, B0); PG8_MMA(0, 1, At, B1); PG8_BAR; PG8_SCHED;
;             PG8_LDA(At, 0, 1); PG8_STAGE(PG8_SB(0, 0), b2, voffB); PG8_STAGE(PG8_SB(0, 1), b2 + hstep, voffB); PG8_STAGE(PG8_SA(0, 0), a2, voffA);
.LBB0_677:
	ds_read_b128 v[150:153], v157
	ds_read_b128 v[164:167], v157 offset:1024
	ds_read_b128 v[168:171], v157 offset:2048
	ds_read_b128 v[172:175], v157 offset:3072
	ds_read_b128 v[176:179], v158
	ds_read_b128 v[180:183], v158 offset:1024
	ds_read_b128 v[184:187], v158 offset:2048
	ds_read_b128 v[188:191], v158 offset:3072
	s_add_u32 s26, s24, 0x440000
	s_addc_u32 s27, s25, 0
	s_cmp_eq_u32 s70, 4
	s_cselect_b32 s34, s62, s26
	s_cselect_b32 s35, s19, s27
	s_cselect_b32 s30, s63, s68
	s_cselect_b32 s31, s17, s69
	s_add_u32 s28, s34, 0x220000
	s_addc_u32 s29, s35, 0
	v_lshl_add_u64 v[224:225], s[24:25], 0, v[142:143]
	s_add_i32 m0, s5, 0xc000
	ds_read_b128 v[192:195], v159
	ds_read_b128 v[196:199], v159 offset:1024
	ds_read_b128 v[200:203], v159 offset:2048
	ds_read_b128 v[204:207], v159 offset:3072
	ds_read_b128 v[208:211], v159 offset:4096
	ds_read_b128 v[212:215], v159 offset:5120
	ds_read_b128 v[216:219], v159 offset:6144
	ds_read_b128 v[220:223], v159 offset:7168
	global_load_lds_dwordx4 v[224:225], off
	v_lshl_add_u64 v[224:225], s[24:25], 0, v[144:145]
	s_add_i32 m0, s5, 0xe000
	s_nop 0
	global_load_lds_dwordx4 v[224:225], off
	s_waitcnt vmcnt(8)
	s_waitcnt lgkmcnt(0)
	s_barrier
	s_setprio 1
	s_waitcnt lgkmcnt(0)
	v_mfma_f32_16x16x32_bf16 v[126:129], v[150:153], v[192:195], v[126:129]
	v_mfma_f32_16x16x32_bf16 v[122:125], v[168:171], v[192:195], v[122:125]
	v_mfma_f32_16x16x32_bf16 v[110:113], v[150:153], v[200:203], v[110:113]
	v_mfma_f32_16x16x32_bf16 v[106:109], v[168:171], v[200:203], v[106:109]
	v_mfma_f32_16x16x32_bf16 v[94:97], v[150:153], v[208:211], v[94:97]
	v_mfma_f32_16x16x32_bf16 v[90:93], v[168:171], v[208:211], v[90:93]
	v_mfma_f32_16x16x32_bf16 v[78:81], v[150:153], v[216:219], v[78:81]
	v_mfma_f32_16x16x32_bf16 v[74:77], v[168:171], v[216:219], v[74:77]
	v_mfma_f32_16x16x32_bf16 v[126:129], v[164:167], v[196:199], v[126:129]
	v_mfma_f32_16x16x32_bf16 v[122:125], v[172:175], v[196:199], v[122:125]
	v_mfma_f32_16x16x32_bf16 v[110:113], v[164:167], v[204:207], v[110:113]
	v_mfma_f32_16x16x32_bf16 v[106:109], v[172:175], v[204:207], v[106:109]
	v_mfma_f32_16x16x32_bf16 v[94:97], v[164:167], v[212:215], v[94:97]
	v_mfma_f32_16x16x32_bf16 v[90:93], v[172:175], v[212:215], v[90:93]
	v_mfma_f32_16x16x32_bf16 v[78:81], v[164:167], v[220:223], v[78:81]
	v_mfma_f32_16x16x32_bf16 v[74:77], v[172:175], v[220:223], v[74:77]
	v_mfma_f32_16x16x32_bf16 v[118:121], v[176:179], v[192:195], v[118:121]
	v_mfma_f32_16x16x32_bf16 v[114:117], v[184:187], v[192:195], v[114:117]
	v_mfma_f32_16x16x32_bf16 v[102:105], v[176:179], v[200:203], v[102:105]
	v_mfma_f32_16x16x32_bf16 v[98:101], v[184:187], v[200:203], v[98:101]
	v_mfma_f32_16x16x32_bf16 v[86:89], v[176:179], v[208:211], v[86:89]
	v_mfma_f32_16x16x32_bf16 v[82:85], v[184:187], v[208:211], v[82:85]
	v_mfma_f32_16x16x32_bf16 v[70:73], v[176:179], v[216:219], v[70:73]
	v_mfma_f32_16x16x32_bf16 v[66:69], v[184:187], v[216:219], v[66:69]
	v_mfma_f32_16x16x32_bf16 v[118:121], v[180:183], v[196:199], v[118:121]
	v_mfma_f32_16x16x32_bf16 v[114:117], v[188:191], v[196:199], v[114:117]
	v_mfma_f32_16x16x32_bf16 v[102:105], v[180:183], v[204:207], v[102:105]
	v_mfma_f32_16x16x32_bf16 v[98:101], v[188:191], v[204:207], v[98:101]
	v_mfma_f32_16x16x32_bf16 v[86:89], v[180:183], v[212:215], v[86:89]
	v_mfma_f32_16x16x32_bf16 v[82:85], v[188:191], v[212:215], v[82:85]
	v_mfma_f32_16x16x32_bf16 v[70:73], v[180:183], v[220:223], v[70:73]
	v_mfma_f32_16x16x32_bf16 v[66:69], v[188:191], v[220:223], v[66:69]
	s_setprio 0
	s_barrier
	s_add_i32 s24, s54, s37
	v_lshl_add_u64 v[224:225], s[30:31], 0, v[134:135]
	s_mov_b32 m0, s24
	ds_read_b128 v[192:195], v159 offset:16384
	ds_read_b128 v[196:199], v159 offset:17408
	ds_read_b128 v[200:203], v159 offset:18432
	ds_read_b128 v[204:207], v159 offset:19456
	ds_read_b128 v[208:211], v159 offset:20480
	ds_read_b128 v[212:215], v159 offset:21504
	ds_read_b128 v[216:219], v159 offset:22528
	ds_read_b128 v[220:223], v159 offset:23552
	global_load_lds_dwordx4 v[224:225], off
	s_add_i32 m0, s24, 0x2000
	s_add_u32 s24, s30, 0x20000
	v_lshl_add_u64 v[226:227], s[30:31], 0, v[130:131]
	s_addc_u32 s25, s31, 0
	s_add_i32 s71, s55, s37
	global_load_lds_dwordx4 v[226:227], off
	v_lshl_add_u64 v[228:229], s[24:25], 0, v[134:135]
	s_mov_b32 m0, s71
	s_nop 0
	global_load_lds_dwordx4 v[228:229], off
	v_lshl_add_u64 v[228:229], s[24:25], 0, v[130:131]
	s_add_i32 m0, s71, 0x2000
	s_nop 0
	global_load_lds_dwordx4 v[228:229], off
	v_lshl_add_u64 v[228:229], s[34:35], 0, v[136:137]
	s_mov_b32 m0, s5
	s_nop 0
	global_load_lds_dwordx4 v[228:229], off
	v_lshl_add_u64 v[228:229], s[34:35], 0, v[132:133]
	s_mov_b32 m0, s39
	s_nop 0
	global_load_lds_dwordx4 v[228:229], off
	s_waitcnt vmcnt(8)
	s_waitcnt lgkmcnt(0)
	s_barrier
; #define PG8_STAGE(bufoff, gbase, voff) do { _Pragma("unroll") for (int _i = 0; _i < 2; ++_i) \
;         __builtin_amdgcn_global_load_lds((const unsigned*)((const char*)(gbase) + (voff)[_i]), (PG8_LAS unsigned*)(lds + (bufoff) + ldsw + _i * 8192), 16, 0, 0); } while (0)
; #define PG8_LDA(dst, b, h) do { _Pragma("unroll") for (int m = 0; m < 4; ++m) _Pragma("unroll") for (int k = 0; k < 2; ++k) dst[m][k] = *(const PG8_LAS bf16x8*)(lds + PG8_SA(b, h) + aoff + m * 2048 + k * 1024); } while (0)
; #define PG8_LDB(dst, b, h) do { _Pragma("unroll") for (int n = 0; n < 2; ++n) _Pragma("unroll") for (int k = 0; k < 2; ++k) dst[n][k] = *(const PG8_LAS bf16x8*)(lds + PG8_SB(b, h) + boff + n * 2048 + k * 1024); } while (0)
; #define PG8_MMA(ai, bj, At, Bt) do { __builtin_amdgcn_s_setprio(1); _Pragma("unroll") for (int m = 0; m < 4; ++m) _Pragma("unroll") for (int n = 0; n < 2; ++n) _Pragma("unroll") for (int k = 0; k < 2; ++k) \
;         acc[ai][bj][m][n] = __builtin_amdgcn_mfma_f32_16x16x32_bf16(Bt[n][k], At[m][k], acc[ai][bj][m][n], 0, 0, 0); __builtin_amdgcn_s_setprio(0); } while (0)
; #define PG8_WAIT_V(n) asm volatile("s_waitcnt vmcnt(" #n ")" ::: "memory")
; #define PG8_WAIT_L(n) asm volatile("s_waitcnt lgkmcnt(" #n ")" ::: "memory")
; #define PG8_BAR __builtin_amdgcn_s_barrier()
; #define PG8_SCHED __builtin_amdgcn_sched_barrier(0)
; template <class Epi, class Sched, bool ALIGN_EPI = false, bool SP2 = false, bool AGM = false  >
; __device__ __forceinline__ void gemm_phase(PG8_LAS unsigned char* lds, const Gemm g, const Sched& S, const Epi& E) {
;     ...
;             PG8_WAIT_V(8); PG8_WAIT_L(0); PG8_BAR; PG8_MMA(1, 0, At, B0); PG8_MMA(1, 1, At, B1); PG8_BAR; PG8_SCHED;
;             PG8_LDB(B0, 1, 0); PG8_LDB(B1, 1, 1); PG8_SCHED; PG8_LDA(At, 1, 0); PG8_STAGE(PG8_SA(0, 1), a2 + hstepA, voffA);
;             PG8_WAIT_V(8); PG8_WAIT_L(0); PG8_BAR; PG8_MMA(0, 0, At, B0); PG8_MMA(0, 1, At, B1); PG8_BAR; PG8_SCHED;
	s_setprio 1
	s_waitcnt lgkmcnt(0)
	v_mfma_f32_16x16x32_bf16 v[62:65], v[150:153], v[192:195], v[62:65]
	v_mfma_f32_16x16x32_bf16 v[58:61], v[168:171], v[192:195], v[58:61]
	v_mfma_f32_16x16x32_bf16 v[46:49], v[150:153], v[200:203], v[46:49]
	v_mfma_f32_16x16x32_bf16 v[42:45], v[168:171], v[200:203], v[42:45]
	v_mfma_f32_16x16x32_bf16 v[30:33], v[150:153], v[208:211], v[30:33]
	v_mfma_f32_16x16x32_bf16 v[26:29], v[168:171], v[208:211], v[26:29]
	v_mfma_f32_16x16x32_bf16 v[14:17], v[150:153], v[216:219], v[14:17]
	v_mfma_f32_16x16x32_bf16 v[10:13], v[168:171], v[216:219], v[10:13]
	v_mfma_f32_16x16x32_bf16 v[62:65], v[164:167], v[196:199], v[62:65]
	v_mfma_f32_16x16x32_bf16 v[58:61], v[172:175], v[196:199], v[58:61]
	v_mfma_f32_16x16x32_bf16 v[46:49], v[164:167], v[204:207], v[46:49]
	v_mfma_f32_16x16x32_bf16 v[42:45], v[172:175], v[204:207], v[42:45]
	v_mfma_f32_16x16x32_bf16 v[30:33], v[164:167], v[212:215], v[30:33]
	v_mfma_f32_16x16x32_bf16 v[26:29], v[172:175], v[212:215], v[26:29]
	v_mfma_f32_16x16x32_bf16 v[14:17], v[164:167], v[220:223], v[14:17]
	v_mfma_f32_16x16x32_bf16 v[10:13], v[172:175], v[220:223], v[10:13]
	v_mfma_f32_16x16x32_bf16 v[54:57], v[176:179], v[192:195], v[54:57]
	v_mfma_f32_16x16x32_bf16 v[50:53], v[184:187], v[192:195], v[50:53]
	v_mfma_f32_16x16x32_bf16 v[38:41], v[176:179], v[200:203], v[38:41]
	v_mfma_f32_16x16x32_bf16 v[34:37], v[184:187], v[200:203], v[34:37]
	v_mfma_f32_16x16x32_bf16 v[22:25], v[176:179], v[208:211], v[22:25]
	v_mfma_f32_16x16x32_bf16 v[18:21], v[184:187], v[208:211], v[18:21]
	v_mfma_f32_16x16x32_bf16 v[6:9], v[176:179], v[216:219], v[6:9]
	v_mfma_f32_16x16x32_bf16 v[2:5], v[184:187], v[216:219], v[2:5]
	v_mfma_f32_16x16x32_bf16 v[54:57], v[180:183], v[196:199], v[54:57]
	v_mfma_f32_16x16x32_bf16 v[50:53], v[188:191], v[196:199], v[50:53]
	v_mfma_f32_16x16x32_bf16 v[38:41], v[180:183], v[204:207], v[38:41]
	v_mfma_f32_16x16x32_bf16 v[34:37], v[188:191], v[204:207], v[34:37]
	v_mfma_f32_16x16x32_bf16 v[22:25], v[180:183], v[212:215], v[22:25]
	v_mfma_f32_16x16x32_bf16 v[18:21], v[188:191], v[212:215], v[18:21]
	v_mfma_f32_16x16x32_bf16 v[6:9], v[180:183], v[220:223], v[6:9]
	v_mfma_f32_16x16x32_bf16 v[2:5], v[188:191], v[220:223], v[2:5]
	s_setprio 0
	s_barrier
	s_add_i32 s71, 0, 0x18000
	v_add_u32_e32 v163, s71, v155
	s_add_i32 s72, 0, 0x1c000
	ds_read_b128 v[150:153], v163
	ds_read_b128 v[164:167], v163 offset:1024
	ds_read_b128 v[168:171], v163 offset:2048
	ds_read_b128 v[172:175], v163 offset:3072
	v_add_u32_e32 v163, s72, v155
	ds_read_b128 v[176:179], v163
	ds_read_b128 v[180:183], v163 offset:1024
	ds_read_b128 v[184:187], v163 offset:2048
	ds_read_b128 v[188:191], v163 offset:3072
	s_add_u32 s24, s34, 0x1000
	s_addc_u32 s25, s35, 0
	s_mov_b32 m0, s40
	v_lshl_add_u64 v[228:229], s[24:25], 0, v[136:137]
	ds_read_b128 v[192:195], v159 offset:32768
	ds_read_b128 v[196:199], v159 offset:33792
	ds_read_b128 v[200:203], v159 offset:34816
	ds_read_b128 v[204:207], v159 offset:35840
	ds_read_b128 v[208:211], v159 offset:36864
	ds_read_b128 v[212:215], v159 offset:37888
	ds_read_b128 v[216:219], v159 offset:38912
	ds_read_b128 v[220:223], v159 offset:39936
	global_load_lds_dwordx4 v[228:229], off
	v_lshl_add_u64 v[228:229], s[24:25], 0, v[132:133]
	s_mov_b32 m0, s41
	s_nop 0
	global_load_lds_dwordx4 v[228:229], off
	s_waitcnt vmcnt(8)
	s_waitcnt lgkmcnt(0)
	s_barrier
	s_setprio 1
	s_waitcnt lgkmcnt(0)
	v_mfma_f32_16x16x32_bf16 v[126:129], v[150:153], v[192:195], v[126:129]
	v_mfma_f32_16x16x32_bf16 v[122:125], v[168:171], v[192:195], v[122:125]
	v_mfma_f32_16x16x32_bf16 v[110:113], v[150:153], v[200:203], v[110:113]
	v_mfma_f32_16x16x32_bf16 v[106:109], v[168:171], v[200:203], v[106:109]
	v_mfma_f32_16x16x32_bf16 v[94:97], v[150:153], v[208:211], v[94:97]
	v_mfma_f32_16x16x32_bf16 v[90:93], v[168:171], v[208:211], v[90:93]
	v_mfma_f32_16x16x32_bf16 v[78:81], v[150:153], v[216:219], v[78:81]
	v_mfma_f32_16x16x32_bf16 v[74:77], v[168:171], v[216:219], v[74:77]
	v_mfma_f32_16x16x32_bf16 v[126:129], v[164:167], v[196:199], v[126:129]
	v_mfma_f32_16x16x32_bf16 v[122:125], v[172:175], v[196:199], v[122:125]
	v_mfma_f32_16x16x32_bf16 v[110:113], v[164:167], v[204:207], v[110:113]
	v_mfma_f32_16x16x32_bf16 v[106:109], v[172:175], v[204:207], v[106:109]
	v_mfma_f32_16x16x32_bf16 v[94:97], v[164:167], v[212:215], v[94:97]
	v_mfma_f32_16x16x32_bf16 v[90:93], v[172:175], v[212:215], v[90:93]
	v_mfma_f32_16x16x32_bf16 v[78:81], v[164:167], v[220:223], v[78:81]
	v_mfma_f32_16x16x32_bf16 v[74:77], v[172:175], v[220:223], v[74:77]
	v_mfma_f32_16x16x32_bf16 v[118:121], v[176:179], v[192:195], v[118:121]
	v_mfma_f32_16x16x32_bf16 v[114:117], v[184:187], v[192:195], v[114:117]
	v_mfma_f32_16x16x32_bf16 v[102:105], v[176:179], v[200:203], v[102:105]
	v_mfma_f32_16x16x32_bf16 v[98:101], v[184:187], v[200:203], v[98:101]
	v_mfma_f32_16x16x32_bf16 v[86:89], v[176:179], v[208:211], v[86:89]
	v_mfma_f32_16x16x32_bf16 v[82:85], v[184:187], v[208:211], v[82:85]
	v_mfma_f32_16x16x32_bf16 v[70:73], v[176:179], v[216:219], v[70:73]
	v_mfma_f32_16x16x32_bf16 v[66:69], v[184:187], v[216:219], v[66:69]
	v_mfma_f32_16x16x32_bf16 v[118:121], v[180:183], v[196:199], v[118:121]
	v_mfma_f32_16x16x32_bf16 v[114:117], v[188:191], v[196:199], v[114:117]
	v_mfma_f32_16x16x32_bf16 v[102:105], v[180:183], v[204:207], v[102:105]
	v_mfma_f32_16x16x32_bf16 v[98:101], v[188:191], v[204:207], v[98:101]
	v_mfma_f32_16x16x32_bf16 v[86:89], v[180:183], v[212:215], v[86:89]
	v_mfma_f32_16x16x32_bf16 v[82:85], v[188:191], v[212:215], v[82:85]
	v_mfma_f32_16x16x32_bf16 v[70:73], v[180:183], v[220:223], v[70:73]
	v_mfma_f32_16x16x32_bf16 v[66:69], v[188:191], v[220:223], v[66:69]
	s_setprio 0
	s_barrier
; #define PG8_STAGE(bufoff, gbase, voff) do { _Pragma("unroll") for (int _i = 0; _i < 2; ++_i) \
;         __builtin_amdgcn_global_load_lds((const unsigned*)((const char*)(gbase) + (voff)[_i]), (PG8_LAS unsigned*)(lds + (bufoff) + ldsw + _i * 8192), 16, 0, 0); } while (0)
; #define PG8_LDA(dst, b, h) do { _Pragma("unroll") for (int m = 0; m < 4; ++m) _Pragma("unroll") for (int k = 0; k < 2; ++k) dst[m][k] = *(const PG8_LAS bf16x8*)(lds + PG8_SA(b, h) + aoff + m * 2048 + k * 1024); } while (0)
; #define PG8_MMA(ai, bj, At, Bt) do { __builtin_amdgcn_s_setprio(1); _Pragma("unroll") for (int m = 0; m < 4; ++m) _Pragma("unroll") for (int n = 0; n < 2; ++n) _Pragma("unroll") for (int k = 0; k < 2; ++k) \
;         acc[ai][bj][m][n] = __builtin_amdgcn_mfma_f32_16x16x32_bf16(Bt[n][k], At[m][k], acc[ai][bj][m][n], 0, 0, 0); __builtin_amdgcn_s_setprio(0); } while (0)
; #define PG8_WAIT_V(n) asm volatile("s_waitcnt vmcnt(" #n ")" ::: "memory")
; #define PG8_WAIT_L(n) asm volatile("s_waitcnt lgkmcnt(" #n ")" ::: "memory")
; #define PG8_BAR __builtin_amdgcn_s_barrier()
; #define PG8_SCHED __builtin_amdgcn_sched_barrier(0)
; template <class Epi, class Sched, bool ALIGN_EPI = false, bool SP2 = false, bool AGM = false  >
; __device__ __forceinline__ void gemm_phase(PG8_LAS unsigned char* lds, const Gemm g, const Sched& S, const Epi& E) {
;     ...
;             PG8_LDA(At, 1, 1); PG8_STAGE(PG8_SB(1, 0), b3, voffB); PG8_STAGE(PG8_SB(1, 1), b3 + hstep, voffB); PG8_STAGE(PG8_SA(1, 0), a3, voffA);
;             PG8_WAIT_V(8); PG8_WAIT_L(0); PG8_BAR; PG8_MMA(1, 0, At, B0); PG8_MMA(1, 1, At, B1); PG8_BAR; PG8_SCHED;
	s_add_i32 s24, s71, s37
	v_lshl_add_u64 v[224:225], v[224:225], 0, s[12:13]
	s_mov_b32 m0, s24
	ds_read_b128 v[192:195], v159 offset:49152
	ds_read_b128 v[196:199], v159 offset:50176
	ds_read_b128 v[200:203], v159 offset:51200
	ds_read_b128 v[204:207], v159 offset:52224
	ds_read_b128 v[208:211], v159 offset:53248
	ds_read_b128 v[212:215], v159 offset:54272
	ds_read_b128 v[216:219], v159 offset:55296
	ds_read_b128 v[220:223], v159 offset:56320
	global_load_lds_dwordx4 v[224:225], off
	s_add_i32 m0, s24, 0x2000
	s_add_u32 s24, s30, 0x20080
	v_lshl_add_u64 v[224:225], v[226:227], 0, s[12:13]
	s_addc_u32 s25, s31, 0
	s_add_i32 s30, s72, s37
	global_load_lds_dwordx4 v[224:225], off
	v_lshl_add_u64 v[224:225], s[24:25], 0, v[134:135]
	s_mov_b32 m0, s30
	s_nop 0
	global_load_lds_dwordx4 v[224:225], off
	v_lshl_add_u64 v[224:225], s[24:25], 0, v[130:131]
	s_add_i32 m0, s30, 0x2000
	s_nop 0
	global_load_lds_dwordx4 v[224:225], off
	v_lshl_add_u64 v[224:225], s[28:29], 0, v[136:137]
	s_mov_b32 m0, s44
	s_nop 0
	global_load_lds_dwordx4 v[224:225], off
	v_lshl_add_u64 v[224:225], s[28:29], 0, v[132:133]
	s_mov_b32 m0, s45
	s_nop 0
	global_load_lds_dwordx4 v[224:225], off
	s_waitcnt vmcnt(8)
	s_waitcnt lgkmcnt(0)
	s_barrier
	s_setprio 1
	s_waitcnt lgkmcnt(0)
	v_mfma_f32_16x16x32_bf16 v[62:65], v[150:153], v[192:195], v[62:65]
	v_mfma_f32_16x16x32_bf16 v[58:61], v[168:171], v[192:195], v[58:61]
	v_mfma_f32_16x16x32_bf16 v[46:49], v[150:153], v[200:203], v[46:49]
	v_mfma_f32_16x16x32_bf16 v[42:45], v[168:171], v[200:203], v[42:45]
	v_mfma_f32_16x16x32_bf16 v[30:33], v[150:153], v[208:211], v[30:33]
	v_mfma_f32_16x16x32_bf16 v[26:29], v[168:171], v[208:211], v[26:29]
	v_mfma_f32_16x16x32_bf16 v[14:17], v[150:153], v[216:219], v[14:17]
	v_mfma_f32_16x16x32_bf16 v[10:13], v[168:171], v[216:219], v[10:13]
	v_mfma_f32_16x16x32_bf16 v[62:65], v[164:167], v[196:199], v[62:65]
	v_mfma_f32_16x16x32_bf16 v[58:61], v[172:175], v[196:199], v[58:61]
	v_mfma_f32_16x16x32_bf16 v[46:49], v[164:167], v[204:207], v[46:49]
	v_mfma_f32_16x16x32_bf16 v[42:45], v[172:175], v[204:207], v[42:45]
	v_mfma_f32_16x16x32_bf16 v[30:33], v[164:167], v[212:215], v[30:33]
	v_mfma_f32_16x16x32_bf16 v[26:29], v[172:175], v[212:215], v[26:29]
	v_mfma_f32_16x16x32_bf16 v[14:17], v[164:167], v[220:223], v[14:17]
	v_mfma_f32_16x16x32_bf16 v[10:13], v[172:175], v[220:223], v[10:13]
	v_mfma_f32_16x16x32_bf16 v[54:57], v[176:179], v[192:195], v[54:57]
	v_mfma_f32_16x16x32_bf16 v[50:53], v[184:187], v[192:195], v[50:53]
	v_mfma_f32_16x16x32_bf16 v[38:41], v[176:179], v[200:203], v[38:41]
	v_mfma_f32_16x16x32_bf16 v[34:37], v[184:187], v[200:203], v[34:37]
	v_mfma_f32_16x16x32_bf16 v[22:25], v[176:179], v[208:211], v[22:25]
	v_mfma_f32_16x16x32_bf16 v[18:21], v[184:187], v[208:211], v[18:21]
	v_mfma_f32_16x16x32_bf16 v[6:9], v[176:179], v[216:219], v[6:9]
	v_mfma_f32_16x16x32_bf16 v[2:5], v[184:187], v[216:219], v[2:5]
	v_mfma_f32_16x16x32_bf16 v[54:57], v[180:183], v[196:199], v[54:57]
	v_mfma_f32_16x16x32_bf16 v[50:53], v[188:191], v[196:199], v[50:53]
	v_mfma_f32_16x16x32_bf16 v[38:41], v[180:183], v[204:207], v[38:41]
	v_mfma_f32_16x16x32_bf16 v[34:37], v[188:191], v[204:207], v[34:37]
	v_mfma_f32_16x16x32_bf16 v[22:25], v[180:183], v[212:215], v[22:25]
	v_mfma_f32_16x16x32_bf16 v[18:21], v[188:191], v[212:215], v[18:21]
	v_mfma_f32_16x16x32_bf16 v[6:9], v[180:183], v[220:223], v[6:9]
	v_mfma_f32_16x16x32_bf16 v[2:5], v[188:191], v[220:223], v[2:5]
	s_setprio 0
	s_barrier
	s_add_i32 s70, s70, 2
	s_add_u32 s68, s68, 0x100
	s_addc_u32 s69, s69, 0
	s_cmp_gt_u32 s70, 5
	s_mov_b64 s[24:25], s[26:27]
	s_cbranch_scc0 .LBB0_677
	s_and_b64 vcc, exec, s[14:15]
	s_cbranch_vccz .LBB0_680
	s_barrier

; #define PG8_STAGE(bufoff, gbase, voff) do { _Pragma("unroll") for (int _i = 0; _i < 2; ++_i) \
;         __builtin_amdgcn_global_load_lds((const unsigned*)((const char*)(gbase) + (voff)[_i]), (PG8_LAS unsigned*)(lds + (bufoff) + ldsw + _i * 8192), 16, 0, 0); } while (0)
; #define PG8_LDA(dst, b, h) do { _Pragma("unroll") for (int m = 0; m < 4; ++m) _Pragma("unroll") for (int k = 0; k < 2; ++k) dst[m][k] = *(const PG8_LAS bf16x8*)(lds + PG8_SA(b, h) + aoff + m * 2048 + k * 1024); } while (0)
; #define PG8_LDB(dst, b, h) do { _Pragma("unroll") for (int n = 0; n < 2; ++n) _Pragma("unroll") for (int k = 0; k < 2; ++k) dst[n][k] = *(const PG8_LAS bf16x8*)(lds + PG8_SB(b, h) + boff + n * 2048 + k * 1024); } while (0)
; #define PG8_MMA(ai, bj, At, Bt) do { __builtin_amdgcn_s_setprio(1); _Pragma("unroll") for (int m = 0; m < 4; ++m) _Pragma("unroll") for (int n = 0; n < 2; ++n) _Pragma("unroll") for (int k = 0; k < 2; ++k) \
;         acc[ai][bj][m][n] = __builtin_amdgcn_mfma_f32_16x16x32_bf16(Bt[n][k], At[m][k], acc[ai][bj][m][n], 0, 0, 0); __builtin_amdgcn_s_setprio(0); } while (0)
; #define PG8_WAIT_V(n) asm volatile("s_waitcnt vmcnt(" #n ")" ::: "memory")
; #define PG8_WAIT_L(n) asm volatile("s_waitcnt lgkmcnt(" #n ")" ::: "memory")
; #define PG8_BAR __builtin_amdgcn_s_barrier()
; #define PG8_SCHED __builtin_amdgcn_sched_barrier(0)
; template <class Epi, class Sched, bool ALIGN_EPI = false, bool SP2 = false, bool AGM = false  >
; __device__ __forceinline__ void gemm_phase(PG8_LAS unsigned char* lds, const Gemm g, const Sched& S, const Epi& E) {
;     ...
;             const bool last = (t == nt - 2);
;             const char* a1 = cA + (size_t)(t + 1) * kstepA;
;             const char* a2 = last ? nA : cA + (size_t)(t + 2) * kstepA; const char* b2 = last ? nB : cB + (size_t)(t + 2) * kstep;
;             const char* a3 = a2 + kstepA; const char* b3 = b2 + kstep;
;             if (last && has_next) S.a_ready(nxt);
;             if constexpr (SP2) {
;             PG8_LDB(B0, 0, 0); PG8_LDB(B1, 0, 1); PG8_SCHED; PG8_LDA(At, 0, 0); PG8_STAGE(PG8_SA(1, 1), a1 + hstepA, voffA);
;             PG8_WAIT_V(8); PG8_WAIT_L(0); PG8_BAR; PG8_MMA(0, 0, At, B0); PG8_MMA(0, 1, At, B1); PG8_BAR; PG8_SCHED;
;             PG8_LDA(At, 0, 1); PG8_STAGE(PG8_SB(0, 0), b2, voffB); PG8_STAGE(PG8_SB(0, 1), b2 + hstep, voffB); PG8_STAGE(PG8_SA(0, 0), a2, voffA);
.LBB0_783:
	ds_read_b128 v[130:133], v186
	ds_read_b128 v[134:137], v186 offset:1024
	ds_read_b128 v[138:141], v186 offset:2048
	ds_read_b128 v[142:145], v186 offset:3072
	ds_read_b128 v[146:149], v187
	ds_read_b128 v[150:153], v187 offset:1024
	ds_read_b128 v[178:181], v187 offset:2048
	ds_read_b128 v[194:197], v187 offset:3072
	s_add_u32 s40, s38, 0xfffc0080
	s_addc_u32 s41, s39, -1
	s_cmp_eq_u32 s75, 12
	s_cselect_b32 s43, s5, s41
	s_cselect_b32 s42, s31, s40
	s_cselect_b32 s41, s29, s74
	s_cselect_b32 s40, s33, s62
	v_lshl_add_u64 v[182:183], s[38:39], 0, v[170:171]
	s_add_i32 m0, s44, 0xc000
	ds_read_b128 v[198:201], v188
	ds_read_b128 v[202:205], v188 offset:1024
	ds_read_b128 v[206:209], v188 offset:2048
	ds_read_b128 v[210:213], v188 offset:3072
	ds_read_b128 v[214:217], v188 offset:4096
	ds_read_b128 v[218:221], v188 offset:5120
	ds_read_b128 v[222:225], v188 offset:6144
	ds_read_b128 v[226:229], v188 offset:7168
	global_load_lds_dwordx4 v[182:183], off
	v_lshl_add_u64 v[182:183], s[38:39], 0, v[172:173]
	s_add_i32 m0, s44, 0xe000
	s_nop 0
	global_load_lds_dwordx4 v[182:183], off
	s_waitcnt vmcnt(8)
	s_waitcnt lgkmcnt(0)
	s_barrier
	s_setprio 1
	s_waitcnt lgkmcnt(0)
	v_mfma_f32_16x16x32_bf16 v[126:129], v[130:133], v[198:201], v[126:129]
	v_mfma_f32_16x16x32_bf16 v[122:125], v[138:141], v[198:201], v[122:125]
	v_mfma_f32_16x16x32_bf16 v[110:113], v[130:133], v[206:209], v[110:113]
	v_mfma_f32_16x16x32_bf16 v[106:109], v[138:141], v[206:209], v[106:109]
	v_mfma_f32_16x16x32_bf16 v[94:97], v[130:133], v[214:217], v[94:97]
	v_mfma_f32_16x16x32_bf16 v[90:93], v[138:141], v[214:217], v[90:93]
	v_mfma_f32_16x16x32_bf16 v[78:81], v[130:133], v[222:225], v[78:81]
	v_mfma_f32_16x16x32_bf16 v[74:77], v[138:141], v[222:225], v[74:77]
	v_mfma_f32_16x16x32_bf16 v[126:129], v[134:137], v[202:205], v[126:129]
	v_mfma_f32_16x16x32_bf16 v[122:125], v[142:145], v[202:205], v[122:125]
	v_mfma_f32_16x16x32_bf16 v[110:113], v[134:137], v[210:213], v[110:113]
	v_mfma_f32_16x16x32_bf16 v[106:109], v[142:145], v[210:213], v[106:109]
	v_mfma_f32_16x16x32_bf16 v[94:97], v[134:137], v[218:221], v[94:97]
	v_mfma_f32_16x16x32_bf16 v[90:93], v[142:145], v[218:221], v[90:93]
	v_mfma_f32_16x16x32_bf16 v[78:81], v[134:137], v[226:229], v[78:81]
	v_mfma_f32_16x16x32_bf16 v[74:77], v[142:145], v[226:229], v[74:77]
	v_mfma_f32_16x16x32_bf16 v[118:121], v[146:149], v[198:201], v[118:121]
	v_mfma_f32_16x16x32_bf16 v[114:117], v[178:181], v[198:201], v[114:117]
	v_mfma_f32_16x16x32_bf16 v[102:105], v[146:149], v[206:209], v[102:105]
	v_mfma_f32_16x16x32_bf16 v[98:101], v[178:181], v[206:209], v[98:101]
	v_mfma_f32_16x16x32_bf16 v[86:89], v[146:149], v[214:217], v[86:89]
	v_mfma_f32_16x16x32_bf16 v[82:85], v[178:181], v[214:217], v[82:85]
	v_mfma_f32_16x16x32_bf16 v[70:73], v[146:149], v[222:225], v[70:73]
	v_mfma_f32_16x16x32_bf16 v[66:69], v[178:181], v[222:225], v[66:69]
	v_mfma_f32_16x16x32_bf16 v[118:121], v[150:153], v[202:205], v[118:121]
	v_mfma_f32_16x16x32_bf16 v[114:117], v[194:197], v[202:205], v[114:117]
	v_mfma_f32_16x16x32_bf16 v[102:105], v[150:153], v[210:213], v[102:105]
	v_mfma_f32_16x16x32_bf16 v[98:101], v[194:197], v[210:213], v[98:101]
	v_mfma_f32_16x16x32_bf16 v[86:89], v[150:153], v[218:221], v[86:89]
	v_mfma_f32_16x16x32_bf16 v[82:85], v[194:197], v[218:221], v[82:85]
	v_mfma_f32_16x16x32_bf16 v[70:73], v[150:153], v[226:229], v[70:73]
	v_mfma_f32_16x16x32_bf16 v[66:69], v[194:197], v[226:229], v[66:69]
	s_setprio 0
	s_barrier
	s_add_i32 s76, s71, s3
	v_lshl_add_u64 v[182:183], s[40:41], 0, v[158:159]
	s_mov_b32 m0, s76
	ds_read_b128 v[198:201], v188 offset:16384
	ds_read_b128 v[202:205], v188 offset:17408
	ds_read_b128 v[206:209], v188 offset:18432
	ds_read_b128 v[210:213], v188 offset:19456
	ds_read_b128 v[214:217], v188 offset:20480
	ds_read_b128 v[218:221], v188 offset:21504
	ds_read_b128 v[222:225], v188 offset:22528
	ds_read_b128 v[226:229], v188 offset:23552
	global_load_lds_dwordx4 v[182:183], off
	s_add_i32 m0, s76, 0x2000
	s_add_u32 s76, s40, 0x40000
	v_lshl_add_u64 v[230:231], s[40:41], 0, v[162:163]
	s_addc_u32 s77, s41, 0
	s_add_i32 s78, s72, s3
	global_load_lds_dwordx4 v[230:231], off
	v_lshl_add_u64 v[232:233], s[76:77], 0, v[158:159]
	s_mov_b32 m0, s78
	v_lshl_add_u64 v[234:235], s[42:43], 0, v[160:161]
	global_load_lds_dwordx4 v[232:233], off
	v_lshl_add_u64 v[232:233], s[76:77], 0, v[162:163]
	s_add_i32 m0, s78, 0x2000
	s_nop 0
	global_load_lds_dwordx4 v[232:233], off
	v_lshl_add_u64 v[232:233], s[42:43], 0, v[156:157]
	s_mov_b32 m0, s44
	s_nop 0
	global_load_lds_dwordx4 v[232:233], off
	s_mov_b32 m0, s45
	s_nop 0
	global_load_lds_dwordx4 v[234:235], off
	s_waitcnt vmcnt(8)
	s_waitcnt lgkmcnt(0)
	s_barrier
; #define PG8_STAGE(bufoff, gbase, voff) do { _Pragma("unroll") for (int _i = 0; _i < 2; ++_i) \
;         __builtin_amdgcn_global_load_lds((const unsigned*)((const char*)(gbase) + (voff)[_i]), (PG8_LAS unsigned*)(lds + (bufoff) + ldsw + _i * 8192), 16, 0, 0); } while (0)
; #define PG8_LDA(dst, b, h) do { _Pragma("unroll") for (int m = 0; m < 4; ++m) _Pragma("unroll") for (int k = 0; k < 2; ++k) dst[m][k] = *(const PG8_LAS bf16x8*)(lds + PG8_SA(b, h) + aoff + m * 2048 + k * 1024); } while (0)
; #define PG8_LDB(dst, b, h) do { _Pragma("unroll") for (int n = 0; n < 2; ++n) _Pragma("unroll") for (int k = 0; k < 2; ++k) dst[n][k] = *(const PG8_LAS bf16x8*)(lds + PG8_SB(b, h) + boff + n * 2048 + k * 1024); } while (0)
; #define PG8_MMA(ai, bj, At, Bt) do { __builtin_amdgcn_s_setprio(1); _Pragma("unroll") for (int m = 0; m < 4; ++m) _Pragma("unroll") for (int n = 0; n < 2; ++n) _Pragma("unroll") for (int k = 0; k < 2; ++k) \
;         acc[ai][bj][m][n] = __builtin_amdgcn_mfma_f32_16x16x32_bf16(Bt[n][k], At[m][k], acc[ai][bj][m][n], 0, 0, 0); __builtin_amdgcn_s_setprio(0); } while (0)
; #define PG8_WAIT_V(n) asm volatile("s_waitcnt vmcnt(" #n ")" ::: "memory")
; #define PG8_WAIT_L(n) asm volatile("s_waitcnt lgkmcnt(" #n ")" ::: "memory")
; #define PG8_BAR __builtin_amdgcn_s_barrier()
; #define PG8_SCHED __builtin_amdgcn_sched_barrier(0)
; template <class Epi, class Sched, bool ALIGN_EPI = false, bool SP2 = false, bool AGM = false  >
; __device__ __forceinline__ void gemm_phase(PG8_LAS unsigned char* lds, const Gemm g, const Sched& S, const Epi& E) {
;     ...
;             PG8_WAIT_V(8); PG8_WAIT_L(0); PG8_BAR; PG8_MMA(1, 0, At, B0); PG8_MMA(1, 1, At, B1); PG8_BAR; PG8_SCHED;
;             PG8_LDB(B0, 1, 0); PG8_LDB(B1, 1, 1); PG8_SCHED; PG8_LDA(At, 1, 0); PG8_STAGE(PG8_SA(0, 1), a2 + hstepA, voffA);
;             PG8_WAIT_V(8); PG8_WAIT_L(0); PG8_BAR; PG8_MMA(0, 0, At, B0); PG8_MMA(0, 1, At, B1); PG8_BAR; PG8_SCHED;
	s_setprio 1
	s_waitcnt lgkmcnt(0)
	v_mfma_f32_16x16x32_bf16 v[62:65], v[130:133], v[198:201], v[62:65]
	v_mfma_f32_16x16x32_bf16 v[58:61], v[138:141], v[198:201], v[58:61]
	v_mfma_f32_16x16x32_bf16 v[46:49], v[130:133], v[206:209], v[46:49]
	v_mfma_f32_16x16x32_bf16 v[42:45], v[138:141], v[206:209], v[42:45]
	v_mfma_f32_16x16x32_bf16 v[30:33], v[130:133], v[214:217], v[30:33]
	v_mfma_f32_16x16x32_bf16 v[26:29], v[138:141], v[214:217], v[26:29]
	v_mfma_f32_16x16x32_bf16 v[14:17], v[130:133], v[222:225], v[14:17]
	v_mfma_f32_16x16x32_bf16 v[10:13], v[138:141], v[222:225], v[10:13]
	v_mfma_f32_16x16x32_bf16 v[62:65], v[134:137], v[202:205], v[62:65]
	v_mfma_f32_16x16x32_bf16 v[58:61], v[142:145], v[202:205], v[58:61]
	v_mfma_f32_16x16x32_bf16 v[46:49], v[134:137], v[210:213], v[46:49]
	v_mfma_f32_16x16x32_bf16 v[42:45], v[142:145], v[210:213], v[42:45]
	v_mfma_f32_16x16x32_bf16 v[30:33], v[134:137], v[218:221], v[30:33]
	v_mfma_f32_16x16x32_bf16 v[26:29], v[142:145], v[218:221], v[26:29]
	v_mfma_f32_16x16x32_bf16 v[14:17], v[134:137], v[226:229], v[14:17]
	v_mfma_f32_16x16x32_bf16 v[10:13], v[142:145], v[226:229], v[10:13]
	v_mfma_f32_16x16x32_bf16 v[54:57], v[146:149], v[198:201], v[54:57]
	v_mfma_f32_16x16x32_bf16 v[50:53], v[178:181], v[198:201], v[50:53]
	v_mfma_f32_16x16x32_bf16 v[38:41], v[146:149], v[206:209], v[38:41]
	v_mfma_f32_16x16x32_bf16 v[34:37], v[178:181], v[206:209], v[34:37]
	v_mfma_f32_16x16x32_bf16 v[22:25], v[146:149], v[214:217], v[22:25]
	v_mfma_f32_16x16x32_bf16 v[18:21], v[178:181], v[214:217], v[18:21]
	v_mfma_f32_16x16x32_bf16 v[6:9], v[146:149], v[222:225], v[6:9]
	v_mfma_f32_16x16x32_bf16 v[2:5], v[178:181], v[222:225], v[2:5]
	v_mfma_f32_16x16x32_bf16 v[54:57], v[150:153], v[202:205], v[54:57]
	v_mfma_f32_16x16x32_bf16 v[50:53], v[194:197], v[202:205], v[50:53]
	v_mfma_f32_16x16x32_bf16 v[38:41], v[150:153], v[210:213], v[38:41]
	v_mfma_f32_16x16x32_bf16 v[34:37], v[194:197], v[210:213], v[34:37]
	v_mfma_f32_16x16x32_bf16 v[22:25], v[150:153], v[218:221], v[22:25]
	v_mfma_f32_16x16x32_bf16 v[18:21], v[194:197], v[218:221], v[18:21]
	v_mfma_f32_16x16x32_bf16 v[6:9], v[150:153], v[226:229], v[6:9]
	v_mfma_f32_16x16x32_bf16 v[2:5], v[194:197], v[226:229], v[2:5]
	s_setprio 0
	s_barrier
	s_add_i32 s76, 0, 0x18000
	s_add_i32 s77, 0, 0x1c000
	v_add_u32_e32 v142, s76, v184
	v_add_u32_e32 v164, s77, v184
	ds_read_b128 v[130:133], v142
	ds_read_b128 v[134:137], v142 offset:1024
	ds_read_b128 v[138:141], v142 offset:2048
	ds_read_b128 v[142:145], v142 offset:3072
	ds_read_b128 v[146:149], v164
	ds_read_b128 v[150:153], v164 offset:1024
	ds_read_b128 v[178:181], v164 offset:2048
	ds_read_b128 v[194:197], v164 offset:3072
	s_add_u32 s42, s42, 0x40000
	s_addc_u32 s43, s43, 0
	s_mov_b32 m0, s53
	v_lshl_add_u64 v[236:237], s[42:43], 0, v[156:157]
	ds_read_b128 v[198:201], v188 offset:32768
	ds_read_b128 v[202:205], v188 offset:33792
	ds_read_b128 v[206:209], v188 offset:34816
	ds_read_b128 v[210:213], v188 offset:35840
	ds_read_b128 v[214:217], v188 offset:36864
	ds_read_b128 v[218:221], v188 offset:37888
	ds_read_b128 v[222:225], v188 offset:38912
	ds_read_b128 v[226:229], v188 offset:39936
	global_load_lds_dwordx4 v[236:237], off
	v_lshl_add_u64 v[236:237], s[42:43], 0, v[160:161]
	s_mov_b32 m0, s54
	s_nop 0
	global_load_lds_dwordx4 v[236:237], off
	s_waitcnt vmcnt(8)
	s_waitcnt lgkmcnt(0)
	s_barrier
	s_setprio 1
	s_waitcnt lgkmcnt(0)
	v_mfma_f32_16x16x32_bf16 v[126:129], v[130:133], v[198:201], v[126:129]
	v_mfma_f32_16x16x32_bf16 v[122:125], v[138:141], v[198:201], v[122:125]
	v_mfma_f32_16x16x32_bf16 v[110:113], v[130:133], v[206:209], v[110:113]
	v_mfma_f32_16x16x32_bf16 v[106:109], v[138:141], v[206:209], v[106:109]
	v_mfma_f32_16x16x32_bf16 v[94:97], v[130:133], v[214:217], v[94:97]
	v_mfma_f32_16x16x32_bf16 v[90:93], v[138:141], v[214:217], v[90:93]
	v_mfma_f32_16x16x32_bf16 v[78:81], v[130:133], v[222:225], v[78:81]
	v_mfma_f32_16x16x32_bf16 v[74:77], v[138:141], v[222:225], v[74:77]
	v_mfma_f32_16x16x32_bf16 v[126:129], v[134:137], v[202:205], v[126:129]
	v_mfma_f32_16x16x32_bf16 v[122:125], v[142:145], v[202:205], v[122:125]
	v_mfma_f32_16x16x32_bf16 v[110:113], v[134:137], v[210:213], v[110:113]
	v_mfma_f32_16x16x32_bf16 v[106:109], v[142:145], v[210:213], v[106:109]
	v_mfma_f32_16x16x32_bf16 v[94:97], v[134:137], v[218:221], v[94:97]
	v_mfma_f32_16x16x32_bf16 v[90:93], v[142:145], v[218:221], v[90:93]
	v_mfma_f32_16x16x32_bf16 v[78:81], v[134:137], v[226:229], v[78:81]
	v_mfma_f32_16x16x32_bf16 v[74:77], v[142:145], v[226:229], v[74:77]
	v_mfma_f32_16x16x32_bf16 v[118:121], v[146:149], v[198:201], v[118:121]
	v_mfma_f32_16x16x32_bf16 v[114:117], v[178:181], v[198:201], v[114:117]
	v_mfma_f32_16x16x32_bf16 v[102:105], v[146:149], v[206:209], v[102:105]
	v_mfma_f32_16x16x32_bf16 v[98:101], v[178:181], v[206:209], v[98:101]
	v_mfma_f32_16x16x32_bf16 v[86:89], v[146:149], v[214:217], v[86:89]
	v_mfma_f32_16x16x32_bf16 v[82:85], v[178:181], v[214:217], v[82:85]
	v_mfma_f32_16x16x32_bf16 v[70:73], v[146:149], v[222:225], v[70:73]
	v_mfma_f32_16x16x32_bf16 v[66:69], v[178:181], v[222:225], v[66:69]
	v_mfma_f32_16x16x32_bf16 v[118:121], v[150:153], v[202:205], v[118:121]
	v_mfma_f32_16x16x32_bf16 v[114:117], v[194:197], v[202:205], v[114:117]
	v_mfma_f32_16x16x32_bf16 v[102:105], v[150:153], v[210:213], v[102:105]
	v_mfma_f32_16x16x32_bf16 v[98:101], v[194:197], v[210:213], v[98:101]
	v_mfma_f32_16x16x32_bf16 v[86:89], v[150:153], v[218:221], v[86:89]
	v_mfma_f32_16x16x32_bf16 v[82:85], v[194:197], v[218:221], v[82:85]
	v_mfma_f32_16x16x32_bf16 v[70:73], v[150:153], v[226:229], v[70:73]
	v_mfma_f32_16x16x32_bf16 v[66:69], v[194:197], v[226:229], v[66:69]
	s_setprio 0
	s_barrier
; #define PG8_STAGE(bufoff, gbase, voff) do { _Pragma("unroll") for (int _i = 0; _i < 2; ++_i) \
;         __builtin_amdgcn_global_load_lds((const unsigned*)((const char*)(gbase) + (voff)[_i]), (PG8_LAS unsigned*)(lds + (bufoff) + ldsw + _i * 8192), 16, 0, 0); } while (0)
; #define PG8_LDA(dst, b, h) do { _Pragma("unroll") for (int m = 0; m < 4; ++m) _Pragma("unroll") for (int k = 0; k < 2; ++k) dst[m][k] = *(const PG8_LAS bf16x8*)(lds + PG8_SA(b, h) + aoff + m * 2048 + k * 1024); } while (0)
; #define PG8_MMA(ai, bj, At, Bt) do { __builtin_amdgcn_s_setprio(1); _Pragma("unroll") for (int m = 0; m < 4; ++m) _Pragma("unroll") for (int n = 0; n < 2; ++n) _Pragma("unroll") for (int k = 0; k < 2; ++k) \
;         acc[ai][bj][m][n] = __builtin_amdgcn_mfma_f32_16x16x32_bf16(Bt[n][k], At[m][k], acc[ai][bj][m][n], 0, 0, 0); __builtin_amdgcn_s_setprio(0); } while (0)
; #define PG8_WAIT_V(n) asm volatile("s_waitcnt vmcnt(" #n ")" ::: "memory")
; #define PG8_WAIT_L(n) asm volatile("s_waitcnt lgkmcnt(" #n ")" ::: "memory")
; #define PG8_BAR __builtin_amdgcn_s_barrier()
; #define PG8_SCHED __builtin_amdgcn_sched_barrier(0)
; template <class Epi, class Sched, bool ALIGN_EPI = false, bool SP2 = false, bool AGM = false  >
; __device__ __forceinline__ void gemm_phase(PG8_LAS unsigned char* lds, const Gemm g, const Sched& S, const Epi& E) {
;     ...
;             PG8_LDA(At, 1, 1); PG8_STAGE(PG8_SB(1, 0), b3, voffB); PG8_STAGE(PG8_SB(1, 1), b3 + hstep, voffB); PG8_STAGE(PG8_SA(1, 0), a3, voffA);
;             PG8_WAIT_V(8); PG8_WAIT_L(0); PG8_BAR; PG8_MMA(1, 0, At, B0); PG8_MMA(1, 1, At, B1); PG8_BAR; PG8_SCHED;
	s_add_i32 s42, s76, s3
	v_lshl_add_u64 v[182:183], v[182:183], 0, s[24:25]
	s_mov_b32 m0, s42
	ds_read_b128 v[198:201], v188 offset:49152
	ds_read_b128 v[202:205], v188 offset:50176
	ds_read_b128 v[206:209], v188 offset:51200
	ds_read_b128 v[210:213], v188 offset:52224
	ds_read_b128 v[214:217], v188 offset:53248
	ds_read_b128 v[218:221], v188 offset:54272
	ds_read_b128 v[222:225], v188 offset:55296
	ds_read_b128 v[226:229], v188 offset:56320
	global_load_lds_dwordx4 v[182:183], off
	s_add_i32 m0, s42, 0x2000
	s_add_u32 s40, s40, 0x40080
	v_lshl_add_u64 v[182:183], v[230:231], 0, s[24:25]
	s_addc_u32 s41, s41, 0
	s_add_i32 s42, s77, s3
	global_load_lds_dwordx4 v[182:183], off
	v_lshl_add_u64 v[182:183], s[40:41], 0, v[158:159]
	s_mov_b32 m0, s42
	s_nop 0
	global_load_lds_dwordx4 v[182:183], off
	v_lshl_add_u64 v[182:183], s[40:41], 0, v[162:163]
	s_add_i32 m0, s42, 0x2000
	s_nop 0
	global_load_lds_dwordx4 v[182:183], off
	v_lshl_add_u64 v[182:183], v[232:233], 0, s[24:25]
	s_mov_b32 m0, s60
	s_nop 0
	global_load_lds_dwordx4 v[182:183], off
	v_lshl_add_u64 v[182:183], v[234:235], 0, s[24:25]
	s_mov_b32 m0, s61
	s_nop 0
	global_load_lds_dwordx4 v[182:183], off
	s_waitcnt vmcnt(8)
	s_waitcnt lgkmcnt(0)
	s_barrier
	s_setprio 1
	s_waitcnt lgkmcnt(0)
	v_mfma_f32_16x16x32_bf16 v[62:65], v[130:133], v[198:201], v[62:65]
	v_mfma_f32_16x16x32_bf16 v[58:61], v[138:141], v[198:201], v[58:61]
	v_mfma_f32_16x16x32_bf16 v[46:49], v[130:133], v[206:209], v[46:49]
	v_mfma_f32_16x16x32_bf16 v[42:45], v[138:141], v[206:209], v[42:45]
	v_mfma_f32_16x16x32_bf16 v[30:33], v[130:133], v[214:217], v[30:33]
	v_mfma_f32_16x16x32_bf16 v[26:29], v[138:141], v[214:217], v[26:29]
	v_mfma_f32_16x16x32_bf16 v[14:17], v[130:133], v[222:225], v[14:17]
	v_mfma_f32_16x16x32_bf16 v[10:13], v[138:141], v[222:225], v[10:13]
	v_mfma_f32_16x16x32_bf16 v[62:65], v[134:137], v[202:205], v[62:65]
	v_mfma_f32_16x16x32_bf16 v[58:61], v[142:145], v[202:205], v[58:61]
	v_mfma_f32_16x16x32_bf16 v[46:49], v[134:137], v[210:213], v[46:49]
	v_mfma_f32_16x16x32_bf16 v[42:45], v[142:145], v[210:213], v[42:45]
	v_mfma_f32_16x16x32_bf16 v[30:33], v[134:137], v[218:221], v[30:33]
	v_mfma_f32_16x16x32_bf16 v[26:29], v[142:145], v[218:221], v[26:29]
	v_mfma_f32_16x16x32_bf16 v[14:17], v[134:137], v[226:229], v[14:17]
	v_mfma_f32_16x16x32_bf16 v[10:13], v[142:145], v[226:229], v[10:13]
	v_mfma_f32_16x16x32_bf16 v[54:57], v[146:149], v[198:201], v[54:57]
	v_mfma_f32_16x16x32_bf16 v[50:53], v[178:181], v[198:201], v[50:53]
	v_mfma_f32_16x16x32_bf16 v[38:41], v[146:149], v[206:209], v[38:41]
	v_mfma_f32_16x16x32_bf16 v[34:37], v[178:181], v[206:209], v[34:37]
	v_mfma_f32_16x16x32_bf16 v[22:25], v[146:149], v[214:217], v[22:25]
	v_mfma_f32_16x16x32_bf16 v[18:21], v[178:181], v[214:217], v[18:21]
	v_mfma_f32_16x16x32_bf16 v[6:9], v[146:149], v[222:225], v[6:9]
	v_mfma_f32_16x16x32_bf16 v[2:5], v[178:181], v[222:225], v[2:5]
	v_mfma_f32_16x16x32_bf16 v[54:57], v[150:153], v[202:205], v[54:57]
	v_mfma_f32_16x16x32_bf16 v[50:53], v[194:197], v[202:205], v[50:53]
	v_mfma_f32_16x16x32_bf16 v[38:41], v[150:153], v[210:213], v[38:41]
	v_mfma_f32_16x16x32_bf16 v[34:37], v[194:197], v[210:213], v[34:37]
	v_mfma_f32_16x16x32_bf16 v[22:25], v[150:153], v[218:221], v[22:25]
	v_mfma_f32_16x16x32_bf16 v[18:21], v[194:197], v[218:221], v[18:21]
	v_mfma_f32_16x16x32_bf16 v[6:9], v[150:153], v[226:229], v[6:9]
	v_mfma_f32_16x16x32_bf16 v[2:5], v[194:197], v[226:229], v[2:5]
	s_setprio 0
	s_barrier
	s_add_i32 s75, s75, 2
	s_add_u32 s38, s38, 0x100
	s_addc_u32 s39, s39, 0
	s_add_u32 s62, s62, 0x100
	s_addc_u32 s74, s74, 0
	s_cmp_gt_u32 s75, 13
	s_cbranch_scc0 .LBB0_783
	s_and_b64 vcc, exec, s[26:27]
	s_cbranch_vccz .LBB0_786
	s_barrier

; #define PG8_STAGE(bufoff, gbase, voff) do { _Pragma("unroll") for (int _i = 0; _i < 2; ++_i) \
;         __builtin_amdgcn_global_load_lds((const unsigned*)((const char*)(gbase) + (voff)[_i]), (PG8_LAS unsigned*)(lds + (bufoff) + ldsw + _i * 8192), 16, 0, 0); } while (0)
; #define PG8_LDA(dst, b, h) do { _Pragma("unroll") for (int m = 0; m < 4; ++m) _Pragma("unroll") for (int k = 0; k < 2; ++k) dst[m][k] = *(const PG8_LAS bf16x8*)(lds + PG8_SA(b, h) + aoff + m * 2048 + k * 1024); } while (0)
; #define PG8_LDB(dst, b, h) do { _Pragma("unroll") for (int n = 0; n < 2; ++n) _Pragma("unroll") for (int k = 0; k < 2; ++k) dst[n][k] = *(const PG8_LAS bf16x8*)(lds + PG8_SB(b, h) + boff + n * 2048 + k * 1024); } while (0)
; #define PG8_MMA(ai, bj, At, Bt) do { __builtin_amdgcn_s_setprio(1); _Pragma("unroll") for (int m = 0; m < 4; ++m) _Pragma("unroll") for (int n = 0; n < 2; ++n) _Pragma("unroll") for (int k = 0; k < 2; ++k) \
;         acc[ai][bj][m][n] = __builtin_amdgcn_mfma_f32_16x16x32_bf16(Bt[n][k], At[m][k], acc[ai][bj][m][n], 0, 0, 0); __builtin_amdgcn_s_setprio(0); } while (0)
; template <class Epi, class Sched, bool ALIGN_EPI = false, bool SP2 = false, bool AGM = false  >
; __device__ __forceinline__ void gemm_phase(PG8_LAS unsigned char* lds, const Gemm g, const Sched& S, const Epi& E) {
;     ...
;         const bool has_next = S.next(ui + 1, nxt);
;         const char* nA = has_next ? (const char*)g.A + (size_t)nxt.pm * tstepA : cA; const char* nB = has_next ? (const char*)g.Bt + (size_t)nxt.pn * tstep : cB;
;         for (int t = 0; t < nt; t += 2) {
;             const bool last = (t == nt - 2);
;             const char* a1 = cA + (size_t)(t + 1) * kstepA;
;             const char* a2 = last ? nA : cA + (size_t)(t + 2) * kstepA; const char* b2 = last ? nB : cB + (size_t)(t + 2) * kstep;
;             const char* a3 = a2 + kstepA; const char* b3 = b2 + kstep;
;             if (last && has_next) S.a_ready(nxt);
;             if constexpr (SP2) {
;             PG8_LDB(B0, 0, 0); PG8_LDB(B1, 0, 1); PG8_SCHED; PG8_LDA(At, 0, 0); PG8_STAGE(PG8_SA(1, 1), a1 + hstepA, voffA);
;             PG8_WAIT_V(8); PG8_WAIT_L(0); PG8_BAR; PG8_MMA(0, 0, At, B0); PG8_MMA(0, 1, At, B1); PG8_BAR; PG8_SCHED;
;             PG8_LDA(At, 0, 1); PG8_STAGE(PG8_SB(0, 0), b2, voffB); PG8_STAGE(PG8_SB(0, 1), b2 + hstep, voffB); PG8_STAGE(PG8_SA(0, 0), a2, voffA);
.LBB0_876:
	s_ashr_i32 s23, s22, 31
	s_lshl_b64 s[24:25], s[22:23], 19
	s_add_u32 s24, s46, s24
	s_addc_u32 s25, s47, s25
	s_and_b64 s[26:27], s[0:1], exec
	s_cselect_b32 s23, s25, s29
	s_cselect_b32 s64, s24, s28
	s_ashr_i32 s21, s20, 31
	s_lshl_b64 s[26:27], s[20:21], 19
	s_add_u32 s26, s10, s26
	s_addc_u32 s27, s11, s27
	s_and_b64 s[34:35], s[0:1], exec
	s_cselect_b32 s21, s27, s31
	s_cselect_b32 s65, s26, s30
	s_add_u32 s28, s28, 0x40080
	s_addc_u32 s29, s29, 0
	s_add_u32 s66, s30, 0x100
	s_addc_u32 s67, s31, 0
	s_mov_b32 s68, -2
	s_waitcnt vmcnt(0)
	s_waitcnt lgkmcnt(0)
	ds_read_b128 v[148:151], v156
	ds_read_b128 v[164:167], v156 offset:1024
	ds_read_b128 v[168:171], v156 offset:2048
	ds_read_b128 v[172:175], v156 offset:3072
	ds_read_b128 v[176:179], v157
	ds_read_b128 v[180:183], v157 offset:1024
	ds_read_b128 v[184:187], v157 offset:2048
	ds_read_b128 v[188:191], v157 offset:3072
	s_add_u32 s30, s28, 0xfffc0080
	s_addc_u32 s31, s29, -1
	s_cmp_eq_u32 s68, 12
	s_cselect_b32 s35, s23, s31
	s_cselect_b32 s34, s64, s30
	s_cselect_b32 s31, s21, s67
	s_cselect_b32 s30, s65, s66
	v_lshl_add_u64 v[224:225], s[28:29], 0, v[140:141]
	s_add_i32 m0, s37, 0xc000
	ds_read_b128 v[192:195], v158
	ds_read_b128 v[196:199], v158 offset:1024
	ds_read_b128 v[200:203], v158 offset:2048
	ds_read_b128 v[204:207], v158 offset:3072
	ds_read_b128 v[208:211], v158 offset:4096
	ds_read_b128 v[212:215], v158 offset:5120
	ds_read_b128 v[216:219], v158 offset:6144
	ds_read_b128 v[220:223], v158 offset:7168
	global_load_lds_dwordx4 v[224:225], off
	v_lshl_add_u64 v[224:225], s[28:29], 0, v[142:143]
	s_add_i32 m0, s37, 0xe000
	s_nop 0
	global_load_lds_dwordx4 v[224:225], off
	s_waitcnt vmcnt(8)
	s_waitcnt lgkmcnt(0)
	s_barrier
	s_setprio 1
	s_waitcnt lgkmcnt(0)
	v_mfma_f32_16x16x32_bf16 v[126:129], v[148:151], v[192:195], 0
	v_mfma_f32_16x16x32_bf16 v[122:125], v[168:171], v[192:195], 0
	v_mfma_f32_16x16x32_bf16 v[110:113], v[148:151], v[200:203], 0
	v_mfma_f32_16x16x32_bf16 v[106:109], v[168:171], v[200:203], 0
	v_mfma_f32_16x16x32_bf16 v[94:97], v[148:151], v[208:211], 0
	v_mfma_f32_16x16x32_bf16 v[90:93], v[168:171], v[208:211], 0
	v_mfma_f32_16x16x32_bf16 v[78:81], v[148:151], v[216:219], 0
	v_mfma_f32_16x16x32_bf16 v[74:77], v[168:171], v[216:219], 0
	v_mfma_f32_16x16x32_bf16 v[126:129], v[164:167], v[196:199], v[126:129]
	v_mfma_f32_16x16x32_bf16 v[122:125], v[172:175], v[196:199], v[122:125]
	v_mfma_f32_16x16x32_bf16 v[110:113], v[164:167], v[204:207], v[110:113]
	v_mfma_f32_16x16x32_bf16 v[106:109], v[172:175], v[204:207], v[106:109]
	v_mfma_f32_16x16x32_bf16 v[94:97], v[164:167], v[212:215], v[94:97]
	v_mfma_f32_16x16x32_bf16 v[90:93], v[172:175], v[212:215], v[90:93]
	v_mfma_f32_16x16x32_bf16 v[78:81], v[164:167], v[220:223], v[78:81]
	v_mfma_f32_16x16x32_bf16 v[74:77], v[172:175], v[220:223], v[74:77]
	v_mfma_f32_16x16x32_bf16 v[118:121], v[176:179], v[192:195], 0
	v_mfma_f32_16x16x32_bf16 v[114:117], v[184:187], v[192:195], 0
	v_mfma_f32_16x16x32_bf16 v[102:105], v[176:179], v[200:203], 0
	v_mfma_f32_16x16x32_bf16 v[98:101], v[184:187], v[200:203], 0
	v_mfma_f32_16x16x32_bf16 v[86:89], v[176:179], v[208:211], 0
	v_mfma_f32_16x16x32_bf16 v[82:85], v[184:187], v[208:211], 0
	v_mfma_f32_16x16x32_bf16 v[70:73], v[176:179], v[216:219], 0
	v_mfma_f32_16x16x32_bf16 v[66:69], v[184:187], v[216:219], 0
	v_mfma_f32_16x16x32_bf16 v[118:121], v[180:183], v[196:199], v[118:121]
	v_mfma_f32_16x16x32_bf16 v[114:117], v[188:191], v[196:199], v[114:117]
	v_mfma_f32_16x16x32_bf16 v[102:105], v[180:183], v[204:207], v[102:105]
	v_mfma_f32_16x16x32_bf16 v[98:101], v[188:191], v[204:207], v[98:101]
	v_mfma_f32_16x16x32_bf16 v[86:89], v[180:183], v[212:215], v[86:89]
	v_mfma_f32_16x16x32_bf16 v[82:85], v[188:191], v[212:215], v[82:85]
	v_mfma_f32_16x16x32_bf16 v[70:73], v[180:183], v[220:223], v[70:73]
	v_mfma_f32_16x16x32_bf16 v[66:69], v[188:191], v[220:223], v[66:69]
	s_setprio 0
	s_barrier
	s_add_i32 s69, s53, s3
	v_lshl_add_u64 v[224:225], s[30:31], 0, v[134:135]
	s_mov_b32 m0, s69
	ds_read_b128 v[192:195], v158 offset:16384
	ds_read_b128 v[196:199], v158 offset:17408
	ds_read_b128 v[200:203], v158 offset:18432
	ds_read_b128 v[204:207], v158 offset:19456
	ds_read_b128 v[208:211], v158 offset:20480
	ds_read_b128 v[212:215], v158 offset:21504
	ds_read_b128 v[216:219], v158 offset:22528
	ds_read_b128 v[220:223], v158 offset:23552
	global_load_lds_dwordx4 v[224:225], off
	s_add_i32 m0, s69, 0x2000
	s_add_u32 s70, s30, 0x40000
	v_lshl_add_u64 v[226:227], s[30:31], 0, v[130:131]
	s_addc_u32 s71, s31, 0
	s_add_i32 s69, s54, s3
	global_load_lds_dwordx4 v[226:227], off
	v_lshl_add_u64 v[228:229], s[70:71], 0, v[134:135]
	s_mov_b32 m0, s69
	v_lshl_add_u64 v[230:231], s[34:35], 0, v[132:133]
	global_load_lds_dwordx4 v[228:229], off
	v_lshl_add_u64 v[228:229], s[70:71], 0, v[130:131]
	s_add_i32 m0, s69, 0x2000
	s_nop 0
	global_load_lds_dwordx4 v[228:229], off
	v_lshl_add_u64 v[228:229], s[34:35], 0, v[136:137]
	s_mov_b32 m0, s37
	s_nop 0
	global_load_lds_dwordx4 v[228:229], off
	s_mov_b32 m0, s38
	s_nop 0
	global_load_lds_dwordx4 v[230:231], off
	s_waitcnt vmcnt(8)
	s_waitcnt lgkmcnt(0)
	s_barrier
; #define PG8_STAGE(bufoff, gbase, voff) do { _Pragma("unroll") for (int _i = 0; _i < 2; ++_i) \
;         __builtin_amdgcn_global_load_lds((const unsigned*)((const char*)(gbase) + (voff)[_i]), (PG8_LAS unsigned*)(lds + (bufoff) + ldsw + _i * 8192), 16, 0, 0); } while (0)
; #define PG8_LDA(dst, b, h) do { _Pragma("unroll") for (int m = 0; m < 4; ++m) _Pragma("unroll") for (int k = 0; k < 2; ++k) dst[m][k] = *(const PG8_LAS bf16x8*)(lds + PG8_SA(b, h) + aoff + m * 2048 + k * 1024); } while (0)
; #define PG8_LDB(dst, b, h) do { _Pragma("unroll") for (int n = 0; n < 2; ++n) _Pragma("unroll") for (int k = 0; k < 2; ++k) dst[n][k] = *(const PG8_LAS bf16x8*)(lds + PG8_SB(b, h) + boff + n * 2048 + k * 1024); } while (0)
; #define PG8_MMA(ai, bj, At, Bt) do { __builtin_amdgcn_s_setprio(1); _Pragma("unroll") for (int m = 0; m < 4; ++m) _Pragma("unroll") for (int n = 0; n < 2; ++n) _Pragma("unroll") for (int k = 0; k < 2; ++k) \
;         acc[ai][bj][m][n] = __builtin_amdgcn_mfma_f32_16x16x32_bf16(Bt[n][k], At[m][k], acc[ai][bj][m][n], 0, 0, 0); __builtin_amdgcn_s_setprio(0); } while (0)
; #define PG8_WAIT_V(n) asm volatile("s_waitcnt vmcnt(" #n ")" ::: "memory")
; #define PG8_WAIT_L(n) asm volatile("s_waitcnt lgkmcnt(" #n ")" ::: "memory")
; #define PG8_BAR __builtin_amdgcn_s_barrier()
; #define PG8_SCHED __builtin_amdgcn_sched_barrier(0)
; template <class Epi, class Sched, bool ALIGN_EPI = false, bool SP2 = false, bool AGM = false  >
; __device__ __forceinline__ void gemm_phase(PG8_LAS unsigned char* lds, const Gemm g, const Sched& S, const Epi& E) {
;     ...
;             PG8_WAIT_V(8); PG8_WAIT_L(0); PG8_BAR; PG8_MMA(1, 0, At, B0); PG8_MMA(1, 1, At, B1); PG8_BAR; PG8_SCHED;
;             PG8_LDB(B0, 1, 0); PG8_LDB(B1, 1, 1); PG8_SCHED; PG8_LDA(At, 1, 0); PG8_STAGE(PG8_SA(0, 1), a2 + hstepA, voffA);
;             PG8_WAIT_V(8); PG8_WAIT_L(0); PG8_BAR; PG8_MMA(0, 0, At, B0); PG8_MMA(0, 1, At, B1); PG8_BAR; PG8_SCHED;
	s_setprio 1
	s_waitcnt lgkmcnt(0)
	v_mfma_f32_16x16x32_bf16 v[62:65], v[148:151], v[192:195], 0
	v_mfma_f32_16x16x32_bf16 v[58:61], v[168:171], v[192:195], 0
	v_mfma_f32_16x16x32_bf16 v[46:49], v[148:151], v[200:203], 0
	v_mfma_f32_16x16x32_bf16 v[42:45], v[168:171], v[200:203], 0
	v_mfma_f32_16x16x32_bf16 v[30:33], v[148:151], v[208:211], 0
	v_mfma_f32_16x16x32_bf16 v[26:29], v[168:171], v[208:211], 0
	v_mfma_f32_16x16x32_bf16 v[14:17], v[148:151], v[216:219], 0
	v_mfma_f32_16x16x32_bf16 v[10:13], v[168:171], v[216:219], 0
	v_mfma_f32_16x16x32_bf16 v[62:65], v[164:167], v[196:199], v[62:65]
	v_mfma_f32_16x16x32_bf16 v[58:61], v[172:175], v[196:199], v[58:61]
	v_mfma_f32_16x16x32_bf16 v[46:49], v[164:167], v[204:207], v[46:49]
	v_mfma_f32_16x16x32_bf16 v[42:45], v[172:175], v[204:207], v[42:45]
	v_mfma_f32_16x16x32_bf16 v[30:33], v[164:167], v[212:215], v[30:33]
	v_mfma_f32_16x16x32_bf16 v[26:29], v[172:175], v[212:215], v[26:29]
	v_mfma_f32_16x16x32_bf16 v[14:17], v[164:167], v[220:223], v[14:17]
	v_mfma_f32_16x16x32_bf16 v[10:13], v[172:175], v[220:223], v[10:13]
	v_mfma_f32_16x16x32_bf16 v[54:57], v[176:179], v[192:195], 0
	v_mfma_f32_16x16x32_bf16 v[50:53], v[184:187], v[192:195], 0
	v_mfma_f32_16x16x32_bf16 v[38:41], v[176:179], v[200:203], 0
	v_mfma_f32_16x16x32_bf16 v[34:37], v[184:187], v[200:203], 0
	v_mfma_f32_16x16x32_bf16 v[22:25], v[176:179], v[208:211], 0
	v_mfma_f32_16x16x32_bf16 v[18:21], v[184:187], v[208:211], 0
	v_mfma_f32_16x16x32_bf16 v[6:9], v[176:179], v[216:219], 0
	v_mfma_f32_16x16x32_bf16 v[2:5], v[184:187], v[216:219], 0
	v_mfma_f32_16x16x32_bf16 v[54:57], v[180:183], v[196:199], v[54:57]
	v_mfma_f32_16x16x32_bf16 v[50:53], v[188:191], v[196:199], v[50:53]
	v_mfma_f32_16x16x32_bf16 v[38:41], v[180:183], v[204:207], v[38:41]
	v_mfma_f32_16x16x32_bf16 v[34:37], v[188:191], v[204:207], v[34:37]
	v_mfma_f32_16x16x32_bf16 v[22:25], v[180:183], v[212:215], v[22:25]
	v_mfma_f32_16x16x32_bf16 v[18:21], v[188:191], v[212:215], v[18:21]
	v_mfma_f32_16x16x32_bf16 v[6:9], v[180:183], v[220:223], v[6:9]
	v_mfma_f32_16x16x32_bf16 v[2:5], v[188:191], v[220:223], v[2:5]
	s_setprio 0
	s_barrier
	s_add_i32 s69, 0, 0x18000
	s_add_i32 s70, 0, 0x1c000
	v_add_u32_e32 v172, s69, v155
	v_add_u32_e32 v188, s70, v155
	ds_read_b128 v[148:151], v172
	ds_read_b128 v[164:167], v172 offset:1024
	ds_read_b128 v[168:171], v172 offset:2048
	ds_read_b128 v[172:175], v172 offset:3072
	ds_read_b128 v[176:179], v188
	ds_read_b128 v[180:183], v188 offset:1024
	ds_read_b128 v[184:187], v188 offset:2048
	ds_read_b128 v[188:191], v188 offset:3072
	s_add_u32 s34, s34, 0x40000
	s_addc_u32 s35, s35, 0
	s_mov_b32 m0, s39
	v_lshl_add_u64 v[232:233], s[34:35], 0, v[136:137]
	ds_read_b128 v[192:195], v158 offset:32768
	ds_read_b128 v[196:199], v158 offset:33792
	ds_read_b128 v[200:203], v158 offset:34816
	ds_read_b128 v[204:207], v158 offset:35840
	ds_read_b128 v[208:211], v158 offset:36864
	ds_read_b128 v[212:215], v158 offset:37888
	ds_read_b128 v[216:219], v158 offset:38912
	ds_read_b128 v[220:223], v158 offset:39936
	global_load_lds_dwordx4 v[232:233], off
	v_lshl_add_u64 v[232:233], s[34:35], 0, v[132:133]
	s_mov_b32 m0, s40
	s_nop 0
	global_load_lds_dwordx4 v[232:233], off
	s_waitcnt vmcnt(8)
	s_waitcnt lgkmcnt(0)
	s_barrier
	s_setprio 1
	s_waitcnt lgkmcnt(0)
	v_mfma_f32_16x16x32_bf16 v[126:129], v[148:151], v[192:195], v[126:129]
	v_mfma_f32_16x16x32_bf16 v[122:125], v[168:171], v[192:195], v[122:125]
	v_mfma_f32_16x16x32_bf16 v[110:113], v[148:151], v[200:203], v[110:113]
	v_mfma_f32_16x16x32_bf16 v[106:109], v[168:171], v[200:203], v[106:109]
	v_mfma_f32_16x16x32_bf16 v[94:97], v[148:151], v[208:211], v[94:97]
	v_mfma_f32_16x16x32_bf16 v[90:93], v[168:171], v[208:211], v[90:93]
	v_mfma_f32_16x16x32_bf16 v[78:81], v[148:151], v[216:219], v[78:81]
	v_mfma_f32_16x16x32_bf16 v[74:77], v[168:171], v[216:219], v[74:77]
	v_mfma_f32_16x16x32_bf16 v[126:129], v[164:167], v[196:199], v[126:129]
	v_mfma_f32_16x16x32_bf16 v[122:125], v[172:175], v[196:199], v[122:125]
	v_mfma_f32_16x16x32_bf16 v[110:113], v[164:167], v[204:207], v[110:113]
	v_mfma_f32_16x16x32_bf16 v[106:109], v[172:175], v[204:207], v[106:109]
	v_mfma_f32_16x16x32_bf16 v[94:97], v[164:167], v[212:215], v[94:97]
	v_mfma_f32_16x16x32_bf16 v[90:93], v[172:175], v[212:215], v[90:93]
	v_mfma_f32_16x16x32_bf16 v[78:81], v[164:167], v[220:223], v[78:81]
	v_mfma_f32_16x16x32_bf16 v[74:77], v[172:175], v[220:223], v[74:77]
	v_mfma_f32_16x16x32_bf16 v[118:121], v[176:179], v[192:195], v[118:121]
	v_mfma_f32_16x16x32_bf16 v[114:117], v[184:187], v[192:195], v[114:117]
	v_mfma_f32_16x16x32_bf16 v[102:105], v[176:179], v[200:203], v[102:105]
	v_mfma_f32_16x16x32_bf16 v[98:101], v[184:187], v[200:203], v[98:101]
	v_mfma_f32_16x16x32_bf16 v[86:89], v[176:179], v[208:211], v[86:89]
	v_mfma_f32_16x16x32_bf16 v[82:85], v[184:187], v[208:211], v[82:85]
	v_mfma_f32_16x16x32_bf16 v[70:73], v[176:179], v[216:219], v[70:73]
	v_mfma_f32_16x16x32_bf16 v[66:69], v[184:187], v[216:219], v[66:69]
	v_mfma_f32_16x16x32_bf16 v[118:121], v[180:183], v[196:199], v[118:121]
	v_mfma_f32_16x16x32_bf16 v[114:117], v[188:191], v[196:199], v[114:117]
	v_mfma_f32_16x16x32_bf16 v[102:105], v[180:183], v[204:207], v[102:105]
	v_mfma_f32_16x16x32_bf16 v[98:101], v[188:191], v[204:207], v[98:101]
	v_mfma_f32_16x16x32_bf16 v[86:89], v[180:183], v[212:215], v[86:89]
	v_mfma_f32_16x16x32_bf16 v[82:85], v[188:191], v[212:215], v[82:85]
	v_mfma_f32_16x16x32_bf16 v[70:73], v[180:183], v[220:223], v[70:73]
	v_mfma_f32_16x16x32_bf16 v[66:69], v[188:191], v[220:223], v[66:69]
	s_setprio 0
	s_barrier
; #define PG8_STAGE(bufoff, gbase, voff) do { _Pragma("unroll") for (int _i = 0; _i < 2; ++_i) \
;         __builtin_amdgcn_global_load_lds((const unsigned*)((const char*)(gbase) + (voff)[_i]), (PG8_LAS unsigned*)(lds + (bufoff) + ldsw + _i * 8192), 16, 0, 0); } while (0)
; #define PG8_LDA(dst, b, h) do { _Pragma("unroll") for (int m = 0; m < 4; ++m) _Pragma("unroll") for (int k = 0; k < 2; ++k) dst[m][k] = *(const PG8_LAS bf16x8*)(lds + PG8_SA(b, h) + aoff + m * 2048 + k * 1024); } while (0)
; #define PG8_LDB(dst, b, h) do { _Pragma("unroll") for (int n = 0; n < 2; ++n) _Pragma("unroll") for (int k = 0; k < 2; ++k) dst[n][k] = *(const PG8_LAS bf16x8*)(lds + PG8_SB(b, h) + boff + n * 2048 + k * 1024); } while (0)
; #define PG8_MMA(ai, bj, At, Bt) do { __builtin_amdgcn_s_setprio(1); _Pragma("unroll") for (int m = 0; m < 4; ++m) _Pragma("unroll") for (int n = 0; n < 2; ++n) _Pragma("unroll") for (int k = 0; k < 2; ++k) \
;         acc[ai][bj][m][n] = __builtin_amdgcn_mfma_f32_16x16x32_bf16(Bt[n][k], At[m][k], acc[ai][bj][m][n], 0, 0, 0); __builtin_amdgcn_s_setprio(0); } while (0)
; #define PG8_WAIT_V(n) asm volatile("s_waitcnt vmcnt(" #n ")" ::: "memory")
; #define PG8_WAIT_L(n) asm volatile("s_waitcnt lgkmcnt(" #n ")" ::: "memory")
; #define PG8_BAR __builtin_amdgcn_s_barrier()
; #define PG8_SCHED __builtin_amdgcn_sched_barrier(0)
; template <class Epi, class Sched, bool ALIGN_EPI = false, bool SP2 = false, bool AGM = false  >
; __device__ __forceinline__ void gemm_phase(PG8_LAS unsigned char* lds, const Gemm g, const Sched& S, const Epi& E) {
;     ...
;             PG8_LDB(B0, 0, 0); PG8_LDB(B1, 0, 1); PG8_SCHED; PG8_LDA(At, 0, 0); PG8_STAGE(PG8_SA(1, 1), a1 + hstepA, voffA);
;     ...
;             PG8_LDA(At, 1, 1); PG8_STAGE(PG8_SB(1, 0), b3, voffB); PG8_STAGE(PG8_SB(1, 1), b3 + hstep, voffB); PG8_STAGE(PG8_SA(1, 0), a3, voffA);
;             PG8_WAIT_V(8); PG8_WAIT_L(0); PG8_BAR; PG8_MMA(1, 0, At, B0); PG8_MMA(1, 1, At, B1); PG8_BAR; PG8_SCHED;
	s_add_i32 s34, s69, s3
	v_lshl_add_u64 v[224:225], v[224:225], 0, s[16:17]
	s_mov_b32 m0, s34
	ds_read_b128 v[192:195], v158 offset:49152
	ds_read_b128 v[196:199], v158 offset:50176
	ds_read_b128 v[200:203], v158 offset:51200
	ds_read_b128 v[204:207], v158 offset:52224
	ds_read_b128 v[208:211], v158 offset:53248
	ds_read_b128 v[212:215], v158 offset:54272
	ds_read_b128 v[216:219], v158 offset:55296
	ds_read_b128 v[220:223], v158 offset:56320
	global_load_lds_dwordx4 v[224:225], off
	s_add_i32 m0, s34, 0x2000
	s_add_u32 s30, s30, 0x40080
	v_lshl_add_u64 v[224:225], v[226:227], 0, s[16:17]
	s_addc_u32 s31, s31, 0
	s_add_i32 s34, s70, s3
	global_load_lds_dwordx4 v[224:225], off
	v_lshl_add_u64 v[224:225], s[30:31], 0, v[134:135]
	s_mov_b32 m0, s34
	s_nop 0
	global_load_lds_dwordx4 v[224:225], off
	v_lshl_add_u64 v[224:225], s[30:31], 0, v[130:131]
	s_add_i32 m0, s34, 0x2000
	s_nop 0
	global_load_lds_dwordx4 v[224:225], off
	v_lshl_add_u64 v[224:225], v[228:229], 0, s[16:17]
	s_mov_b32 m0, s43
	s_nop 0
	global_load_lds_dwordx4 v[224:225], off
	v_lshl_add_u64 v[224:225], v[230:231], 0, s[16:17]
	s_mov_b32 m0, s44
	s_nop 0
	global_load_lds_dwordx4 v[224:225], off
	s_waitcnt vmcnt(8)
	s_waitcnt lgkmcnt(0)
	s_barrier
	s_setprio 1
	s_waitcnt lgkmcnt(0)
	v_mfma_f32_16x16x32_bf16 v[62:65], v[148:151], v[192:195], v[62:65]
	v_mfma_f32_16x16x32_bf16 v[58:61], v[168:171], v[192:195], v[58:61]
	v_mfma_f32_16x16x32_bf16 v[46:49], v[148:151], v[200:203], v[46:49]
	v_mfma_f32_16x16x32_bf16 v[42:45], v[168:171], v[200:203], v[42:45]
	v_mfma_f32_16x16x32_bf16 v[30:33], v[148:151], v[208:211], v[30:33]
	v_mfma_f32_16x16x32_bf16 v[26:29], v[168:171], v[208:211], v[26:29]
	v_mfma_f32_16x16x32_bf16 v[14:17], v[148:151], v[216:219], v[14:17]
	v_mfma_f32_16x16x32_bf16 v[10:13], v[168:171], v[216:219], v[10:13]
	v_mfma_f32_16x16x32_bf16 v[62:65], v[164:167], v[196:199], v[62:65]
	v_mfma_f32_16x16x32_bf16 v[58:61], v[172:175], v[196:199], v[58:61]
	v_mfma_f32_16x16x32_bf16 v[46:49], v[164:167], v[204:207], v[46:49]
	v_mfma_f32_16x16x32_bf16 v[42:45], v[172:175], v[204:207], v[42:45]
	v_mfma_f32_16x16x32_bf16 v[30:33], v[164:167], v[212:215], v[30:33]
	v_mfma_f32_16x16x32_bf16 v[26:29], v[172:175], v[212:215], v[26:29]
	v_mfma_f32_16x16x32_bf16 v[14:17], v[164:167], v[220:223], v[14:17]
	v_mfma_f32_16x16x32_bf16 v[10:13], v[172:175], v[220:223], v[10:13]
	v_mfma_f32_16x16x32_bf16 v[54:57], v[176:179], v[192:195], v[54:57]
	v_mfma_f32_16x16x32_bf16 v[50:53], v[184:187], v[192:195], v[50:53]
	v_mfma_f32_16x16x32_bf16 v[38:41], v[176:179], v[200:203], v[38:41]
	v_mfma_f32_16x16x32_bf16 v[34:37], v[184:187], v[200:203], v[34:37]
	v_mfma_f32_16x16x32_bf16 v[22:25], v[176:179], v[208:211], v[22:25]
	v_mfma_f32_16x16x32_bf16 v[18:21], v[184:187], v[208:211], v[18:21]
	v_mfma_f32_16x16x32_bf16 v[6:9], v[176:179], v[216:219], v[6:9]
	v_mfma_f32_16x16x32_bf16 v[2:5], v[184:187], v[216:219], v[2:5]
	v_mfma_f32_16x16x32_bf16 v[54:57], v[180:183], v[196:199], v[54:57]
	v_mfma_f32_16x16x32_bf16 v[50:53], v[188:191], v[196:199], v[50:53]
	v_mfma_f32_16x16x32_bf16 v[38:41], v[180:183], v[204:207], v[38:41]
	v_mfma_f32_16x16x32_bf16 v[34:37], v[188:191], v[204:207], v[34:37]
	v_mfma_f32_16x16x32_bf16 v[22:25], v[180:183], v[212:215], v[22:25]
	v_mfma_f32_16x16x32_bf16 v[18:21], v[188:191], v[212:215], v[18:21]
	v_mfma_f32_16x16x32_bf16 v[6:9], v[180:183], v[220:223], v[6:9]
	v_mfma_f32_16x16x32_bf16 v[2:5], v[188:191], v[220:223], v[2:5]
	s_setprio 0
	s_barrier
	s_add_i32 s68, s68, 2
	s_add_u32 s28, s28, 0x100
	s_addc_u32 s29, s29, 0
	s_add_u32 s66, s66, 0x100
	s_addc_u32 s67, s67, 0
	s_cmp_gt_u32 s68, 13
	s_cbranch_scc1 .Lpeel_done_p6
	.p2align	6
.LBB0_877:
	ds_read_b128 v[148:151], v156
	ds_read_b128 v[164:167], v156 offset:1024
	ds_read_b128 v[168:171], v156 offset:2048
	ds_read_b128 v[172:175], v156 offset:3072
	ds_read_b128 v[176:179], v157
	ds_read_b128 v[180:183], v157 offset:1024
	ds_read_b128 v[184:187], v157 offset:2048
	ds_read_b128 v[188:191], v157 offset:3072
	s_add_u32 s30, s28, 0xfffc0080
	s_addc_u32 s31, s29, -1
	s_cmp_eq_u32 s68, 12
	s_cselect_b32 s35, s23, s31
	s_cselect_b32 s34, s64, s30
	s_cselect_b32 s31, s21, s67
	s_cselect_b32 s30, s65, s66
	v_lshl_add_u64 v[224:225], s[28:29], 0, v[140:141]
	s_add_i32 m0, s37, 0xc000
	ds_read_b128 v[192:195], v158
	ds_read_b128 v[196:199], v158 offset:1024
	ds_read_b128 v[200:203], v158 offset:2048
	ds_read_b128 v[204:207], v158 offset:3072
	ds_read_b128 v[208:211], v158 offset:4096
	ds_read_b128 v[212:215], v158 offset:5120
	ds_read_b128 v[216:219], v158 offset:6144
	ds_read_b128 v[220:223], v158 offset:7168
	global_load_lds_dwordx4 v[224:225], off
	v_lshl_add_u64 v[224:225], s[28:29], 0, v[142:143]
	s_add_i32 m0, s37, 0xe000
	s_nop 0
	global_load_lds_dwordx4 v[224:225], off
	s_waitcnt vmcnt(8)
	s_waitcnt lgkmcnt(0)
	s_barrier
; #define PG8_STAGE(bufoff, gbase, voff) do { _Pragma("unroll") for (int _i = 0; _i < 2; ++_i) \
;         __builtin_amdgcn_global_load_lds((const unsigned*)((const char*)(gbase) + (voff)[_i]), (PG8_LAS unsigned*)(lds + (bufoff) + ldsw + _i * 8192), 16, 0, 0); } while (0)
; #define PG8_LDA(dst, b, h) do { _Pragma("unroll") for (int m = 0; m < 4; ++m) _Pragma("unroll") for (int k = 0; k < 2; ++k) dst[m][k] = *(const PG8_LAS bf16x8*)(lds + PG8_SA(b, h) + aoff + m * 2048 + k * 1024); } while (0)
; #define PG8_MMA(ai, bj, At, Bt) do { __builtin_amdgcn_s_setprio(1); _Pragma("unroll") for (int m = 0; m < 4; ++m) _Pragma("unroll") for (int n = 0; n < 2; ++n) _Pragma("unroll") for (int k = 0; k < 2; ++k) \
;         acc[ai][bj][m][n] = __builtin_amdgcn_mfma_f32_16x16x32_bf16(Bt[n][k], At[m][k], acc[ai][bj][m][n], 0, 0, 0); __builtin_amdgcn_s_setprio(0); } while (0)
; #define PG8_WAIT_V(n) asm volatile("s_waitcnt vmcnt(" #n ")" ::: "memory")
; #define PG8_WAIT_L(n) asm volatile("s_waitcnt lgkmcnt(" #n ")" ::: "memory")
; #define PG8_BAR __builtin_amdgcn_s_barrier()
; #define PG8_SCHED __builtin_amdgcn_sched_barrier(0)
; template <class Epi, class Sched, bool ALIGN_EPI = false, bool SP2 = false, bool AGM = false  >
; __device__ __forceinline__ void gemm_phase(PG8_LAS unsigned char* lds, const Gemm g, const Sched& S, const Epi& E) {
;     ...
;             PG8_WAIT_V(8); PG8_WAIT_L(0); PG8_BAR; PG8_MMA(0, 0, At, B0); PG8_MMA(0, 1, At, B1); PG8_BAR; PG8_SCHED;
;             PG8_LDA(At, 0, 1); PG8_STAGE(PG8_SB(0, 0), b2, voffB); PG8_STAGE(PG8_SB(0, 1), b2 + hstep, voffB); PG8_STAGE(PG8_SA(0, 0), a2, voffA);
;             PG8_WAIT_V(8); PG8_WAIT_L(0); PG8_BAR; PG8_MMA(1, 0, At, B0); PG8_MMA(1, 1, At, B1); PG8_BAR; PG8_SCHED;
	s_setprio 1
	s_waitcnt lgkmcnt(0)
	v_mfma_f32_16x16x32_bf16 v[126:129], v[148:151], v[192:195], v[126:129]
	v_mfma_f32_16x16x32_bf16 v[122:125], v[168:171], v[192:195], v[122:125]
	v_mfma_f32_16x16x32_bf16 v[110:113], v[148:151], v[200:203], v[110:113]
	v_mfma_f32_16x16x32_bf16 v[106:109], v[168:171], v[200:203], v[106:109]
	v_mfma_f32_16x16x32_bf16 v[94:97], v[148:151], v[208:211], v[94:97]
	v_mfma_f32_16x16x32_bf16 v[90:93], v[168:171], v[208:211], v[90:93]
	v_mfma_f32_16x16x32_bf16 v[78:81], v[148:151], v[216:219], v[78:81]
	v_mfma_f32_16x16x32_bf16 v[74:77], v[168:171], v[216:219], v[74:77]
	v_mfma_f32_16x16x32_bf16 v[126:129], v[164:167], v[196:199], v[126:129]
	v_mfma_f32_16x16x32_bf16 v[122:125], v[172:175], v[196:199], v[122:125]
	v_mfma_f32_16x16x32_bf16 v[110:113], v[164:167], v[204:207], v[110:113]
	v_mfma_f32_16x16x32_bf16 v[106:109], v[172:175], v[204:207], v[106:109]
	v_mfma_f32_16x16x32_bf16 v[94:97], v[164:167], v[212:215], v[94:97]
	v_mfma_f32_16x16x32_bf16 v[90:93], v[172:175], v[212:215], v[90:93]
	v_mfma_f32_16x16x32_bf16 v[78:81], v[164:167], v[220:223], v[78:81]
	v_mfma_f32_16x16x32_bf16 v[74:77], v[172:175], v[220:223], v[74:77]
	v_mfma_f32_16x16x32_bf16 v[118:121], v[176:179], v[192:195], v[118:121]
	v_mfma_f32_16x16x32_bf16 v[114:117], v[184:187], v[192:195], v[114:117]
	v_mfma_f32_16x16x32_bf16 v[102:105], v[176:179], v[200:203], v[102:105]
	v_mfma_f32_16x16x32_bf16 v[98:101], v[184:187], v[200:203], v[98:101]
	v_mfma_f32_16x16x32_bf16 v[86:89], v[176:179], v[208:211], v[86:89]
	v_mfma_f32_16x16x32_bf16 v[82:85], v[184:187], v[208:211], v[82:85]
	v_mfma_f32_16x16x32_bf16 v[70:73], v[176:179], v[216:219], v[70:73]
	v_mfma_f32_16x16x32_bf16 v[66:69], v[184:187], v[216:219], v[66:69]
	v_mfma_f32_16x16x32_bf16 v[118:121], v[180:183], v[196:199], v[118:121]
	v_mfma_f32_16x16x32_bf16 v[114:117], v[188:191], v[196:199], v[114:117]
	v_mfma_f32_16x16x32_bf16 v[102:105], v[180:183], v[204:207], v[102:105]
	v_mfma_f32_16x16x32_bf16 v[98:101], v[188:191], v[204:207], v[98:101]
	v_mfma_f32_16x16x32_bf16 v[86:89], v[180:183], v[212:215], v[86:89]
	v_mfma_f32_16x16x32_bf16 v[82:85], v[188:191], v[212:215], v[82:85]
	v_mfma_f32_16x16x32_bf16 v[70:73], v[180:183], v[220:223], v[70:73]
	v_mfma_f32_16x16x32_bf16 v[66:69], v[188:191], v[220:223], v[66:69]
	s_setprio 0
	s_barrier
	s_add_i32 s69, s53, s3
	v_lshl_add_u64 v[224:225], s[30:31], 0, v[134:135]
	s_mov_b32 m0, s69
	ds_read_b128 v[192:195], v158 offset:16384
	ds_read_b128 v[196:199], v158 offset:17408
	ds_read_b128 v[200:203], v158 offset:18432
	ds_read_b128 v[204:207], v158 offset:19456
	ds_read_b128 v[208:211], v158 offset:20480
	ds_read_b128 v[212:215], v158 offset:21504
	ds_read_b128 v[216:219], v158 offset:22528
	ds_read_b128 v[220:223], v158 offset:23552
	global_load_lds_dwordx4 v[224:225], off
	s_add_i32 m0, s69, 0x2000
	s_add_u32 s70, s30, 0x40000
	v_lshl_add_u64 v[226:227], s[30:31], 0, v[130:131]
	s_addc_u32 s71, s31, 0
	s_add_i32 s69, s54, s3
	global_load_lds_dwordx4 v[226:227], off
	v_lshl_add_u64 v[228:229], s[70:71], 0, v[134:135]
	s_mov_b32 m0, s69
	v_lshl_add_u64 v[230:231], s[34:35], 0, v[132:133]
	global_load_lds_dwordx4 v[228:229], off
	v_lshl_add_u64 v[228:229], s[70:71], 0, v[130:131]
	s_add_i32 m0, s69, 0x2000
	s_nop 0
	global_load_lds_dwordx4 v[228:229], off
	v_lshl_add_u64 v[228:229], s[34:35], 0, v[136:137]
	s_mov_b32 m0, s37
	s_nop 0
	global_load_lds_dwordx4 v[228:229], off
	s_mov_b32 m0, s38
	s_nop 0
	global_load_lds_dwordx4 v[230:231], off
	s_waitcnt vmcnt(8)
	s_waitcnt lgkmcnt(0)
	s_barrier
	s_setprio 1
	s_waitcnt lgkmcnt(0)
	v_mfma_f32_16x16x32_bf16 v[62:65], v[148:151], v[192:195], v[62:65]
	v_mfma_f32_16x16x32_bf16 v[58:61], v[168:171], v[192:195], v[58:61]
	v_mfma_f32_16x16x32_bf16 v[46:49], v[148:151], v[200:203], v[46:49]
	v_mfma_f32_16x16x32_bf16 v[42:45], v[168:171], v[200:203], v[42:45]
	v_mfma_f32_16x16x32_bf16 v[30:33], v[148:151], v[208:211], v[30:33]
	v_mfma_f32_16x16x32_bf16 v[26:29], v[168:171], v[208:211], v[26:29]
	v_mfma_f32_16x16x32_bf16 v[14:17], v[148:151], v[216:219], v[14:17]
	v_mfma_f32_16x16x32_bf16 v[10:13], v[168:171], v[216:219], v[10:13]
	v_mfma_f32_16x16x32_bf16 v[62:65], v[164:167], v[196:199], v[62:65]
	v_mfma_f32_16x16x32_bf16 v[58:61], v[172:175], v[196:199], v[58:61]
	v_mfma_f32_16x16x32_bf16 v[46:49], v[164:167], v[204:207], v[46:49]
	v_mfma_f32_16x16x32_bf16 v[42:45], v[172:175], v[204:207], v[42:45]
	v_mfma_f32_16x16x32_bf16 v[30:33], v[164:167], v[212:215], v[30:33]
	v_mfma_f32_16x16x32_bf16 v[26:29], v[172:175], v[212:215], v[26:29]
	v_mfma_f32_16x16x32_bf16 v[14:17], v[164:167], v[220:223], v[14:17]
	v_mfma_f32_16x16x32_bf16 v[10:13], v[172:175], v[220:223], v[10:13]
	v_mfma_f32_16x16x32_bf16 v[54:57], v[176:179], v[192:195], v[54:57]
	v_mfma_f32_16x16x32_bf16 v[50:53], v[184:187], v[192:195], v[50:53]
	v_mfma_f32_16x16x32_bf16 v[38:41], v[176:179], v[200:203], v[38:41]
	v_mfma_f32_16x16x32_bf16 v[34:37], v[184:187], v[200:203], v[34:37]
	v_mfma_f32_16x16x32_bf16 v[22:25], v[176:179], v[208:211], v[22:25]
	v_mfma_f32_16x16x32_bf16 v[18:21], v[184:187], v[208:211], v[18:21]
	v_mfma_f32_16x16x32_bf16 v[6:9], v[176:179], v[216:219], v[6:9]
	v_mfma_f32_16x16x32_bf16 v[2:5], v[184:187], v[216:219], v[2:5]
	v_mfma_f32_16x16x32_bf16 v[54:57], v[180:183], v[196:199], v[54:57]
	v_mfma_f32_16x16x32_bf16 v[50:53], v[188:191], v[196:199], v[50:53]
	v_mfma_f32_16x16x32_bf16 v[38:41], v[180:183], v[204:207], v[38:41]
	v_mfma_f32_16x16x32_bf16 v[34:37], v[188:191], v[204:207], v[34:37]
	v_mfma_f32_16x16x32_bf16 v[22:25], v[180:183], v[212:215], v[22:25]
	v_mfma_f32_16x16x32_bf16 v[18:21], v[188:191], v[212:215], v[18:21]
	v_mfma_f32_16x16x32_bf16 v[6:9], v[180:183], v[220:223], v[6:9]
	v_mfma_f32_16x16x32_bf16 v[2:5], v[188:191], v[220:223], v[2:5]
	s_setprio 0
	s_barrier
; #define PG8_STAGE(bufoff, gbase, voff) do { _Pragma("unroll") for (int _i = 0; _i < 2; ++_i) \
;         __builtin_amdgcn_global_load_lds((const unsigned*)((const char*)(gbase) + (voff)[_i]), (PG8_LAS unsigned*)(lds + (bufoff) + ldsw + _i * 8192), 16, 0, 0); } while (0)
; #define PG8_LDA(dst, b, h) do { _Pragma("unroll") for (int m = 0; m < 4; ++m) _Pragma("unroll") for (int k = 0; k < 2; ++k) dst[m][k] = *(const PG8_LAS bf16x8*)(lds + PG8_SA(b, h) + aoff + m * 2048 + k * 1024); } while (0)
; #define PG8_LDB(dst, b, h) do { _Pragma("unroll") for (int n = 0; n < 2; ++n) _Pragma("unroll") for (int k = 0; k < 2; ++k) dst[n][k] = *(const PG8_LAS bf16x8*)(lds + PG8_SB(b, h) + boff + n * 2048 + k * 1024); } while (0)
; #define PG8_MMA(ai, bj, At, Bt) do { __builtin_amdgcn_s_setprio(1); _Pragma("unroll") for (int m = 0; m < 4; ++m) _Pragma("unroll") for (int n = 0; n < 2; ++n) _Pragma("unroll") for (int k = 0; k < 2; ++k) \
;         acc[ai][bj][m][n] = __builtin_amdgcn_mfma_f32_16x16x32_bf16(Bt[n][k], At[m][k], acc[ai][bj][m][n], 0, 0, 0); __builtin_amdgcn_s_setprio(0); } while (0)
; #define PG8_WAIT_V(n) asm volatile("s_waitcnt vmcnt(" #n ")" ::: "memory")
; #define PG8_WAIT_L(n) asm volatile("s_waitcnt lgkmcnt(" #n ")" ::: "memory")
; #define PG8_BAR __builtin_amdgcn_s_barrier()
; #define PG8_SCHED __builtin_amdgcn_sched_barrier(0)
; template <class Epi, class Sched, bool ALIGN_EPI = false, bool SP2 = false, bool AGM = false  >
; __device__ __forceinline__ void gemm_phase(PG8_LAS unsigned char* lds, const Gemm g, const Sched& S, const Epi& E) {
;     ...
;             PG8_LDB(B0, 1, 0); PG8_LDB(B1, 1, 1); PG8_SCHED; PG8_LDA(At, 1, 0); PG8_STAGE(PG8_SA(0, 1), a2 + hstepA, voffA);
;             PG8_WAIT_V(8); PG8_WAIT_L(0); PG8_BAR; PG8_MMA(0, 0, At, B0); PG8_MMA(0, 1, At, B1); PG8_BAR; PG8_SCHED;
	s_add_i32 s69, 0, 0x18000
	s_add_i32 s70, 0, 0x1c000
	v_add_u32_e32 v172, s69, v155
	v_add_u32_e32 v188, s70, v155
	ds_read_b128 v[148:151], v172
	ds_read_b128 v[164:167], v172 offset:1024
	ds_read_b128 v[168:171], v172 offset:2048
	ds_read_b128 v[172:175], v172 offset:3072
	ds_read_b128 v[176:179], v188
	ds_read_b128 v[180:183], v188 offset:1024
	ds_read_b128 v[184:187], v188 offset:2048
	ds_read_b128 v[188:191], v188 offset:3072
	s_add_u32 s34, s34, 0x40000
	s_addc_u32 s35, s35, 0
	s_mov_b32 m0, s39
	v_lshl_add_u64 v[232:233], s[34:35], 0, v[136:137]
	ds_read_b128 v[192:195], v158 offset:32768
	ds_read_b128 v[196:199], v158 offset:33792
	ds_read_b128 v[200:203], v158 offset:34816
	ds_read_b128 v[204:207], v158 offset:35840
	ds_read_b128 v[208:211], v158 offset:36864
	ds_read_b128 v[212:215], v158 offset:37888
	ds_read_b128 v[216:219], v158 offset:38912
	ds_read_b128 v[220:223], v158 offset:39936
	global_load_lds_dwordx4 v[232:233], off
	v_lshl_add_u64 v[232:233], s[34:35], 0, v[132:133]
	s_mov_b32 m0, s40
	s_nop 0
	global_load_lds_dwordx4 v[232:233], off
	s_waitcnt vmcnt(8)
	s_waitcnt lgkmcnt(0)
	s_barrier
	s_setprio 1
	s_waitcnt lgkmcnt(0)
	v_mfma_f32_16x16x32_bf16 v[126:129], v[148:151], v[192:195], v[126:129]
	v_mfma_f32_16x16x32_bf16 v[122:125], v[168:171], v[192:195], v[122:125]
	v_mfma_f32_16x16x32_bf16 v[110:113], v[148:151], v[200:203], v[110:113]
	v_mfma_f32_16x16x32_bf16 v[106:109], v[168:171], v[200:203], v[106:109]
	v_mfma_f32_16x16x32_bf16 v[94:97], v[148:151], v[208:211], v[94:97]
	v_mfma_f32_16x16x32_bf16 v[90:93], v[168:171], v[208:211], v[90:93]
	v_mfma_f32_16x16x32_bf16 v[78:81], v[148:151], v[216:219], v[78:81]
	v_mfma_f32_16x16x32_bf16 v[74:77], v[168:171], v[216:219], v[74:77]
	v_mfma_f32_16x16x32_bf16 v[126:129], v[164:167], v[196:199], v[126:129]
	v_mfma_f32_16x16x32_bf16 v[122:125], v[172:175], v[196:199], v[122:125]
	v_mfma_f32_16x16x32_bf16 v[110:113], v[164:167], v[204:207], v[110:113]
	v_mfma_f32_16x16x32_bf16 v[106:109], v[172:175], v[204:207], v[106:109]
	v_mfma_f32_16x16x32_bf16 v[94:97], v[164:167], v[212:215], v[94:97]
	v_mfma_f32_16x16x32_bf16 v[90:93], v[172:175], v[212:215], v[90:93]
	v_mfma_f32_16x16x32_bf16 v[78:81], v[164:167], v[220:223], v[78:81]
	v_mfma_f32_16x16x32_bf16 v[74:77], v[172:175], v[220:223], v[74:77]
	v_mfma_f32_16x16x32_bf16 v[118:121], v[176:179], v[192:195], v[118:121]
	v_mfma_f32_16x16x32_bf16 v[114:117], v[184:187], v[192:195], v[114:117]
	v_mfma_f32_16x16x32_bf16 v[102:105], v[176:179], v[200:203], v[102:105]
	v_mfma_f32_16x16x32_bf16 v[98:101], v[184:187], v[200:203], v[98:101]
	v_mfma_f32_16x16x32_bf16 v[86:89], v[176:179], v[208:211], v[86:89]
	v_mfma_f32_16x16x32_bf16 v[82:85], v[184:187], v[208:211], v[82:85]
	v_mfma_f32_16x16x32_bf16 v[70:73], v[176:179], v[216:219], v[70:73]
	v_mfma_f32_16x16x32_bf16 v[66:69], v[184:187], v[216:219], v[66:69]
	v_mfma_f32_16x16x32_bf16 v[118:121], v[180:183], v[196:199], v[118:121]
	v_mfma_f32_16x16x32_bf16 v[114:117], v[188:191], v[196:199], v[114:117]
	v_mfma_f32_16x16x32_bf16 v[102:105], v[180:183], v[204:207], v[102:105]
	v_mfma_f32_16x16x32_bf16 v[98:101], v[188:191], v[204:207], v[98:101]
	v_mfma_f32_16x16x32_bf16 v[86:89], v[180:183], v[212:215], v[86:89]
	v_mfma_f32_16x16x32_bf16 v[82:85], v[188:191], v[212:215], v[82:85]
	v_mfma_f32_16x16x32_bf16 v[70:73], v[180:183], v[220:223], v[70:73]
	v_mfma_f32_16x16x32_bf16 v[66:69], v[188:191], v[220:223], v[66:69]
	s_setprio 0
	s_barrier
; #define PG8_STAGE(bufoff, gbase, voff) do { _Pragma("unroll") for (int _i = 0; _i < 2; ++_i) \
;         __builtin_amdgcn_global_load_lds((const unsigned*)((const char*)(gbase) + (voff)[_i]), (PG8_LAS unsigned*)(lds + (bufoff) + ldsw + _i * 8192), 16, 0, 0); } while (0)
; #define PG8_LDA(dst, b, h) do { _Pragma("unroll") for (int m = 0; m < 4; ++m) _Pragma("unroll") for (int k = 0; k < 2; ++k) dst[m][k] = *(const PG8_LAS bf16x8*)(lds + PG8_SA(b, h) + aoff + m * 2048 + k * 1024); } while (0)
; #define PG8_MMA(ai, bj, At, Bt) do { __builtin_amdgcn_s_setprio(1); _Pragma("unroll") for (int m = 0; m < 4; ++m) _Pragma("unroll") for (int n = 0; n < 2; ++n) _Pragma("unroll") for (int k = 0; k < 2; ++k) \
;         acc[ai][bj][m][n] = __builtin_amdgcn_mfma_f32_16x16x32_bf16(Bt[n][k], At[m][k], acc[ai][bj][m][n], 0, 0, 0); __builtin_amdgcn_s_setprio(0); } while (0)
; #define PG8_WAIT_V(n) asm volatile("s_waitcnt vmcnt(" #n ")" ::: "memory")
; #define PG8_WAIT_L(n) asm volatile("s_waitcnt lgkmcnt(" #n ")" ::: "memory")
; #define PG8_BAR __builtin_amdgcn_s_barrier()
; #define PG8_SCHED __builtin_amdgcn_sched_barrier(0)
; template <class Epi, class Sched, bool ALIGN_EPI = false, bool SP2 = false, bool AGM = false  >
; __device__ __forceinline__ void gemm_phase(PG8_LAS unsigned char* lds, const Gemm g, const Sched& S, const Epi& E) {
;     ...
;         for (int t = 0; t < nt; t += 2) {
;     ...
;             PG8_LDA(At, 1, 1); PG8_STAGE(PG8_SB(1, 0), b3, voffB); PG8_STAGE(PG8_SB(1, 1), b3 + hstep, voffB); PG8_STAGE(PG8_SA(1, 0), a3, voffA);
;             PG8_WAIT_V(8); PG8_WAIT_L(0); PG8_BAR; PG8_MMA(1, 0, At, B0); PG8_MMA(1, 1, At, B1); PG8_BAR; PG8_SCHED;
	s_add_i32 s34, s69, s3
	v_lshl_add_u64 v[224:225], v[224:225], 0, s[16:17]
	s_mov_b32 m0, s34
	ds_read_b128 v[192:195], v158 offset:49152
	ds_read_b128 v[196:199], v158 offset:50176
	ds_read_b128 v[200:203], v158 offset:51200
	ds_read_b128 v[204:207], v158 offset:52224
	ds_read_b128 v[208:211], v158 offset:53248
	ds_read_b128 v[212:215], v158 offset:54272
	ds_read_b128 v[216:219], v158 offset:55296
	ds_read_b128 v[220:223], v158 offset:56320
	global_load_lds_dwordx4 v[224:225], off
	s_add_i32 m0, s34, 0x2000
	s_add_u32 s30, s30, 0x40080
	v_lshl_add_u64 v[224:225], v[226:227], 0, s[16:17]
	s_addc_u32 s31, s31, 0
	s_add_i32 s34, s70, s3
	global_load_lds_dwordx4 v[224:225], off
	v_lshl_add_u64 v[224:225], s[30:31], 0, v[134:135]
	s_mov_b32 m0, s34
	s_nop 0
	global_load_lds_dwordx4 v[224:225], off
	v_lshl_add_u64 v[224:225], s[30:31], 0, v[130:131]
	s_add_i32 m0, s34, 0x2000
	s_nop 0
	global_load_lds_dwordx4 v[224:225], off
	v_lshl_add_u64 v[224:225], v[228:229], 0, s[16:17]
	s_mov_b32 m0, s43
	s_nop 0
	global_load_lds_dwordx4 v[224:225], off
	v_lshl_add_u64 v[224:225], v[230:231], 0, s[16:17]
	s_mov_b32 m0, s44
	s_nop 0
	global_load_lds_dwordx4 v[224:225], off
	s_waitcnt vmcnt(8)
	s_waitcnt lgkmcnt(0)
	s_barrier
	s_setprio 1
	s_waitcnt lgkmcnt(0)
	v_mfma_f32_16x16x32_bf16 v[62:65], v[148:151], v[192:195], v[62:65]
	v_mfma_f32_16x16x32_bf16 v[58:61], v[168:171], v[192:195], v[58:61]
	v_mfma_f32_16x16x32_bf16 v[46:49], v[148:151], v[200:203], v[46:49]
	v_mfma_f32_16x16x32_bf16 v[42:45], v[168:171], v[200:203], v[42:45]
	v_mfma_f32_16x16x32_bf16 v[30:33], v[148:151], v[208:211], v[30:33]
	v_mfma_f32_16x16x32_bf16 v[26:29], v[168:171], v[208:211], v[26:29]
	v_mfma_f32_16x16x32_bf16 v[14:17], v[148:151], v[216:219], v[14:17]
	v_mfma_f32_16x16x32_bf16 v[10:13], v[168:171], v[216:219], v[10:13]
	v_mfma_f32_16x16x32_bf16 v[62:65], v[164:167], v[196:199], v[62:65]
	v_mfma_f32_16x16x32_bf16 v[58:61], v[172:175], v[196:199], v[58:61]
	v_mfma_f32_16x16x32_bf16 v[46:49], v[164:167], v[204:207], v[46:49]
	v_mfma_f32_16x16x32_bf16 v[42:45], v[172:175], v[204:207], v[42:45]
	v_mfma_f32_16x16x32_bf16 v[30:33], v[164:167], v[212:215], v[30:33]
	v_mfma_f32_16x16x32_bf16 v[26:29], v[172:175], v[212:215], v[26:29]
	v_mfma_f32_16x16x32_bf16 v[14:17], v[164:167], v[220:223], v[14:17]
	v_mfma_f32_16x16x32_bf16 v[10:13], v[172:175], v[220:223], v[10:13]
	v_mfma_f32_16x16x32_bf16 v[54:57], v[176:179], v[192:195], v[54:57]
	v_mfma_f32_16x16x32_bf16 v[50:53], v[184:187], v[192:195], v[50:53]
	v_mfma_f32_16x16x32_bf16 v[38:41], v[176:179], v[200:203], v[38:41]
	v_mfma_f32_16x16x32_bf16 v[34:37], v[184:187], v[200:203], v[34:37]
	v_mfma_f32_16x16x32_bf16 v[22:25], v[176:179], v[208:211], v[22:25]
	v_mfma_f32_16x16x32_bf16 v[18:21], v[184:187], v[208:211], v[18:21]
	v_mfma_f32_16x16x32_bf16 v[6:9], v[176:179], v[216:219], v[6:9]
	v_mfma_f32_16x16x32_bf16 v[2:5], v[184:187], v[216:219], v[2:5]
	v_mfma_f32_16x16x32_bf16 v[54:57], v[180:183], v[196:199], v[54:57]
	v_mfma_f32_16x16x32_bf16 v[50:53], v[188:191], v[196:199], v[50:53]
	v_mfma_f32_16x16x32_bf16 v[38:41], v[180:183], v[204:207], v[38:41]
	v_mfma_f32_16x16x32_bf16 v[34:37], v[188:191], v[204:207], v[34:37]
	v_mfma_f32_16x16x32_bf16 v[22:25], v[180:183], v[212:215], v[22:25]
	v_mfma_f32_16x16x32_bf16 v[18:21], v[188:191], v[212:215], v[18:21]
	v_mfma_f32_16x16x32_bf16 v[6:9], v[180:183], v[220:223], v[6:9]
	v_mfma_f32_16x16x32_bf16 v[2:5], v[188:191], v[220:223], v[2:5]
	s_setprio 0
	s_barrier
	s_add_i32 s68, s68, 2
	s_add_u32 s28, s28, 0x100
	s_addc_u32 s29, s29, 0
	s_add_u32 s66, s66, 0x100
	s_addc_u32 s67, s67, 0
	s_cmp_gt_u32 s68, 13
	s_cbranch_scc0 .LBB0_877

; #define PG8_STAGE(bufoff, gbase, voff) do { _Pragma("unroll") for (int _i = 0; _i < 2; ++_i) \
;         __builtin_amdgcn_global_load_lds((const unsigned*)((const char*)(gbase) + (voff)[_i]), (PG8_LAS unsigned*)(lds + (bufoff) + ldsw + _i * 8192), 16, 0, 0); } while (0)
; #define PG8_LDA(dst, b, h) do { _Pragma("unroll") for (int m = 0; m < 4; ++m) _Pragma("unroll") for (int k = 0; k < 2; ++k) dst[m][k] = *(const PG8_LAS bf16x8*)(lds + PG8_SA(b, h) + aoff + m * 2048 + k * 1024); } while (0)
; #define PG8_LDB(dst, b, h) do { _Pragma("unroll") for (int n = 0; n < 2; ++n) _Pragma("unroll") for (int k = 0; k < 2; ++k) dst[n][k] = *(const PG8_LAS bf16x8*)(lds + PG8_SB(b, h) + boff + n * 2048 + k * 1024); } while (0)
; #define PG8_MMA(ai, bj, At, Bt) do { __builtin_amdgcn_s_setprio(1); _Pragma("unroll") for (int m = 0; m < 4; ++m) _Pragma("unroll") for (int n = 0; n < 2; ++n) _Pragma("unroll") for (int k = 0; k < 2; ++k) \
;         acc[ai][bj][m][n] = __builtin_amdgcn_mfma_f32_16x16x32_bf16(Bt[n][k], At[m][k], acc[ai][bj][m][n], 0, 0, 0); __builtin_amdgcn_s_setprio(0); } while (0)
; #define PG8_WAIT_V(n) asm volatile("s_waitcnt vmcnt(" #n ")" ::: "memory")
; #define PG8_WAIT_L(n) asm volatile("s_waitcnt lgkmcnt(" #n ")" ::: "memory")
; template <class Epi, class Sched, bool ALIGN_EPI = false, bool SP2 = false, bool AGM = false  >
; __device__ __forceinline__ void gemm_phase(PG8_LAS unsigned char* lds, const Gemm g, const Sched& S, const Epi& E) {
;     ...
;             const bool last = (t == nt - 2);
;             const char* a1 = cA + (size_t)(t + 1) * kstepA;
;             const char* a2 = last ? nA : cA + (size_t)(t + 2) * kstepA; const char* b2 = last ? nB : cB + (size_t)(t + 2) * kstep;
;             const char* a3 = a2 + kstepA; const char* b3 = b2 + kstep;
;             if (last && has_next) S.a_ready(nxt);
;             if constexpr (SP2) {
;             PG8_LDB(B0, 0, 0); PG8_LDB(B1, 0, 1); PG8_SCHED; PG8_LDA(At, 0, 0); PG8_STAGE(PG8_SA(1, 1), a1 + hstepA, voffA);
;             PG8_WAIT_V(8); PG8_WAIT_L(0); PG8_BAR; PG8_MMA(0, 0, At, B0); PG8_MMA(0, 1, At, B1); PG8_BAR; PG8_SCHED;
;             PG8_LDA(At, 0, 1); PG8_STAGE(PG8_SB(0, 0), b2, voffB); PG8_STAGE(PG8_SB(0, 1), b2 + hstep, voffB); PG8_STAGE(PG8_SA(0, 0), a2, voffA);
;             PG8_WAIT_V(8); PG8_WAIT_L(0); PG8_BAR; PG8_MMA(1, 0, At, B0); PG8_MMA(1, 1, At, B1); PG8_BAR; PG8_SCHED;
.LBB0_1068:
	ds_read_b128 v[150:153], v167
	ds_read_b128 v[156:159], v167 offset:1024
	ds_read_b128 v[160:163], v167 offset:2048
	ds_read_b128 v[176:179], v167 offset:3072
	ds_read_b128 v[180:183], v168
	ds_read_b128 v[184:187], v168 offset:1024
	ds_read_b128 v[188:191], v168 offset:2048
	ds_read_b128 v[192:195], v168 offset:3072
	s_add_u32 s34, s30, 0xfff50080
	s_addc_u32 s35, s31, -1
	s_cmp_eq_u32 s65, 40
	s_cselect_b32 s37, s13, s35
	s_cselect_b32 s36, s12, s34
	s_cselect_b32 s35, s29, s33
	s_cselect_b32 s34, s28, s5
	v_lshl_add_u64 v[164:165], s[30:31], 0, v[142:143]
	s_add_i32 m0, s39, 0xc000
	ds_read_b128 v[196:199], v169
	ds_read_b128 v[200:203], v169 offset:1024
	ds_read_b128 v[204:207], v169 offset:2048
	ds_read_b128 v[208:211], v169 offset:3072
	ds_read_b128 v[212:215], v169 offset:4096
	ds_read_b128 v[216:219], v169 offset:5120
	ds_read_b128 v[220:223], v169 offset:6144
	ds_read_b128 v[224:227], v169 offset:7168
	global_load_lds_dwordx4 v[164:165], off
	v_lshl_add_u64 v[164:165], s[30:31], 0, v[144:145]
	s_add_i32 m0, s39, 0xe000
	s_nop 0
	global_load_lds_dwordx4 v[164:165], off
	s_waitcnt vmcnt(8)
	s_waitcnt lgkmcnt(0)
	s_barrier
	s_setprio 1
	s_waitcnt lgkmcnt(0)
	v_mfma_f32_16x16x32_bf16 v[126:129], v[150:153], v[196:199], v[126:129]
	v_mfma_f32_16x16x32_bf16 v[122:125], v[160:163], v[196:199], v[122:125]
	v_mfma_f32_16x16x32_bf16 v[110:113], v[150:153], v[204:207], v[110:113]
	v_mfma_f32_16x16x32_bf16 v[106:109], v[160:163], v[204:207], v[106:109]
	v_mfma_f32_16x16x32_bf16 v[94:97], v[150:153], v[212:215], v[94:97]
	v_mfma_f32_16x16x32_bf16 v[90:93], v[160:163], v[212:215], v[90:93]
	v_mfma_f32_16x16x32_bf16 v[78:81], v[150:153], v[220:223], v[78:81]
	v_mfma_f32_16x16x32_bf16 v[74:77], v[160:163], v[220:223], v[74:77]
	v_mfma_f32_16x16x32_bf16 v[126:129], v[156:159], v[200:203], v[126:129]
	v_mfma_f32_16x16x32_bf16 v[122:125], v[176:179], v[200:203], v[122:125]
	v_mfma_f32_16x16x32_bf16 v[110:113], v[156:159], v[208:211], v[110:113]
	v_mfma_f32_16x16x32_bf16 v[106:109], v[176:179], v[208:211], v[106:109]
	v_mfma_f32_16x16x32_bf16 v[94:97], v[156:159], v[216:219], v[94:97]
	v_mfma_f32_16x16x32_bf16 v[90:93], v[176:179], v[216:219], v[90:93]
	v_mfma_f32_16x16x32_bf16 v[78:81], v[156:159], v[224:227], v[78:81]
	v_mfma_f32_16x16x32_bf16 v[74:77], v[176:179], v[224:227], v[74:77]
	v_mfma_f32_16x16x32_bf16 v[118:121], v[180:183], v[196:199], v[118:121]
	v_mfma_f32_16x16x32_bf16 v[114:117], v[188:191], v[196:199], v[114:117]
	v_mfma_f32_16x16x32_bf16 v[102:105], v[180:183], v[204:207], v[102:105]
	v_mfma_f32_16x16x32_bf16 v[98:101], v[188:191], v[204:207], v[98:101]
	v_mfma_f32_16x16x32_bf16 v[86:89], v[180:183], v[212:215], v[86:89]
	v_mfma_f32_16x16x32_bf16 v[82:85], v[188:191], v[212:215], v[82:85]
	v_mfma_f32_16x16x32_bf16 v[70:73], v[180:183], v[220:223], v[70:73]
	v_mfma_f32_16x16x32_bf16 v[66:69], v[188:191], v[220:223], v[66:69]
	v_mfma_f32_16x16x32_bf16 v[118:121], v[184:187], v[200:203], v[118:121]
	v_mfma_f32_16x16x32_bf16 v[114:117], v[192:195], v[200:203], v[114:117]
	v_mfma_f32_16x16x32_bf16 v[102:105], v[184:187], v[208:211], v[102:105]
	v_mfma_f32_16x16x32_bf16 v[98:101], v[192:195], v[208:211], v[98:101]
	v_mfma_f32_16x16x32_bf16 v[86:89], v[184:187], v[216:219], v[86:89]
	v_mfma_f32_16x16x32_bf16 v[82:85], v[192:195], v[216:219], v[82:85]
	v_mfma_f32_16x16x32_bf16 v[70:73], v[184:187], v[224:227], v[70:73]
	v_mfma_f32_16x16x32_bf16 v[66:69], v[192:195], v[224:227], v[66:69]
	s_setprio 0
	s_barrier
	s_add_i32 s66, s60, s38
	v_lshl_add_u64 v[164:165], s[34:35], 0, v[132:133]
	s_mov_b32 m0, s66
	ds_read_b128 v[196:199], v169 offset:16384
	ds_read_b128 v[200:203], v169 offset:17408
	ds_read_b128 v[204:207], v169 offset:18432
	ds_read_b128 v[208:211], v169 offset:19456
	ds_read_b128 v[212:215], v169 offset:20480
	ds_read_b128 v[216:219], v169 offset:21504
	ds_read_b128 v[220:223], v169 offset:22528
	ds_read_b128 v[224:227], v169 offset:23552
	global_load_lds_dwordx4 v[164:165], off
	s_add_i32 m0, s66, 0x2000
	s_add_u32 s66, s34, 0xb0000
	v_lshl_add_u64 v[228:229], s[34:35], 0, v[136:137]
	s_addc_u32 s67, s35, 0
	s_add_i32 s68, s61, s38
	global_load_lds_dwordx4 v[228:229], off
	v_lshl_add_u64 v[230:231], s[66:67], 0, v[132:133]
	s_mov_b32 m0, s68
	v_lshl_add_u64 v[232:233], s[36:37], 0, v[134:135]
	global_load_lds_dwordx4 v[230:231], off
	v_lshl_add_u64 v[230:231], s[66:67], 0, v[136:137]
	s_add_i32 m0, s68, 0x2000
	s_nop 0
	global_load_lds_dwordx4 v[230:231], off
	v_lshl_add_u64 v[230:231], s[36:37], 0, v[130:131]
	s_mov_b32 m0, s39
	s_nop 0
	global_load_lds_dwordx4 v[230:231], off
	s_mov_b32 m0, s40
	s_nop 0
	global_load_lds_dwordx4 v[232:233], off
	s_waitcnt vmcnt(8)
	s_waitcnt lgkmcnt(0)
	s_barrier
; #define PG8_STAGE(bufoff, gbase, voff) do { _Pragma("unroll") for (int _i = 0; _i < 2; ++_i) \
;         __builtin_amdgcn_global_load_lds((const unsigned*)((const char*)(gbase) + (voff)[_i]), (PG8_LAS unsigned*)(lds + (bufoff) + ldsw + _i * 8192), 16, 0, 0); } while (0)
; #define PG8_LDA(dst, b, h) do { _Pragma("unroll") for (int m = 0; m < 4; ++m) _Pragma("unroll") for (int k = 0; k < 2; ++k) dst[m][k] = *(const PG8_LAS bf16x8*)(lds + PG8_SA(b, h) + aoff + m * 2048 + k * 1024); } while (0)
; #define PG8_LDB(dst, b, h) do { _Pragma("unroll") for (int n = 0; n < 2; ++n) _Pragma("unroll") for (int k = 0; k < 2; ++k) dst[n][k] = *(const PG8_LAS bf16x8*)(lds + PG8_SB(b, h) + boff + n * 2048 + k * 1024); } while (0)
; #define PG8_MMA(ai, bj, At, Bt) do { __builtin_amdgcn_s_setprio(1); _Pragma("unroll") for (int m = 0; m < 4; ++m) _Pragma("unroll") for (int n = 0; n < 2; ++n) _Pragma("unroll") for (int k = 0; k < 2; ++k) \
;         acc[ai][bj][m][n] = __builtin_amdgcn_mfma_f32_16x16x32_bf16(Bt[n][k], At[m][k], acc[ai][bj][m][n], 0, 0, 0); __builtin_amdgcn_s_setprio(0); } while (0)
; #define PG8_WAIT_V(n) asm volatile("s_waitcnt vmcnt(" #n ")" ::: "memory")
; #define PG8_WAIT_L(n) asm volatile("s_waitcnt lgkmcnt(" #n ")" ::: "memory")
; #define PG8_BAR __builtin_amdgcn_s_barrier()
; #define PG8_SCHED __builtin_amdgcn_sched_barrier(0)
; template <class Epi, class Sched, bool ALIGN_EPI = false, bool SP2 = false, bool AGM = false  >
; __device__ __forceinline__ void gemm_phase(PG8_LAS unsigned char* lds, const Gemm g, const Sched& S, const Epi& E) {
;     ...
;             PG8_WAIT_V(8); PG8_WAIT_L(0); PG8_BAR; PG8_MMA(1, 0, At, B0); PG8_MMA(1, 1, At, B1); PG8_BAR; PG8_SCHED;
;             PG8_LDB(B0, 1, 0); PG8_LDB(B1, 1, 1); PG8_SCHED; PG8_LDA(At, 1, 0); PG8_STAGE(PG8_SA(0, 1), a2 + hstepA, voffA);
;             PG8_WAIT_V(8); PG8_WAIT_L(0); PG8_BAR; PG8_MMA(0, 0, At, B0); PG8_MMA(0, 1, At, B1); PG8_BAR; PG8_SCHED;
	s_setprio 1
	s_waitcnt lgkmcnt(0)
	v_mfma_f32_16x16x32_bf16 v[62:65], v[150:153], v[196:199], v[62:65]
	v_mfma_f32_16x16x32_bf16 v[58:61], v[160:163], v[196:199], v[58:61]
	v_mfma_f32_16x16x32_bf16 v[46:49], v[150:153], v[204:207], v[46:49]
	v_mfma_f32_16x16x32_bf16 v[42:45], v[160:163], v[204:207], v[42:45]
	v_mfma_f32_16x16x32_bf16 v[30:33], v[150:153], v[212:215], v[30:33]
	v_mfma_f32_16x16x32_bf16 v[26:29], v[160:163], v[212:215], v[26:29]
	v_mfma_f32_16x16x32_bf16 v[14:17], v[150:153], v[220:223], v[14:17]
	v_mfma_f32_16x16x32_bf16 v[10:13], v[160:163], v[220:223], v[10:13]
	v_mfma_f32_16x16x32_bf16 v[62:65], v[156:159], v[200:203], v[62:65]
	v_mfma_f32_16x16x32_bf16 v[58:61], v[176:179], v[200:203], v[58:61]
	v_mfma_f32_16x16x32_bf16 v[46:49], v[156:159], v[208:211], v[46:49]
	v_mfma_f32_16x16x32_bf16 v[42:45], v[176:179], v[208:211], v[42:45]
	v_mfma_f32_16x16x32_bf16 v[30:33], v[156:159], v[216:219], v[30:33]
	v_mfma_f32_16x16x32_bf16 v[26:29], v[176:179], v[216:219], v[26:29]
	v_mfma_f32_16x16x32_bf16 v[14:17], v[156:159], v[224:227], v[14:17]
	v_mfma_f32_16x16x32_bf16 v[10:13], v[176:179], v[224:227], v[10:13]
	v_mfma_f32_16x16x32_bf16 v[54:57], v[180:183], v[196:199], v[54:57]
	v_mfma_f32_16x16x32_bf16 v[50:53], v[188:191], v[196:199], v[50:53]
	v_mfma_f32_16x16x32_bf16 v[38:41], v[180:183], v[204:207], v[38:41]
	v_mfma_f32_16x16x32_bf16 v[34:37], v[188:191], v[204:207], v[34:37]
	v_mfma_f32_16x16x32_bf16 v[22:25], v[180:183], v[212:215], v[22:25]
	v_mfma_f32_16x16x32_bf16 v[18:21], v[188:191], v[212:215], v[18:21]
	v_mfma_f32_16x16x32_bf16 v[6:9], v[180:183], v[220:223], v[6:9]
	v_mfma_f32_16x16x32_bf16 v[2:5], v[188:191], v[220:223], v[2:5]
	v_mfma_f32_16x16x32_bf16 v[54:57], v[184:187], v[200:203], v[54:57]
	v_mfma_f32_16x16x32_bf16 v[50:53], v[192:195], v[200:203], v[50:53]
	v_mfma_f32_16x16x32_bf16 v[38:41], v[184:187], v[208:211], v[38:41]
	v_mfma_f32_16x16x32_bf16 v[34:37], v[192:195], v[208:211], v[34:37]
	v_mfma_f32_16x16x32_bf16 v[22:25], v[184:187], v[216:219], v[22:25]
	v_mfma_f32_16x16x32_bf16 v[18:21], v[192:195], v[216:219], v[18:21]
	v_mfma_f32_16x16x32_bf16 v[6:9], v[184:187], v[224:227], v[6:9]
	v_mfma_f32_16x16x32_bf16 v[2:5], v[192:195], v[224:227], v[2:5]
	s_setprio 0
	s_barrier
	s_add_i32 s66, 0, 0x18000
	s_add_i32 s67, 0, 0x1c000
	v_add_u32_e32 v176, s66, v1
	v_add_u32_e32 v192, s67, v1
	ds_read_b128 v[150:153], v176
	ds_read_b128 v[156:159], v176 offset:1024
	ds_read_b128 v[160:163], v176 offset:2048
	ds_read_b128 v[176:179], v176 offset:3072
	ds_read_b128 v[180:183], v192
	ds_read_b128 v[184:187], v192 offset:1024
	ds_read_b128 v[188:191], v192 offset:2048
	ds_read_b128 v[192:195], v192 offset:3072
	s_add_u32 s36, s36, 0xb0000
	s_addc_u32 s37, s37, 0
	s_mov_b32 m0, s41
	v_lshl_add_u64 v[234:235], s[36:37], 0, v[130:131]
	ds_read_b128 v[196:199], v169 offset:32768
	ds_read_b128 v[200:203], v169 offset:33792
	ds_read_b128 v[204:207], v169 offset:34816
	ds_read_b128 v[208:211], v169 offset:35840
	ds_read_b128 v[212:215], v169 offset:36864
	ds_read_b128 v[216:219], v169 offset:37888
	ds_read_b128 v[220:223], v169 offset:38912
	ds_read_b128 v[224:227], v169 offset:39936
	global_load_lds_dwordx4 v[234:235], off
	v_lshl_add_u64 v[234:235], s[36:37], 0, v[134:135]
	s_mov_b32 m0, s42
	s_nop 0
	global_load_lds_dwordx4 v[234:235], off
	s_waitcnt vmcnt(8)
	s_waitcnt lgkmcnt(0)
	s_barrier
	s_setprio 1
	s_waitcnt lgkmcnt(0)
	v_mfma_f32_16x16x32_bf16 v[126:129], v[150:153], v[196:199], v[126:129]
	v_mfma_f32_16x16x32_bf16 v[122:125], v[160:163], v[196:199], v[122:125]
	v_mfma_f32_16x16x32_bf16 v[110:113], v[150:153], v[204:207], v[110:113]
	v_mfma_f32_16x16x32_bf16 v[106:109], v[160:163], v[204:207], v[106:109]
	v_mfma_f32_16x16x32_bf16 v[94:97], v[150:153], v[212:215], v[94:97]
	v_mfma_f32_16x16x32_bf16 v[90:93], v[160:163], v[212:215], v[90:93]
	v_mfma_f32_16x16x32_bf16 v[78:81], v[150:153], v[220:223], v[78:81]
	v_mfma_f32_16x16x32_bf16 v[74:77], v[160:163], v[220:223], v[74:77]
	v_mfma_f32_16x16x32_bf16 v[126:129], v[156:159], v[200:203], v[126:129]
	v_mfma_f32_16x16x32_bf16 v[122:125], v[176:179], v[200:203], v[122:125]
	v_mfma_f32_16x16x32_bf16 v[110:113], v[156:159], v[208:211], v[110:113]
	v_mfma_f32_16x16x32_bf16 v[106:109], v[176:179], v[208:211], v[106:109]
	v_mfma_f32_16x16x32_bf16 v[94:97], v[156:159], v[216:219], v[94:97]
	v_mfma_f32_16x16x32_bf16 v[90:93], v[176:179], v[216:219], v[90:93]
	v_mfma_f32_16x16x32_bf16 v[78:81], v[156:159], v[224:227], v[78:81]
	v_mfma_f32_16x16x32_bf16 v[74:77], v[176:179], v[224:227], v[74:77]
	v_mfma_f32_16x16x32_bf16 v[118:121], v[180:183], v[196:199], v[118:121]
	v_mfma_f32_16x16x32_bf16 v[114:117], v[188:191], v[196:199], v[114:117]
	v_mfma_f32_16x16x32_bf16 v[102:105], v[180:183], v[204:207], v[102:105]
	v_mfma_f32_16x16x32_bf16 v[98:101], v[188:191], v[204:207], v[98:101]
	v_mfma_f32_16x16x32_bf16 v[86:89], v[180:183], v[212:215], v[86:89]
	v_mfma_f32_16x16x32_bf16 v[82:85], v[188:191], v[212:215], v[82:85]
	v_mfma_f32_16x16x32_bf16 v[70:73], v[180:183], v[220:223], v[70:73]
	v_mfma_f32_16x16x32_bf16 v[66:69], v[188:191], v[220:223], v[66:69]
	v_mfma_f32_16x16x32_bf16 v[118:121], v[184:187], v[200:203], v[118:121]
	v_mfma_f32_16x16x32_bf16 v[114:117], v[192:195], v[200:203], v[114:117]
	v_mfma_f32_16x16x32_bf16 v[102:105], v[184:187], v[208:211], v[102:105]
	v_mfma_f32_16x16x32_bf16 v[98:101], v[192:195], v[208:211], v[98:101]
	v_mfma_f32_16x16x32_bf16 v[86:89], v[184:187], v[216:219], v[86:89]
	v_mfma_f32_16x16x32_bf16 v[82:85], v[192:195], v[216:219], v[82:85]
	v_mfma_f32_16x16x32_bf16 v[70:73], v[184:187], v[224:227], v[70:73]
	v_mfma_f32_16x16x32_bf16 v[66:69], v[192:195], v[224:227], v[66:69]
	s_setprio 0
	s_barrier
; #define PG8_STAGE(bufoff, gbase, voff) do { _Pragma("unroll") for (int _i = 0; _i < 2; ++_i) \
;         __builtin_amdgcn_global_load_lds((const unsigned*)((const char*)(gbase) + (voff)[_i]), (PG8_LAS unsigned*)(lds + (bufoff) + ldsw + _i * 8192), 16, 0, 0); } while (0)
; #define PG8_LDA(dst, b, h) do { _Pragma("unroll") for (int m = 0; m < 4; ++m) _Pragma("unroll") for (int k = 0; k < 2; ++k) dst[m][k] = *(const PG8_LAS bf16x8*)(lds + PG8_SA(b, h) + aoff + m * 2048 + k * 1024); } while (0)
; #define PG8_MMA(ai, bj, At, Bt) do { __builtin_amdgcn_s_setprio(1); _Pragma("unroll") for (int m = 0; m < 4; ++m) _Pragma("unroll") for (int n = 0; n < 2; ++n) _Pragma("unroll") for (int k = 0; k < 2; ++k) \
;         acc[ai][bj][m][n] = __builtin_amdgcn_mfma_f32_16x16x32_bf16(Bt[n][k], At[m][k], acc[ai][bj][m][n], 0, 0, 0); __builtin_amdgcn_s_setprio(0); } while (0)
; #define PG8_WAIT_V(n) asm volatile("s_waitcnt vmcnt(" #n ")" ::: "memory")
; #define PG8_WAIT_L(n) asm volatile("s_waitcnt lgkmcnt(" #n ")" ::: "memory")
; #define PG8_BAR __builtin_amdgcn_s_barrier()
; #define PG8_SCHED __builtin_amdgcn_sched_barrier(0)
; template <class Epi, class Sched, bool ALIGN_EPI = false, bool SP2 = false, bool AGM = false  >
; __device__ __forceinline__ void gemm_phase(PG8_LAS unsigned char* lds, const Gemm g, const Sched& S, const Epi& E) {
;     ...
;             PG8_LDA(At, 1, 1); PG8_STAGE(PG8_SB(1, 0), b3, voffB); PG8_STAGE(PG8_SB(1, 1), b3 + hstep, voffB); PG8_STAGE(PG8_SA(1, 0), a3, voffA);
;             PG8_WAIT_V(8); PG8_WAIT_L(0); PG8_BAR; PG8_MMA(1, 0, At, B0); PG8_MMA(1, 1, At, B1); PG8_BAR; PG8_SCHED;
;     ...
;         if constexpr (ALIGN_EPI) { if (wr == 0) PG8_BAR; }
	s_add_i32 s36, s66, s38
	v_lshl_add_u64 v[164:165], v[164:165], 0, s[24:25]
	s_mov_b32 m0, s36
	ds_read_b128 v[196:199], v169 offset:49152
	ds_read_b128 v[200:203], v169 offset:50176
	ds_read_b128 v[204:207], v169 offset:51200
	ds_read_b128 v[208:211], v169 offset:52224
	ds_read_b128 v[212:215], v169 offset:53248
	ds_read_b128 v[216:219], v169 offset:54272
	ds_read_b128 v[220:223], v169 offset:55296
	ds_read_b128 v[224:227], v169 offset:56320
	global_load_lds_dwordx4 v[164:165], off
	s_add_i32 m0, s36, 0x2000
	s_add_u32 s34, s34, 0xb0080
	v_lshl_add_u64 v[164:165], v[228:229], 0, s[24:25]
	s_addc_u32 s35, s35, 0
	s_add_i32 s36, s67, s38
	global_load_lds_dwordx4 v[164:165], off
	v_lshl_add_u64 v[164:165], s[34:35], 0, v[132:133]
	s_mov_b32 m0, s36
	s_nop 0
	global_load_lds_dwordx4 v[164:165], off
	v_lshl_add_u64 v[164:165], s[34:35], 0, v[136:137]
	s_add_i32 m0, s36, 0x2000
	s_nop 0
	global_load_lds_dwordx4 v[164:165], off
	v_lshl_add_u64 v[164:165], v[230:231], 0, s[24:25]
	s_mov_b32 m0, s55
	s_nop 0
	global_load_lds_dwordx4 v[164:165], off
	v_lshl_add_u64 v[164:165], v[232:233], 0, s[24:25]
	s_mov_b32 m0, s58
	s_nop 0
	global_load_lds_dwordx4 v[164:165], off
	s_waitcnt vmcnt(8)
	s_waitcnt lgkmcnt(0)
	s_barrier
	s_setprio 1
	s_waitcnt lgkmcnt(0)
	v_mfma_f32_16x16x32_bf16 v[62:65], v[150:153], v[196:199], v[62:65]
	v_mfma_f32_16x16x32_bf16 v[58:61], v[160:163], v[196:199], v[58:61]
	v_mfma_f32_16x16x32_bf16 v[46:49], v[150:153], v[204:207], v[46:49]
	v_mfma_f32_16x16x32_bf16 v[42:45], v[160:163], v[204:207], v[42:45]
	v_mfma_f32_16x16x32_bf16 v[30:33], v[150:153], v[212:215], v[30:33]
	v_mfma_f32_16x16x32_bf16 v[26:29], v[160:163], v[212:215], v[26:29]
	v_mfma_f32_16x16x32_bf16 v[14:17], v[150:153], v[220:223], v[14:17]
	v_mfma_f32_16x16x32_bf16 v[10:13], v[160:163], v[220:223], v[10:13]
	v_mfma_f32_16x16x32_bf16 v[62:65], v[156:159], v[200:203], v[62:65]
	v_mfma_f32_16x16x32_bf16 v[58:61], v[176:179], v[200:203], v[58:61]
	v_mfma_f32_16x16x32_bf16 v[46:49], v[156:159], v[208:211], v[46:49]
	v_mfma_f32_16x16x32_bf16 v[42:45], v[176:179], v[208:211], v[42:45]
	v_mfma_f32_16x16x32_bf16 v[30:33], v[156:159], v[216:219], v[30:33]
	v_mfma_f32_16x16x32_bf16 v[26:29], v[176:179], v[216:219], v[26:29]
	v_mfma_f32_16x16x32_bf16 v[14:17], v[156:159], v[224:227], v[14:17]
	v_mfma_f32_16x16x32_bf16 v[10:13], v[176:179], v[224:227], v[10:13]
	v_mfma_f32_16x16x32_bf16 v[54:57], v[180:183], v[196:199], v[54:57]
	v_mfma_f32_16x16x32_bf16 v[50:53], v[188:191], v[196:199], v[50:53]
	v_mfma_f32_16x16x32_bf16 v[38:41], v[180:183], v[204:207], v[38:41]
	v_mfma_f32_16x16x32_bf16 v[34:37], v[188:191], v[204:207], v[34:37]
	v_mfma_f32_16x16x32_bf16 v[22:25], v[180:183], v[212:215], v[22:25]
	v_mfma_f32_16x16x32_bf16 v[18:21], v[188:191], v[212:215], v[18:21]
	v_mfma_f32_16x16x32_bf16 v[6:9], v[180:183], v[220:223], v[6:9]
	v_mfma_f32_16x16x32_bf16 v[2:5], v[188:191], v[220:223], v[2:5]
	v_mfma_f32_16x16x32_bf16 v[54:57], v[184:187], v[200:203], v[54:57]
	v_mfma_f32_16x16x32_bf16 v[50:53], v[192:195], v[200:203], v[50:53]
	v_mfma_f32_16x16x32_bf16 v[38:41], v[184:187], v[208:211], v[38:41]
	v_mfma_f32_16x16x32_bf16 v[34:37], v[192:195], v[208:211], v[34:37]
	v_mfma_f32_16x16x32_bf16 v[22:25], v[184:187], v[216:219], v[22:25]
	v_mfma_f32_16x16x32_bf16 v[18:21], v[192:195], v[216:219], v[18:21]
	v_mfma_f32_16x16x32_bf16 v[6:9], v[184:187], v[224:227], v[6:9]
	v_mfma_f32_16x16x32_bf16 v[2:5], v[192:195], v[224:227], v[2:5]
	s_setprio 0
	s_barrier
	s_add_i32 s65, s65, 2
	s_add_u32 s30, s30, 0x100
	s_addc_u32 s31, s31, 0
	s_add_u32 s5, s5, 0x100
	s_addc_u32 s33, s33, 0
	s_cmp_gt_u32 s65, 41
	s_cbranch_scc0 .LBB0_1068
	s_and_b64 vcc, exec, s[26:27]
	s_cbranch_vccz .LBB0_1071
	s_barrier
